# prep phase: hgrn chunk-state items forget-gate column loads software-pipelined (28 in flight)
# speedup vs baseline: 1.0251x; 1.0030x over previous
; #define LAS __attribute__((address_space(3)))
; __device__ __forceinline__ float bf2f(unsigned v) { return __uint_as_float(v << 16); }
; __device__ __forceinline__ int hg_row(int dir, int c, int s) {
;     const int p = 64 * c + s;
;     if (dir == 0) return p < CTX ? SEQ + p : p - CTX;
;     return p < CTX ? SEQ + (CTX - 1) - p : (SEQ - 1) - (p - CTX);
; }
; __device__ __forceinline__ void hgrn_h1_item(const Ctx& F, const bf16_t* PB, const float* logits, int l, int item, float* GS, float* HA, LAS unsigned char* scrb) {
;     const int head = item & 3, c = (item >> 2) % NCHUNK, dir = item / (4 * NCHUNK), lane = F.lane, q_ = lane & 31, h = lane >> 5;
;     constexpr int TP = 144;
;     LAS unsigned char* TKh = scrb;
;     const int colf = (dir ? C_BFB : C_BFF) + head * 64 + lane;
;     const float lb = lb_val(logits, l, dir, head * 64 + lane);
;     float r = 0.f;
; #pragma unroll
;     ...
;         float kh[8];
; #pragma unroll
;         for (int i = 7; i >= 0; --i) {
;             const float pre = bf2f(PB[(size_t)hg_row(dir, c, 8 * cb + i) * INW + colf]);
.LBB0_437:
	s_ashr_i32 s2, s42, 2
	s_mul_hi_i32 s4, s2, 0x7e07e07f
	s_lshr_b32 s5, s4, 31
	s_ashr_i32 s4, s4, 7
	s_add_i32 s4, s4, s5
	s_mulk_i32 s4, 0x104
	s_sub_i32 s28, s2, s4
	s_lshl_b32 s38, s28, 6
	s_add_i32 s4, s42, 0x40f
	s_or_b32 s2, s38, 1
	s_cmpk_lt_i32 s2, 0x100
	s_cselect_b32 s5, 0x4000, s30
	s_add_i32 s5, s5, s2
	s_cmp_lt_i32 s28, 4
	s_cselect_b32 s20, 0x4000, s30
	s_add_i32 s20, s20, s38
	s_sub_i32 s24, 0x40ff, s38
	s_cmpk_lt_u32 s4, 0x81f
	s_cselect_b64 s[22:23], -1, 0
	s_and_b64 s[22:23], s[22:23], exec
	s_cselect_b32 s29, s20, s24
	s_sub_i32 s2, 0x40ff, s2
	s_cmpk_lt_u32 s4, 0x81f
	s_cselect_b64 s[22:23], -1, 0
	s_and_b64 s[22:23], s[22:23], exec
	s_cselect_b32 s26, s5, s2
	s_or_b32 s2, s38, 2
	s_cmpk_lt_i32 s2, 0x100
	s_cselect_b32 s5, 0x4000, s30
	s_add_i32 s5, s5, s2
	s_sub_i32 s2, 0x40ff, s2
	s_cmpk_lt_u32 s4, 0x81f
	s_cselect_b64 s[22:23], -1, 0
	s_and_b64 s[22:23], s[22:23], exec
	s_cselect_b32 s27, s5, s2
	s_or_b32 s2, s38, 3
	s_cmpk_lt_i32 s2, 0x100
	s_cselect_b32 s5, 0x4000, s30
	s_add_i32 s5, s5, s2
	s_sub_i32 s2, 0x40ff, s2
	s_cmpk_lt_u32 s4, 0x81f
	s_cselect_b64 s[22:23], -1, 0
	s_and_b64 s[22:23], s[22:23], exec
	s_cselect_b32 s33, s5, s2
	s_or_b32 s2, s38, 4
	s_cmpk_lt_i32 s2, 0x100
	s_cselect_b32 s5, 0x4000, s30
	s_add_i32 s5, s5, s2
	s_sub_i32 s2, 0x40ff, s2
	s_cmpk_lt_u32 s4, 0x81f
	s_cselect_b64 s[22:23], -1, 0
	s_and_b64 s[22:23], s[22:23], exec
	s_cselect_b32 s36, s5, s2
	s_or_b32 s2, s38, 5
	s_cmpk_lt_i32 s2, 0x100
	s_cselect_b32 s5, 0x4000, s30
	s_add_i32 s5, s5, s2
	s_sub_i32 s2, 0x40ff, s2
	s_cmpk_lt_u32 s4, 0x81f
	s_cselect_b64 s[22:23], -1, 0
	s_and_b64 s[22:23], s[22:23], exec
	s_cselect_b32 s37, s5, s2
	s_or_b32 s2, s38, 6
	s_cmpk_lt_i32 s2, 0x100
	s_cselect_b32 s5, 0x4000, s30
	s_add_i32 s5, s5, s2
	s_sub_i32 s2, 0x40ff, s2
	s_cmpk_lt_u32 s4, 0x81f
	s_cselect_b64 s[22:23], -1, 0
	s_and_b64 s[22:23], s[22:23], exec
	s_cselect_b32 s44, s5, s2
	s_or_b32 s2, s38, 7
	s_cmpk_lt_i32 s2, 0x100
	s_cselect_b32 s5, 0x4000, s30
	s_add_i32 s5, s5, s2
	s_sub_i32 s2, 0x40ff, s2
	s_cmpk_lt_u32 s4, 0x81f
	s_cselect_b64 s[22:23], -1, 0
	s_and_b64 s[22:23], s[22:23], exec
	s_cselect_b32 s45, s5, s2
	s_or_b32 s2, s38, 8
	s_cmpk_lt_i32 s2, 0x100
	s_cselect_b32 s5, 0x4000, s30
	s_add_i32 s5, s5, s2
	s_sub_i32 s2, 0x40ff, s2
	s_cmpk_lt_u32 s4, 0x81f
	s_cselect_b64 s[22:23], -1, 0
	s_and_b64 s[22:23], s[22:23], exec
	s_cselect_b32 s48, s5, s2
	s_or_b32 s2, s38, 9
	s_cmpk_lt_i32 s2, 0x100
	s_cselect_b32 s5, 0x4000, s30
	s_add_i32 s5, s5, s2
	s_sub_i32 s2, 0x40ff, s2
	s_cmpk_lt_u32 s4, 0x81f
	s_cselect_b64 s[22:23], -1, 0
	s_and_b64 s[22:23], s[22:23], exec
	s_cselect_b32 s49, s5, s2
	s_or_b32 s2, s38, 10
	s_cmpk_lt_i32 s2, 0x100
	s_cselect_b32 s5, 0x4000, s30
	s_add_i32 s5, s5, s2
	s_sub_i32 s2, 0x40ff, s2
	s_cmpk_lt_u32 s4, 0x81f
	s_cselect_b64 s[22:23], -1, 0
	s_and_b64 s[22:23], s[22:23], exec
	s_cselect_b32 s50, s5, s2
	s_or_b32 s2, s38, 11
	s_cmpk_lt_i32 s2, 0x100
	s_cselect_b32 s5, 0x4000, s30
	s_add_i32 s5, s5, s2
	s_sub_i32 s2, 0x40ff, s2
	s_cmpk_lt_u32 s4, 0x81f
	s_cselect_b64 s[22:23], -1, 0
	s_and_b64 s[22:23], s[22:23], exec
	s_cselect_b32 s51, s5, s2
	s_or_b32 s2, s38, 12
	s_cmpk_lt_i32 s2, 0x100
	s_cselect_b32 s5, 0x4000, s30
	s_add_i32 s5, s5, s2
	s_sub_i32 s2, 0x40ff, s2
	s_cmpk_lt_u32 s4, 0x81f
	s_cselect_b64 s[22:23], -1, 0
	s_and_b64 s[22:23], s[22:23], exec
	s_cselect_b32 s52, s5, s2
	s_or_b32 s2, s38, 13
	s_cmpk_lt_i32 s2, 0x100
	s_cselect_b32 s5, 0x4000, s30
	s_add_i32 s5, s5, s2
	s_sub_i32 s2, 0x40ff, s2
	s_cmpk_lt_u32 s4, 0x81f
	s_cselect_b64 s[22:23], -1, 0
	s_and_b64 s[22:23], s[22:23], exec
	s_cselect_b32 s53, s5, s2
	s_or_b32 s2, s38, 14
	s_cmpk_lt_i32 s2, 0x100
	s_cselect_b32 s5, 0x4000, s30
	s_add_i32 s5, s5, s2
	s_sub_i32 s2, 0x40ff, s2
	s_cmpk_lt_u32 s4, 0x81f
	s_cselect_b64 s[22:23], -1, 0
	s_and_b64 s[22:23], s[22:23], exec
	s_cselect_b32 s24, s5, s2
	s_or_b32 s2, s38, 15
	s_cmpk_lt_i32 s2, 0x100
	s_cselect_b32 s5, 0x4000, s30
	s_add_i32 s5, s5, s2
	s_sub_i32 s2, 0x40ff, s2
	s_cmpk_lt_u32 s4, 0x81f
	s_cselect_b64 s[22:23], -1, 0
	s_and_b64 s[22:23], s[22:23], exec
	s_cselect_b32 s25, s5, s2
	s_or_b32 s2, s38, 16
	s_cmpk_lt_i32 s2, 0x100
	s_cselect_b32 s5, 0x4000, s30
	s_add_i32 s5, s5, s2
	s_sub_i32 s2, 0x40ff, s2
	s_cmpk_lt_u32 s4, 0x81f
	s_cselect_b64 s[22:23], -1, 0
	s_and_b64 s[22:23], s[22:23], exec
	s_cselect_b32 s55, s5, s2
	s_or_b32 s2, s38, 17
	s_cmpk_lt_i32 s2, 0x100
	s_cselect_b32 s5, 0x4000, s30
	s_add_i32 s5, s5, s2
	s_sub_i32 s2, 0x40ff, s2
	s_cmpk_lt_u32 s4, 0x81f
	s_cselect_b64 s[22:23], -1, 0
	s_and_b64 s[22:23], s[22:23], exec
	s_cselect_b32 s56, s5, s2
	s_or_b32 s2, s38, 18
	s_cmpk_lt_i32 s2, 0x100
	s_cselect_b32 s5, 0x4000, s30
	s_add_i32 s5, s5, s2
	s_sub_i32 s2, 0x40ff, s2
	s_cmpk_lt_u32 s4, 0x81f
	s_cselect_b64 s[22:23], -1, 0
	s_and_b64 s[22:23], s[22:23], exec
	s_cselect_b32 s57, s5, s2
	s_or_b32 s2, s38, 19
	s_cmpk_lt_i32 s2, 0x100
	s_cselect_b32 s5, 0x4000, s30
	s_add_i32 s5, s5, s2
	s_sub_i32 s2, 0x40ff, s2
	s_cmpk_lt_u32 s4, 0x81f
	s_cselect_b64 s[22:23], -1, 0
	s_and_b64 s[22:23], s[22:23], exec
	s_cselect_b32 s2, s5, s2
	s_or_b32 s5, s38, 20
	s_cmpk_lt_i32 s5, 0x100
	s_cselect_b32 s20, 0x4000, s30
	s_add_i32 s20, s20, s5
	s_sub_i32 s5, 0x40ff, s5
	s_cmpk_lt_u32 s4, 0x81f
	s_cselect_b64 s[22:23], -1, 0
	s_and_b64 s[22:23], s[22:23], exec
	s_cselect_b32 s58, s20, s5
	s_or_b32 s5, s38, 21
	s_cmpk_lt_i32 s5, 0x100
	s_cselect_b32 s20, 0x4000, s30
	s_add_i32 s20, s20, s5
	s_sub_i32 s5, 0x40ff, s5
	s_cmpk_lt_u32 s4, 0x81f
	s_cselect_b64 s[22:23], -1, 0
	s_and_b64 s[22:23], s[22:23], exec
	s_cselect_b32 s59, s20, s5
	s_or_b32 s5, s38, 22
	s_cmpk_lt_i32 s5, 0x100
; #define LAS __attribute__((address_space(3)))
; __device__ __forceinline__ float bf2f(unsigned v) { return __uint_as_float(v << 16); }
; __device__ __forceinline__ int hg_row(int dir, int c, int s) {
;     const int p = 64 * c + s;
;     if (dir == 0) return p < CTX ? SEQ + p : p - CTX;
;     return p < CTX ? SEQ + (CTX - 1) - p : (SEQ - 1) - (p - CTX);
; }
; __device__ __forceinline__ void hgrn_h1_item(const Ctx& F, const bf16_t* PB, const float* logits, int l, int item, float* GS, float* HA, LAS unsigned char* scrb) {
;     const int head = item & 3, c = (item >> 2) % NCHUNK, dir = item / (4 * NCHUNK), lane = F.lane, q_ = lane & 31, h = lane >> 5;
;     constexpr int TP = 144;
;     LAS unsigned char* TKh = scrb;
;     const int colf = (dir ? C_BFB : C_BFF) + head * 64 + lane;
;     const float lb = lb_val(logits, l, dir, head * 64 + lane);
;     float r = 0.f;
; #pragma unroll
;     ...
;         float kh[8];
; #pragma unroll
;         for (int i = 7; i >= 0; --i) {
;             const float pre = bf2f(PB[(size_t)hg_row(dir, c, 8 * cb + i) * INW + colf]);
	s_cselect_b32 s20, 0x4000, s30
	s_add_i32 s20, s20, s5
	s_sub_i32 s5, 0x40ff, s5
	s_cmpk_lt_u32 s4, 0x81f
	s_cselect_b64 s[22:23], -1, 0
	s_and_b64 s[22:23], s[22:23], exec
	s_cselect_b32 s62, s20, s5
	s_or_b32 s5, s38, 23
	s_cmpk_lt_i32 s5, 0x100
	s_cselect_b32 s20, 0x4000, s30
	s_add_i32 s20, s20, s5
	s_sub_i32 s5, 0x40ff, s5
	s_cmpk_lt_u32 s4, 0x81f
	s_cselect_b64 s[22:23], -1, 0
	s_and_b64 s[22:23], s[22:23], exec
	s_cselect_b32 s20, s20, s5
	s_or_b32 s5, s38, 24
	s_cmpk_lt_i32 s5, 0x100
	s_cselect_b32 s22, 0x4000, s30
	s_add_i32 s46, s22, s5
	s_sub_i32 s5, 0x40ff, s5
	s_cmpk_lt_u32 s4, 0x81f
	s_cselect_b64 s[22:23], -1, 0
	s_and_b64 s[22:23], s[22:23], exec
	s_cselect_b32 s22, s46, s5
	s_or_b32 s5, s38, 25
	s_cmpk_lt_i32 s5, 0x100
	s_cselect_b32 s23, 0x4000, s30
	s_add_i32 s23, s23, s5
	s_sub_i32 s5, 0x40ff, s5
	s_cmpk_lt_u32 s4, 0x81f
	s_cselect_b64 s[46:47], -1, 0
	s_and_b64 s[46:47], s[46:47], exec
	s_cselect_b32 s23, s23, s5
	s_or_b32 s5, s38, 26
	s_cmpk_lt_i32 s5, 0x100
	s_cselect_b32 s46, 0x4000, s30
	s_add_i32 s54, s46, s5
	s_sub_i32 s5, 0x40ff, s5
	s_cmpk_lt_u32 s4, 0x81f
	s_cselect_b64 s[46:47], -1, 0
	s_and_b64 s[46:47], s[46:47], exec
	s_cselect_b32 s63, s54, s5
	s_or_b32 s5, s38, 27
	s_cmpk_lt_i32 s5, 0x100
	s_cselect_b32 s46, 0x4000, s30
	s_add_i32 s54, s46, s5
	s_sub_i32 s5, 0x40ff, s5
	s_cmpk_lt_u32 s4, 0x81f
	s_cselect_b64 s[46:47], -1, 0
	s_and_b64 s[46:47], s[46:47], exec
	s_cselect_b32 s64, s54, s5
	s_or_b32 s5, s38, 28
	s_cmpk_lt_i32 s5, 0x100
	s_cselect_b32 s46, 0x4000, s30
	s_add_i32 s54, s46, s5
	s_sub_i32 s5, 0x40ff, s5
	s_cmpk_lt_u32 s4, 0x81f
	s_cselect_b64 s[46:47], -1, 0
	s_and_b64 s[46:47], s[46:47], exec
	s_cselect_b32 s65, s54, s5
	s_or_b32 s5, s38, 29
	s_cmpk_lt_i32 s5, 0x100
	s_cselect_b32 s46, 0x4000, s30
	s_add_i32 s54, s46, s5
	s_sub_i32 s5, 0x40ff, s5
	s_cmpk_lt_u32 s4, 0x81f
	s_cselect_b64 s[46:47], -1, 0
	s_and_b64 s[46:47], s[46:47], exec
	s_cselect_b32 s66, s54, s5
	s_or_b32 s5, s38, 30
	s_cmpk_lt_i32 s5, 0x100
	s_cselect_b32 s46, 0x4000, s30
	s_add_i32 s54, s46, s5
	s_sub_i32 s5, 0x40ff, s5
	s_cmpk_lt_u32 s4, 0x81f
	s_cselect_b64 s[46:47], -1, 0
	s_and_b64 s[46:47], s[46:47], exec
	s_cselect_b32 s67, s54, s5
	s_or_b32 s5, s38, 31
	s_cmpk_lt_i32 s5, 0x100
	s_cselect_b32 s46, 0x4000, s30
	s_add_i32 s54, s46, s5
	s_sub_i32 s5, 0x40ff, s5
	s_cmpk_lt_u32 s4, 0x81f
	s_cselect_b64 s[46:47], -1, 0
	s_and_b64 s[46:47], s[46:47], exec
	s_cselect_b32 s68, s54, s5
	s_or_b32 s5, s38, 32
	s_cmpk_lt_i32 s5, 0x100
	s_cselect_b32 s46, 0x4000, s30
	s_add_i32 s54, s46, s5
	s_sub_i32 s5, 0x40ff, s5
	s_cmpk_lt_u32 s4, 0x81f
	s_cselect_b64 s[46:47], -1, 0
	s_and_b64 s[46:47], s[46:47], exec
	s_cselect_b32 s69, s54, s5
	s_or_b32 s5, s38, 33
	s_cmpk_lt_i32 s5, 0x100
	s_cselect_b32 s46, 0x4000, s30
	s_add_i32 s54, s46, s5
	s_sub_i32 s5, 0x40ff, s5
	s_cmpk_lt_u32 s4, 0x81f
	s_cselect_b64 s[46:47], -1, 0
	s_and_b64 s[46:47], s[46:47], exec
	s_cselect_b32 s70, s54, s5
	s_or_b32 s5, s38, 34
	s_cmpk_lt_i32 s5, 0x100
	s_cselect_b32 s46, 0x4000, s30
	s_add_i32 s54, s46, s5
	s_sub_i32 s5, 0x40ff, s5
	s_cmpk_lt_u32 s4, 0x81f
	s_cselect_b64 s[46:47], -1, 0
	s_and_b64 s[46:47], s[46:47], exec
	s_cselect_b32 s71, s54, s5
	s_or_b32 s5, s38, 35
	s_cmpk_lt_i32 s5, 0x100
	s_cselect_b32 s46, 0x4000, s30
	s_add_i32 s54, s46, s5
	s_sub_i32 s5, 0x40ff, s5
	s_cmpk_lt_u32 s4, 0x81f
	s_cselect_b64 s[46:47], -1, 0
	s_and_b64 s[46:47], s[46:47], exec
	s_cselect_b32 s72, s54, s5
	s_or_b32 s5, s38, 36
	s_cmpk_lt_i32 s5, 0x100
	s_cselect_b32 s46, 0x4000, s30
	s_add_i32 s54, s46, s5
	s_sub_i32 s5, 0x40ff, s5
	s_cmpk_lt_u32 s4, 0x81f
	s_cselect_b64 s[46:47], -1, 0
	s_and_b64 s[46:47], s[46:47], exec
	s_cselect_b32 s73, s54, s5
	s_or_b32 s5, s38, 37
	s_cmpk_lt_i32 s5, 0x100
	s_cselect_b32 s46, 0x4000, s30
	s_add_i32 s54, s46, s5
	s_sub_i32 s5, 0x40ff, s5
	s_cmpk_lt_u32 s4, 0x81f
	s_cselect_b64 s[46:47], -1, 0
	s_and_b64 s[46:47], s[46:47], exec
	s_cselect_b32 s74, s54, s5
	s_or_b32 s5, s38, 38
	s_cmpk_lt_i32 s5, 0x100
	s_cselect_b32 s46, 0x4000, s30
	s_add_i32 s54, s46, s5
	s_sub_i32 s5, 0x40ff, s5
	s_cmpk_lt_u32 s4, 0x81f
	s_cselect_b64 s[46:47], -1, 0
	s_and_b64 s[46:47], s[46:47], exec
	s_cselect_b32 s75, s54, s5
	s_or_b32 s5, s38, 39
	s_cmpk_lt_i32 s5, 0x100
	s_cselect_b32 s46, 0x4000, s30
	s_add_i32 s54, s46, s5
	s_sub_i32 s5, 0x40ff, s5
	s_cmpk_lt_u32 s4, 0x81f
	s_cselect_b64 s[46:47], -1, 0
	s_and_b64 s[46:47], s[46:47], exec
	s_cselect_b32 s76, s54, s5
	s_or_b32 s5, s38, 40
	s_cmpk_lt_i32 s5, 0x100
	s_cselect_b32 s46, 0x4000, s30
	s_add_i32 s54, s46, s5
	s_sub_i32 s5, 0x40ff, s5
	s_cmpk_lt_u32 s4, 0x81f
	s_cselect_b64 s[46:47], -1, 0
	s_and_b64 s[46:47], s[46:47], exec
	s_cselect_b32 s77, s54, s5
	s_or_b32 s5, s38, 41
	s_cmpk_lt_i32 s5, 0x100
	s_cselect_b32 s46, 0x4000, s30
	s_add_i32 s54, s46, s5
	s_sub_i32 s5, 0x40ff, s5
	s_cmpk_lt_u32 s4, 0x81f
	s_cselect_b64 s[46:47], -1, 0
	s_and_b64 s[46:47], s[46:47], exec
	s_cselect_b32 s78, s54, s5
	s_or_b32 s5, s38, 42
	s_cmpk_lt_i32 s5, 0x100
	s_cselect_b32 s46, 0x4000, s30
	s_add_i32 s54, s46, s5
	s_sub_i32 s5, 0x40ff, s5
	s_cmpk_lt_u32 s4, 0x81f
	s_cselect_b64 s[46:47], -1, 0
	s_and_b64 s[46:47], s[46:47], exec
	s_cselect_b32 s79, s54, s5
	s_or_b32 s5, s38, 43
	s_cmpk_lt_i32 s5, 0x100
	s_cselect_b32 s46, 0x4000, s30
	s_add_i32 s54, s46, s5
	s_sub_i32 s5, 0x40ff, s5
	s_cmpk_lt_u32 s4, 0x81f
	s_cselect_b64 s[46:47], -1, 0
	s_and_b64 s[46:47], s[46:47], exec
	s_cselect_b32 s80, s54, s5
	s_or_b32 s5, s38, 44
	s_cmpk_lt_i32 s5, 0x100
	s_cselect_b32 s46, 0x4000, s30
	s_add_i32 s54, s46, s5
	s_sub_i32 s5, 0x40ff, s5
	s_cmpk_lt_u32 s4, 0x81f
	s_cselect_b64 s[46:47], -1, 0
	s_and_b64 s[46:47], s[46:47], exec
; __device__ __forceinline__ float lb_val(const float* logits, int l, int dir, int ch) {
;     float v[4]; float mx = -3.0e38f;
; #pragma unroll
;     for (int j = 0; j < 4; ++j) { v[j] = logits[(j * 2 + dir) * 256 + ch]; mx = fmaxf(mx, v[j]); }
; __device__ __forceinline__ int hg_row(int dir, int c, int s) {
;     const int p = 64 * c + s;
;     if (dir == 0) return p < CTX ? SEQ + p : p - CTX;
;     return p < CTX ? SEQ + (CTX - 1) - p : (SEQ - 1) - (p - CTX);
; }
	s_cselect_b32 s81, s54, s5
	s_or_b32 s5, s38, 45
	s_cmpk_lt_i32 s5, 0x100
	s_cselect_b32 s46, 0x4000, s30
	s_add_i32 s54, s46, s5
	s_sub_i32 s5, 0x40ff, s5
	s_cmpk_lt_u32 s4, 0x81f
	s_cselect_b64 s[46:47], -1, 0
	s_and_b64 s[46:47], s[46:47], exec
	s_cselect_b32 s82, s54, s5
	s_or_b32 s5, s38, 46
	s_cmpk_lt_i32 s5, 0x100
	s_cselect_b32 s46, 0x4000, s30
	s_add_i32 s54, s46, s5
	s_sub_i32 s5, 0x40ff, s5
	s_cmpk_lt_u32 s4, 0x81f
	s_cselect_b64 s[46:47], -1, 0
	s_and_b64 s[46:47], s[46:47], exec
	s_cselect_b32 s83, s54, s5
	s_or_b32 s5, s38, 47
	s_cmpk_lt_i32 s5, 0x100
	s_cselect_b32 s46, 0x4000, s30
	s_add_i32 s54, s46, s5
	s_sub_i32 s5, 0x40ff, s5
	s_cmpk_lt_u32 s4, 0x81f
	s_cselect_b64 s[46:47], -1, 0
	s_and_b64 s[46:47], s[46:47], exec
	s_cselect_b32 s84, s54, s5
	s_or_b32 s5, s38, 48
	s_cmpk_lt_i32 s5, 0x100
	s_cselect_b32 s46, 0x4000, s30
	s_add_i32 s54, s46, s5
	s_sub_i32 s5, 0x40ff, s5
	s_cmpk_lt_u32 s4, 0x81f
	s_cselect_b64 s[46:47], -1, 0
	s_and_b64 s[46:47], s[46:47], exec
	s_cselect_b32 s85, s54, s5
	s_or_b32 s5, s38, 49
	s_cmpk_lt_i32 s5, 0x100
	s_cselect_b32 s46, 0x4000, s30
	s_add_i32 s54, s46, s5
	s_sub_i32 s5, 0x40ff, s5
	s_cmpk_lt_u32 s4, 0x81f
	s_cselect_b64 s[46:47], -1, 0
	s_and_b64 s[46:47], s[46:47], exec
	s_cselect_b32 s86, s54, s5
	s_or_b32 s5, s38, 50
	s_cmpk_lt_i32 s5, 0x100
	s_cselect_b32 s46, 0x4000, s30
	s_add_i32 s54, s46, s5
	s_sub_i32 s5, 0x40ff, s5
	s_cmpk_lt_u32 s4, 0x81f
	s_cselect_b64 s[46:47], -1, 0
	s_and_b64 s[46:47], s[46:47], exec
	s_cselect_b32 s87, s54, s5
	s_or_b32 s5, s38, 51
	s_cmpk_lt_i32 s5, 0x100
	s_cselect_b32 s46, 0x4000, s30
	s_add_i32 s54, s46, s5
	s_sub_i32 s5, 0x40ff, s5
	s_cmpk_lt_u32 s4, 0x81f
	s_cselect_b64 s[46:47], -1, 0
	s_and_b64 s[46:47], s[46:47], exec
	s_cselect_b32 s88, s54, s5
	s_or_b32 s5, s38, 52
	s_cmpk_lt_i32 s5, 0x100
	s_cselect_b32 s46, 0x4000, s30
	s_add_i32 s54, s46, s5
	s_sub_i32 s5, 0x40ff, s5
	s_cmpk_lt_u32 s4, 0x81f
	s_cselect_b64 s[46:47], -1, 0
	s_and_b64 s[46:47], s[46:47], exec
	s_cselect_b32 s89, s54, s5
	s_or_b32 s5, s38, 53
	s_cmpk_lt_i32 s5, 0x100
	s_cselect_b32 s46, 0x4000, s30
	s_add_i32 s54, s46, s5
	s_sub_i32 s5, 0x40ff, s5
	s_cmpk_lt_u32 s4, 0x81f
	s_cselect_b64 s[46:47], -1, 0
	s_and_b64 s[46:47], s[46:47], exec
	s_cselect_b32 s90, s54, s5
	s_or_b32 s5, s38, 54
	s_cmpk_lt_i32 s5, 0x100
	s_cselect_b32 s46, 0x4000, s30
	s_add_i32 s54, s46, s5
	s_sub_i32 s5, 0x40ff, s5
	s_cmpk_lt_u32 s4, 0x81f
	s_cselect_b64 s[46:47], -1, 0
	s_and_b64 s[46:47], s[46:47], exec
	s_cselect_b32 s91, s54, s5
	s_or_b32 s5, s38, 55
	s_cmpk_lt_i32 s5, 0x100
	s_cselect_b32 s46, 0x4000, s30
	s_add_i32 s54, s46, s5
	s_sub_i32 s5, 0x40ff, s5
	s_cmpk_lt_u32 s4, 0x81f
	s_cselect_b64 s[46:47], -1, 0
	s_and_b64 s[46:47], s[46:47], exec
	s_cselect_b32 s92, s54, s5
	s_or_b32 s5, s38, 56
	s_cmpk_lt_i32 s5, 0x100
	s_cselect_b32 s46, 0x4000, s30
	s_add_i32 s54, s46, s5
	s_sub_i32 s5, 0x40ff, s5
	s_cmpk_lt_u32 s4, 0x81f
	s_cselect_b64 s[46:47], -1, 0
	s_and_b64 s[46:47], s[46:47], exec
	s_cselect_b32 s93, s54, s5
	s_or_b32 s5, s38, 57
	s_cmpk_lt_i32 s5, 0x100
	s_cselect_b32 s46, 0x4000, s30
	s_add_i32 s54, s46, s5
	s_sub_i32 s5, 0x40ff, s5
	s_cmpk_lt_u32 s4, 0x81f
	s_cselect_b64 s[46:47], -1, 0
	s_and_b64 s[46:47], s[46:47], exec
	s_cselect_b32 s94, s54, s5
	s_or_b32 s5, s38, 58
	s_cmpk_lt_i32 s5, 0x100
	s_cselect_b32 s46, 0x4000, s30
	s_add_i32 s54, s46, s5
	s_sub_i32 s5, 0x40ff, s5
	s_cmpk_lt_u32 s4, 0x81f
	s_cselect_b64 s[46:47], -1, 0
	s_and_b64 s[46:47], s[46:47], exec
	s_cselect_b32 s95, s54, s5
	s_or_b32 s5, s38, 59
	s_cmpk_lt_i32 s5, 0x100
	s_cselect_b32 s46, 0x4000, s30
	s_add_i32 s54, s46, s5
	s_sub_i32 s5, 0x40ff, s5
	s_cmpk_lt_u32 s4, 0x81f
	s_cselect_b64 s[46:47], -1, 0
	s_and_b64 s[46:47], s[46:47], exec
	s_cselect_b32 s96, s54, s5
	s_or_b32 s5, s38, 60
	s_cmpk_lt_i32 s5, 0x100
	s_cselect_b32 s46, 0x4000, s30
	s_add_i32 s54, s46, s5
	s_sub_i32 s5, 0x40ff, s5
	s_cmpk_lt_u32 s4, 0x81f
	s_cselect_b64 s[46:47], -1, 0
	s_and_b64 s[46:47], s[46:47], exec
	s_cselect_b32 s97, s54, s5
	s_or_b32 s5, s38, 61
	s_cmpk_lt_i32 s5, 0x100
	s_cselect_b32 s46, 0x4000, s30
	s_add_i32 s54, s46, s5
	s_sub_i32 s5, 0x40ff, s5
	s_cmpk_lt_u32 s4, 0x81f
	s_cselect_b64 s[46:47], -1, 0
	s_and_b64 s[46:47], s[46:47], exec
	s_cselect_b32 s6, s54, s5
	s_or_b32 s5, s38, 62
	s_cmpk_lt_i32 s5, 0x100
	s_cselect_b32 s7, 0x4000, s30
	s_add_i32 s7, s7, s5
	s_sub_i32 s5, 0x40ff, s5
	s_cmpk_lt_u32 s4, 0x81f
	s_cselect_b64 s[46:47], -1, 0
	s_and_b64 s[46:47], s[46:47], exec
	s_cselect_b32 s7, s7, s5
	s_or_b32 s5, s38, 63
	s_cmpk_lt_i32 s5, 0x100
	s_cselect_b32 s46, 0x4000, s30
	s_add_i32 s54, s46, s5
	s_sub_i32 vcc_lo, 0x40ff, s5
	s_cmpk_lt_u32 s4, 0x81f
	s_cselect_b64 s[46:47], -1, 0
	s_mul_hi_i32 vcc_hi, s42, 0x7e07e07f
	s_and_b64 s[4:5], s[46:47], exec
	s_cselect_b32 s4, s43, 0x400
	s_cselect_b32 s43, s54, vcc_lo
	s_lshr_b32 s5, vcc_hi, 31
	s_ashr_i32 s54, vcc_hi, 9
	s_add_i32 s54, s54, s5
	v_or_b32_e32 v0, s4, v98
	v_lshl_or_b32 v2, s54, 8, v98
	v_readlane_b32 s4, v253, 29
	v_ashrrev_i32_e32 v3, 31, v2
	v_readlane_b32 s5, v253, 30
	s_mov_b32 s0, 0x3fb8aa3b
	v_lshlrev_b32_e32 v0, 1, v0
	v_lshl_add_u64 v[2:3], v[2:3], 2, s[4:5]
	global_load_dword v4, v[2:3], off
	global_load_dword v5, v[2:3], off offset:2048
	s_mov_b32 s4, 0xff61b1e6
	v_or_b32_e32 v92, s38, v94
	v_or_b32_e32 v93, 21, v92
	v_or_b32_e32 v167, 22, v92
	v_or_b32_e32 v170, 23, v92
	s_waitcnt vmcnt(0)
	v_max3_f32 v6, v4, s4, v5
	s_movk_i32 s4, 0x1000
	v_add_co_u32_e32 v2, vcc, s4, v2
	s_mov_b32 s4, 0xc2ce8ed0
	s_nop 0
	v_addc_co_u32_e32 v3, vcc, 0, v3, vcc
	global_load_dword v7, v[2:3], off
	s_nop 0
	global_load_dword v2, v[2:3], off offset:2048
	s_waitcnt vmcnt(0)
; __device__ __forceinline__ float bf2f(unsigned v) { return __uint_as_float(v << 16); }
; __device__ __forceinline__ float sigmoidf_(float x) { return __builtin_amdgcn_rcpf(1.0f + __builtin_amdgcn_exp2f(-1.4426950408889634f * x)); }
; __device__ __forceinline__ float lb_val(const float* logits, int l, int dir, int ch) {
;     float v[4]; float mx = -3.0e38f;
; #pragma unroll
;     for (int j = 0; j < 4; ++j) { v[j] = logits[(j * 2 + dir) * 256 + ch]; mx = fmaxf(mx, v[j]); }
;     float s = 0.f, c = 0.f;
; #pragma unroll
;     for (int j = 0; j < 4; ++j) { v[j] = expf(v[j] - mx); s += v[j]; if (j >= 1 && j <= l) c += v[j]; }
;     return c / s;
; }
; __device__ __forceinline__ void hgrn_h1_item(const Ctx& F, const bf16_t* PB, const float* logits, int l, int item, float* GS, float* HA, LAS unsigned char* scrb) {
;     ...
;         float kh[8];
; #pragma unroll
;         for (int i = 7; i >= 0; --i) {
;             const float pre = bf2f(PB[(size_t)hg_row(dir, c, 8 * cb + i) * INW + colf]);
;             const float f = lb + (1.0f - lb) * sigmoidf_(pre);
	v_max3_f32 v3, v6, v7, v2
	v_sub_f32_e32 v4, v4, v3
	v_mul_f32_e32 v6, 0x3fb8aa3b, v4
	v_fma_f32 v8, v4, s0, -v6
	v_rndne_f32_e32 v9, v6
	v_fmac_f32_e32 v8, 0x32a5705f, v4
	v_sub_f32_e32 v6, v6, v9
	v_add_f32_e32 v6, v6, v8
	v_exp_f32_e32 v6, v6
	v_cvt_i32_f32_e32 v8, v9
	v_cmp_ngt_f32_e32 vcc, s4, v4
	v_sub_f32_e32 v5, v5, v3
	v_sub_f32_e32 v2, v2, v3
	v_ldexp_f32 v6, v6, v8
	v_cndmask_b32_e32 v6, 0, v6, vcc
	v_cmp_nlt_f32_e32 vcc, s9, v4
	s_nop 1
	v_cndmask_b32_e32 v4, v204, v6, vcc
	v_mul_f32_e32 v6, 0x3fb8aa3b, v5
	v_fma_f32 v8, v5, s0, -v6
	v_rndne_f32_e32 v9, v6
	v_fmac_f32_e32 v8, 0x32a5705f, v5
	v_sub_f32_e32 v6, v6, v9
	v_add_f32_e32 v6, v6, v8
	v_exp_f32_e32 v6, v6
	v_cvt_i32_f32_e32 v8, v9
	v_cmp_ngt_f32_e32 vcc, s4, v5
	v_ldexp_f32 v6, v6, v8
	s_nop 0
	v_cndmask_b32_e32 v6, 0, v6, vcc
	v_cmp_nlt_f32_e32 vcc, s9, v5
	s_nop 1
	v_cndmask_b32_e32 v5, v204, v6, vcc
	v_sub_f32_e32 v6, v7, v3
	v_mul_f32_e32 v7, 0x3fb8aa3b, v6
	v_fma_f32 v8, v6, s0, -v7
	v_rndne_f32_e32 v9, v7
	v_fmac_f32_e32 v8, 0x32a5705f, v6
	v_sub_f32_e32 v7, v7, v9
	v_add_f32_e32 v7, v7, v8
	v_exp_f32_e32 v7, v7
	v_cvt_i32_f32_e32 v8, v9
	v_readlane_b32 vcc_lo, v253, 19
	v_readlane_b32 vcc_hi, v253, 20
	v_add_f32_e32 v4, v4, v5
	v_ldexp_f32 v7, v7, v8
	v_cndmask_b32_e32 v5, 0, v5, vcc
	v_cmp_ngt_f32_e32 vcc, s4, v6
	v_mul_f32_e32 v3, 0x3fb8aa3b, v2
	s_nop 0
	v_cndmask_b32_e32 v7, 0, v7, vcc
	v_cmp_nlt_f32_e32 vcc, s9, v6
	s_nop 1
	v_cndmask_b32_e32 v6, v204, v7, vcc
	v_readlane_b32 vcc_lo, v253, 24
	v_add_f32_e32 v4, v6, v4
	v_add_f32_e32 v6, v6, v5
	v_readlane_b32 vcc_hi, v253, 25
	v_rndne_f32_e32 v7, v3
	s_nop 0
	v_cndmask_b32_e32 v5, v6, v5, vcc
	v_fma_f32 v6, v2, s0, -v3
	v_fmac_f32_e32 v6, 0x32a5705f, v2
	v_sub_f32_e32 v3, v3, v7
	v_add_f32_e32 v3, v3, v6
	v_exp_f32_e32 v3, v3
	v_cvt_i32_f32_e32 v6, v7
	v_cmp_ngt_f32_e32 vcc, s4, v2
	v_readlane_b32 s4, v253, 26
	v_readlane_b32 s5, v253, 27
	v_ldexp_f32 v3, v3, v6
	v_cndmask_b32_e32 v3, 0, v3, vcc
	v_cmp_nlt_f32_e32 vcc, s9, v2
	s_nop 1
	v_cndmask_b32_e32 v2, v204, v3, vcc
	v_add_f32_e32 v3, v2, v4
	v_add_f32_e32 v2, v2, v5
	v_cndmask_b32_e64 v2, v2, v5, s[4:5]
	v_div_scale_f32 v4, s[4:5], v3, v3, v2
	v_rcp_f32_e32 v5, v4
	v_readlane_b32 s4, v252, 61
	v_readlane_b32 s5, v252, 62
	v_fma_f32 v6, -v4, v5, 1.0
	v_fmac_f32_e32 v5, v6, v5
	v_div_scale_f32 v6, vcc, v2, v3, v2
	v_mul_f32_e32 v7, v6, v5
	v_fma_f32 v8, -v4, v7, v6
	v_fmac_f32_e32 v7, v8, v5
	v_fma_f32 v4, -v4, v7, v6
	v_div_fmas_f32 v4, v4, v5, v7
	v_div_fixup_f32 v2, v4, v3, v2
	v_lshl_add_u64 v[4:5], s[4:5], 0, v[0:1]
	s_mul_i32 s4, s43, 0x3600
	s_ashr_i32 s5, s4, 31
	v_lshl_add_u64 v[6:7], v[4:5], 0, s[4:5]
	s_mul_i32 s100, s43, 0x3600
	s_mov_b32 s101, 0
	v_lshl_add_u64 v[248:249], v[4:5], 0, s[100:101]
	global_load_ushort v218, v[248:249], off
	s_mul_i32 s100, s7, 0x3600
	s_mov_b32 s101, 0
	v_lshl_add_u64 v[248:249], v[4:5], 0, s[100:101]
	global_load_ushort v219, v[248:249], off
	s_mul_i32 s100, s6, 0x3600
	s_mov_b32 s101, 0
	v_lshl_add_u64 v[248:249], v[4:5], 0, s[100:101]
	global_load_ushort v220, v[248:249], off
	s_mul_i32 s100, s97, 0x3600
	s_mov_b32 s101, 0
	v_lshl_add_u64 v[248:249], v[4:5], 0, s[100:101]
	global_load_ushort v221, v[248:249], off
	s_mul_i32 s100, s96, 0x3600
	s_mov_b32 s101, 0
	v_lshl_add_u64 v[248:249], v[4:5], 0, s[100:101]
	global_load_ushort v222, v[248:249], off
	s_mul_i32 s100, s95, 0x3600
	s_mov_b32 s101, 0
	v_lshl_add_u64 v[248:249], v[4:5], 0, s[100:101]
	global_load_ushort v223, v[248:249], off
	s_mul_i32 s100, s94, 0x3600
	s_mov_b32 s101, 0
	v_lshl_add_u64 v[248:249], v[4:5], 0, s[100:101]
	global_load_ushort v224, v[248:249], off
	s_mul_i32 s100, s93, 0x3600
	s_mov_b32 s101, 0
	v_lshl_add_u64 v[248:249], v[4:5], 0, s[100:101]
	global_load_ushort v225, v[248:249], off
	s_mul_i32 s100, s92, 0x3600
	s_mov_b32 s101, 0
	v_lshl_add_u64 v[248:249], v[4:5], 0, s[100:101]
	global_load_ushort v226, v[248:249], off
	s_mul_i32 s100, s91, 0x3600
	s_mov_b32 s101, 0
	v_lshl_add_u64 v[248:249], v[4:5], 0, s[100:101]
	global_load_ushort v227, v[248:249], off
	s_mul_i32 s100, s90, 0x3600
	s_mov_b32 s101, 0
	v_lshl_add_u64 v[248:249], v[4:5], 0, s[100:101]
	global_load_ushort v228, v[248:249], off
	s_mul_i32 s100, s89, 0x3600
	s_mov_b32 s101, 0
	v_lshl_add_u64 v[248:249], v[4:5], 0, s[100:101]
	global_load_ushort v229, v[248:249], off
	s_mul_i32 s100, s88, 0x3600
	s_mov_b32 s101, 0
	v_lshl_add_u64 v[248:249], v[4:5], 0, s[100:101]
	global_load_ushort v230, v[248:249], off
	s_mul_i32 s100, s87, 0x3600
	s_mov_b32 s101, 0
	v_lshl_add_u64 v[248:249], v[4:5], 0, s[100:101]
	global_load_ushort v231, v[248:249], off
	s_mul_i32 s100, s86, 0x3600
	s_mov_b32 s101, 0
	v_lshl_add_u64 v[248:249], v[4:5], 0, s[100:101]
	global_load_ushort v232, v[248:249], off
	s_mul_i32 s100, s85, 0x3600
	s_mov_b32 s101, 0
	v_lshl_add_u64 v[248:249], v[4:5], 0, s[100:101]
	global_load_ushort v233, v[248:249], off
	s_mul_i32 s100, s84, 0x3600
	s_mov_b32 s101, 0
	v_lshl_add_u64 v[248:249], v[4:5], 0, s[100:101]
	global_load_ushort v234, v[248:249], off
	s_mul_i32 s100, s83, 0x3600
	s_mov_b32 s101, 0
	v_lshl_add_u64 v[248:249], v[4:5], 0, s[100:101]
	global_load_ushort v235, v[248:249], off
	s_mul_i32 s100, s82, 0x3600
	s_mov_b32 s101, 0
	v_lshl_add_u64 v[248:249], v[4:5], 0, s[100:101]
	global_load_ushort v236, v[248:249], off
	s_mul_i32 s100, s81, 0x3600
	s_mov_b32 s101, 0
	v_lshl_add_u64 v[248:249], v[4:5], 0, s[100:101]
	global_load_ushort v237, v[248:249], off
	s_mul_i32 s100, s80, 0x3600
	s_mov_b32 s101, 0
	v_lshl_add_u64 v[248:249], v[4:5], 0, s[100:101]
	global_load_ushort v238, v[248:249], off
	s_mul_i32 s100, s79, 0x3600
	s_mov_b32 s101, 0
	v_lshl_add_u64 v[248:249], v[4:5], 0, s[100:101]
	global_load_ushort v239, v[248:249], off
	s_mul_i32 s100, s78, 0x3600
	s_mov_b32 s101, 0
	v_lshl_add_u64 v[248:249], v[4:5], 0, s[100:101]
	global_load_ushort v240, v[248:249], off
	s_mul_i32 s100, s77, 0x3600
	s_mov_b32 s101, 0
	v_lshl_add_u64 v[248:249], v[4:5], 0, s[100:101]
	global_load_ushort v241, v[248:249], off
	s_mul_i32 s100, s76, 0x3600
	s_mov_b32 s101, 0
	v_lshl_add_u64 v[248:249], v[4:5], 0, s[100:101]
	global_load_ushort v242, v[248:249], off
	s_mul_i32 s100, s75, 0x3600
	s_mov_b32 s101, 0
	v_lshl_add_u64 v[248:249], v[4:5], 0, s[100:101]
	global_load_ushort v243, v[248:249], off
	s_mul_i32 s100, s74, 0x3600
	s_mov_b32 s101, 0
	v_lshl_add_u64 v[248:249], v[4:5], 0, s[100:101]
	global_load_ushort v244, v[248:249], off
	s_mul_i32 s100, s73, 0x3600
	s_mov_b32 s101, 0
	v_lshl_add_u64 v[248:249], v[4:5], 0, s[100:101]
	global_load_ushort v245, v[248:249], off
	s_mul_i32 s100, s72, 0x3600
	s_mov_b32 s101, 0
	v_lshl_add_u64 v[248:249], v[4:5], 0, s[100:101]
	global_load_ushort v246, v[248:249], off
	v_sub_f32_e32 v0, 1.0, v2
	s_movk_i32 s43, 0x300
	s_waitcnt vmcnt(28)
; #define LAS __attribute__((address_space(3)))
; __device__ __forceinline__ float bf2f(unsigned v) { return __uint_as_float(v << 16); }
; __device__ __forceinline__ unsigned pk2(float lo, float hi) { const f32x2_t v = {lo, hi}; const bf16x2_t b = __builtin_convertvector(v, bf16x2_t); return __builtin_bit_cast(unsigned, b); }
; __device__ __forceinline__ float sigmoidf_(float x) { return __builtin_amdgcn_rcpf(1.0f + __builtin_amdgcn_exp2f(-1.4426950408889634f * x)); }
; __device__ __forceinline__ void hgrn_h1_item(const Ctx& F, const bf16_t* PB, const float* logits, int l, int item, float* GS, float* HA, LAS unsigned char* scrb) {
;     ...
;         float kh[8];
; #pragma unroll
;         for (int i = 7; i >= 0; --i) {
;             const float pre = bf2f(PB[(size_t)hg_row(dir, c, 8 * cb + i) * INW + colf]);
;             const float f = lb + (1.0f - lb) * sigmoidf_(pre);
;             kh[i] = (1.0f - f) * __expf(r);
;             r += __logf(f);
;         }
;         const u32x4 w = {pk2(kh[0], kh[1]), pk2(kh[2], kh[3]), pk2(kh[4], kh[5]), pk2(kh[6], kh[7])};
;         *(LAS u32x4*)(TKh + lane * TP + 16 * cb) = w;
	v_lshlrev_b32_e32 v3, 16, v218
	v_mul_f32_e32 v3, 0xbfb8aa3b, v3
	v_exp_f32_e32 v3, v3
	s_nop 0
	v_add_f32_e32 v3, 1.0, v3
	v_rcp_f32_e32 v3, v3
	s_nop 0
	v_fma_f32 v3, v3, v0, v2
	v_cmp_gt_f32_e32 vcc, s35, v3
	v_sub_f32_e32 v16, 1.0, v3
	s_nop 0
	v_cndmask_b32_e64 v6, 0, 32, vcc
	v_ldexp_f32 v3, v3, v6
	v_log_f32_e32 v3, v3
	s_nop 0
	v_mul_f32_e32 v6, 0x3f317217, v3
	v_fma_f32 v6, v3, s31, -v6
	v_fmac_f32_e32 v6, 0x3377d1cf, v3
	v_fmac_f32_e32 v6, 0x3f317217, v3
	v_cmp_lt_f32_e64 s[4:5], |v3|, s34
	s_nop 1
	v_cndmask_b32_e64 v3, v3, v6, s[4:5]
	s_mul_i32 s4, s7, 0x3600
	v_cndmask_b32_e32 v6, 0, v206, vcc
	s_ashr_i32 s5, s4, 31
	v_sub_f32_e32 v3, v3, v6
	v_lshl_add_u64 v[6:7], v[4:5], 0, s[4:5]
	s_mul_i32 s100, s71, 0x3600
	s_mov_b32 s101, 0
	v_lshl_add_u64 v[248:249], v[4:5], 0, s[100:101]
	global_load_ushort v247, v[248:249], off
	v_add_f32_e32 v3, 0, v3
	v_mul_f32_e32 v8, 0x3fb8aa3b, v3
	v_exp_f32_e32 v8, v8
	s_waitcnt vmcnt(28)
	v_lshlrev_b32_e32 v6, 16, v219
	v_mul_f32_e32 v6, 0xbfb8aa3b, v6
	v_exp_f32_e32 v6, v6
	s_nop 0
	v_add_f32_e32 v6, 1.0, v6
	v_rcp_f32_e32 v6, v6
	s_nop 0
	v_fma_f32 v6, v6, v0, v2
	v_sub_f32_e32 v7, 1.0, v6
	v_cmp_gt_f32_e32 vcc, s35, v6
	v_mul_f32_e32 v17, v7, v8
	s_nop 0
	v_cndmask_b32_e64 v7, 0, 32, vcc
	v_ldexp_f32 v6, v6, v7
	v_log_f32_e32 v6, v6
	s_nop 0
	v_mul_f32_e32 v7, 0x3f317217, v6
	v_fma_f32 v7, v6, s31, -v7
	v_fmac_f32_e32 v7, 0x3377d1cf, v6
	v_fmac_f32_e32 v7, 0x3f317217, v6
	v_cmp_lt_f32_e64 s[4:5], |v6|, s34
	s_nop 1
	v_cndmask_b32_e64 v6, v6, v7, s[4:5]
	v_cndmask_b32_e32 v7, 0, v206, vcc
	s_mul_i32 s4, s6, 0x3600
	v_sub_f32_e32 v6, v6, v7
	s_ashr_i32 s5, s4, 31
	v_add_f32_e32 v3, v6, v3
	v_lshl_add_u64 v[6:7], v[4:5], 0, s[4:5]
	s_mul_i32 s100, s70, 0x3600
	s_mov_b32 s101, 0
	v_lshl_add_u64 v[248:249], v[4:5], 0, s[100:101]
	global_load_ushort v218, v[248:249], off
	s_mul_i32 s4, s97, 0x3600
	s_ashr_i32 s5, s4, 31
	v_lshl_add_u64 v[10:11], v[4:5], 0, s[4:5]
	s_movk_i32 s6, 0x100
	s_waitcnt vmcnt(28)
	v_lshlrev_b32_e32 v6, 16, v220
	v_mul_f32_e32 v6, 0xbfb8aa3b, v6
	v_exp_f32_e32 v6, v6
	s_nop 0
	v_add_f32_e32 v6, 1.0, v6
	v_rcp_f32_e32 v7, v6
	v_mul_f32_e32 v6, 0x3fb8aa3b, v3
	v_exp_f32_e32 v9, v6
	s_mul_i32 s100, s69, 0x3600
	s_mov_b32 s101, 0
	v_lshl_add_u64 v[248:249], v[4:5], 0, s[100:101]
	global_load_ushort v219, v[248:249], off
	s_waitcnt vmcnt(28)
	v_lshlrev_b32_e32 v6, 16, v221
	v_mul_f32_e32 v6, 0xbfb8aa3b, v6
	v_exp_f32_e32 v6, v6
	s_nop 0
	v_add_f32_e32 v6, 1.0, v6
	v_rcp_f32_e32 v6, v6
	s_nop 0
	v_pk_fma_f32 v[6:7], v[0:1], v[6:7], v[2:3] op_sel_hi:[0,1,0]
	v_cmp_gt_f32_e32 vcc, s35, v7
	s_nop 1
	v_cndmask_b32_e64 v8, 0, 32, vcc
	v_ldexp_f32 v8, v7, v8
	v_log_f32_e32 v8, v8
	s_nop 0
	v_mul_f32_e32 v10, 0x3f317217, v8
	v_fma_f32 v10, v8, s31, -v10
	v_fmac_f32_e32 v10, 0x3377d1cf, v8
	v_fmac_f32_e32 v10, 0x3f317217, v8
	v_cmp_lt_f32_e64 s[4:5], |v8|, s34
	s_nop 1
	v_cndmask_b32_e64 v8, v8, v10, s[4:5]
	v_cndmask_b32_e32 v10, 0, v206, vcc
	v_sub_f32_e32 v8, v8, v10
	v_add_f32_e32 v3, v8, v3
	v_pk_add_f32 v[10:11], v[6:7], 1.0 op_sel_hi:[1,0] neg_lo:[1,0] neg_hi:[1,0]
	v_mul_f32_e32 v7, 0x3fb8aa3b, v3
	v_cmp_gt_f32_e32 vcc, s35, v6
	v_exp_f32_e32 v8, v7
	s_nop 0
	v_cndmask_b32_e64 v7, 0, 32, vcc
	v_ldexp_f32 v6, v6, v7
	v_log_f32_e32 v6, v6
	v_pk_mul_f32 v[8:9], v[10:11], v[8:9]
	v_mul_f32_e32 v7, 0x3f317217, v6
	v_fma_f32 v7, v6, s31, -v7
	v_fmac_f32_e32 v7, 0x3377d1cf, v6
	v_fmac_f32_e32 v7, 0x3f317217, v6
	v_cmp_lt_f32_e64 s[4:5], |v6|, s34
	v_cvt_pk_bf16_f32 v8, v8, v9
	v_cvt_pk_bf16_f32 v9, v17, v16
	v_cndmask_b32_e64 v6, v6, v7, s[4:5]
	v_cndmask_b32_e32 v7, 0, v206, vcc
	s_mul_i32 s4, s96, 0x3600
	v_sub_f32_e32 v6, v6, v7
	s_ashr_i32 s5, s4, 31
	v_add_f32_e32 v3, v6, v3
	v_lshl_add_u64 v[6:7], v[4:5], 0, s[4:5]
	s_mul_i32 s100, s68, 0x3600
	s_mov_b32 s101, 0
	v_lshl_add_u64 v[248:249], v[4:5], 0, s[100:101]
	global_load_ushort v220, v[248:249], off
	s_mul_i32 s4, s95, 0x3600
	s_ashr_i32 s5, s4, 31
	v_lshl_add_u64 v[12:13], v[4:5], 0, s[4:5]
	s_waitcnt vmcnt(28)
	v_lshlrev_b32_e32 v6, 16, v222
	v_mul_f32_e32 v6, 0xbfb8aa3b, v6
	v_exp_f32_e32 v6, v6
	s_nop 0
	v_add_f32_e32 v6, 1.0, v6
	v_rcp_f32_e32 v7, v6
	v_mul_f32_e32 v6, 0x3fb8aa3b, v3
	v_exp_f32_e32 v11, v6
	s_mul_i32 s100, s67, 0x3600
	s_mov_b32 s101, 0
	v_lshl_add_u64 v[248:249], v[4:5], 0, s[100:101]
	global_load_ushort v221, v[248:249], off
	s_waitcnt vmcnt(28)
	v_lshlrev_b32_e32 v6, 16, v223
	v_mul_f32_e32 v6, 0xbfb8aa3b, v6
	v_exp_f32_e32 v6, v6
	s_nop 0
	v_add_f32_e32 v6, 1.0, v6
	v_rcp_f32_e32 v6, v6
	s_nop 0
	v_pk_fma_f32 v[6:7], v[0:1], v[6:7], v[2:3] op_sel_hi:[0,1,0]
	v_cmp_gt_f32_e32 vcc, s35, v7
	s_nop 1
	v_cndmask_b32_e64 v10, 0, 32, vcc
	v_ldexp_f32 v10, v7, v10
	v_log_f32_e32 v10, v10
	s_nop 0
	v_mul_f32_e32 v12, 0x3f317217, v10
	v_fma_f32 v12, v10, s31, -v12
	v_fmac_f32_e32 v12, 0x3377d1cf, v10
	v_fmac_f32_e32 v12, 0x3f317217, v10
	v_cmp_lt_f32_e64 s[4:5], |v10|, s34
	s_nop 1
	v_cndmask_b32_e64 v10, v10, v12, s[4:5]
	v_cndmask_b32_e32 v12, 0, v206, vcc
	v_sub_f32_e32 v10, v10, v12
	v_add_f32_e32 v3, v10, v3
	v_pk_add_f32 v[12:13], v[6:7], 1.0 op_sel_hi:[1,0] neg_lo:[1,0] neg_hi:[1,0]
	v_mul_f32_e32 v7, 0x3fb8aa3b, v3
	v_cmp_gt_f32_e32 vcc, s35, v6
	v_exp_f32_e32 v10, v7
	s_nop 0
	v_cndmask_b32_e64 v7, 0, 32, vcc
	v_ldexp_f32 v6, v6, v7
	v_log_f32_e32 v6, v6
	v_pk_mul_f32 v[10:11], v[12:13], v[10:11]
	v_mul_f32_e32 v7, 0x3f317217, v6
	v_fma_f32 v7, v6, s31, -v7
	v_fmac_f32_e32 v7, 0x3377d1cf, v6
	v_fmac_f32_e32 v7, 0x3f317217, v6
	v_cmp_lt_f32_e64 s[4:5], |v6|, s34
	s_nop 1
	v_cndmask_b32_e64 v6, v6, v7, s[4:5]
	v_cndmask_b32_e32 v7, 0, v206, vcc
	s_mul_i32 s4, s94, 0x3600
	v_sub_f32_e32 v6, v6, v7
	s_ashr_i32 s5, s4, 31
	v_add_f32_e32 v3, v6, v3
	v_lshl_add_u64 v[6:7], v[4:5], 0, s[4:5]
	s_mul_i32 s100, s66, 0x3600
	s_mov_b32 s101, 0
	v_lshl_add_u64 v[248:249], v[4:5], 0, s[100:101]
	global_load_ushort v222, v[248:249], off
	s_mul_i32 s4, s93, 0x3600
	s_ashr_i32 s5, s4, 31
	v_lshl_add_u64 v[14:15], v[4:5], 0, s[4:5]
	s_waitcnt vmcnt(28)
; #define LAS __attribute__((address_space(3)))
; __device__ __forceinline__ float bf2f(unsigned v) { return __uint_as_float(v << 16); }
; __device__ __forceinline__ unsigned pk2(float lo, float hi) { const f32x2_t v = {lo, hi}; const bf16x2_t b = __builtin_convertvector(v, bf16x2_t); return __builtin_bit_cast(unsigned, b); }
; __device__ __forceinline__ float sigmoidf_(float x) { return __builtin_amdgcn_rcpf(1.0f + __builtin_amdgcn_exp2f(-1.4426950408889634f * x)); }
; __device__ __forceinline__ void hgrn_h1_item(const Ctx& F, const bf16_t* PB, const float* logits, int l, int item, float* GS, float* HA, LAS unsigned char* scrb) {
;     ...
;         float kh[8];
; #pragma unroll
;         for (int i = 7; i >= 0; --i) {
;             const float pre = bf2f(PB[(size_t)hg_row(dir, c, 8 * cb + i) * INW + colf]);
;             const float f = lb + (1.0f - lb) * sigmoidf_(pre);
;             kh[i] = (1.0f - f) * __expf(r);
;             r += __logf(f);
;         }
;         const u32x4 w = {pk2(kh[0], kh[1]), pk2(kh[2], kh[3]), pk2(kh[4], kh[5]), pk2(kh[6], kh[7])};
;         *(LAS u32x4*)(TKh + lane * TP + 16 * cb) = w;
	v_lshlrev_b32_e32 v6, 16, v224
	v_mul_f32_e32 v6, 0xbfb8aa3b, v6
	v_exp_f32_e32 v6, v6
	s_nop 0
	v_add_f32_e32 v6, 1.0, v6
	v_rcp_f32_e32 v7, v6
	v_mul_f32_e32 v6, 0x3fb8aa3b, v3
	v_exp_f32_e32 v13, v6
	s_mul_i32 s100, s65, 0x3600
	s_mov_b32 s101, 0
	v_lshl_add_u64 v[248:249], v[4:5], 0, s[100:101]
	global_load_ushort v223, v[248:249], off
	s_waitcnt vmcnt(28)
	v_lshlrev_b32_e32 v6, 16, v225
	v_mul_f32_e32 v6, 0xbfb8aa3b, v6
	v_exp_f32_e32 v6, v6
	s_nop 0
	v_add_f32_e32 v6, 1.0, v6
	v_rcp_f32_e32 v6, v6
	s_nop 0
	v_pk_fma_f32 v[6:7], v[0:1], v[6:7], v[2:3] op_sel_hi:[0,1,0]
	v_cmp_gt_f32_e32 vcc, s35, v7
	s_nop 1
	v_cndmask_b32_e64 v12, 0, 32, vcc
	v_ldexp_f32 v12, v7, v12
	v_log_f32_e32 v12, v12
	s_nop 0
	v_mul_f32_e32 v14, 0x3f317217, v12
	v_fma_f32 v14, v12, s31, -v14
	v_fmac_f32_e32 v14, 0x3377d1cf, v12
	v_fmac_f32_e32 v14, 0x3f317217, v12
	v_cmp_lt_f32_e64 s[4:5], |v12|, s34
	s_nop 1
	v_cndmask_b32_e64 v12, v12, v14, s[4:5]
	v_cndmask_b32_e32 v14, 0, v206, vcc
	v_sub_f32_e32 v12, v12, v14
	v_add_f32_e32 v3, v12, v3
	v_pk_add_f32 v[14:15], v[6:7], 1.0 op_sel_hi:[1,0] neg_lo:[1,0] neg_hi:[1,0]
	v_mul_f32_e32 v7, 0x3fb8aa3b, v3
	v_cmp_gt_f32_e32 vcc, s35, v6
	v_exp_f32_e32 v12, v7
	s_nop 0
	v_cndmask_b32_e64 v7, 0, 32, vcc
	v_ldexp_f32 v6, v6, v7
	v_log_f32_e32 v6, v6
	v_pk_mul_f32 v[12:13], v[14:15], v[12:13]
	v_mul_f32_e32 v7, 0x3f317217, v6
	v_fma_f32 v7, v6, s31, -v7
	v_fmac_f32_e32 v7, 0x3377d1cf, v6
	v_fmac_f32_e32 v7, 0x3f317217, v6
	v_cmp_lt_f32_e64 s[4:5], |v6|, s34
	s_nop 1
	v_cndmask_b32_e64 v6, v6, v7, s[4:5]
	v_cndmask_b32_e32 v7, 0, v206, vcc
	v_sub_f32_e32 v6, v6, v7
	s_mul_i32 s4, s92, 0x3600
	v_add_f32_e32 v3, v6, v3
	v_cvt_pk_bf16_f32 v6, v12, v13
	v_cvt_pk_bf16_f32 v7, v10, v11
	s_ashr_i32 s5, s4, 31
	ds_write_b128 v99, v[6:9] offset:112
	v_lshl_add_u64 v[6:7], v[4:5], 0, s[4:5]
	s_mul_i32 s100, s64, 0x3600
	s_mov_b32 s101, 0
	v_lshl_add_u64 v[248:249], v[4:5], 0, s[100:101]
	global_load_ushort v224, v[248:249], off
	s_mul_i32 s4, s91, 0x3600
	s_ashr_i32 s5, s4, 31
	v_lshl_add_u64 v[10:11], v[4:5], 0, s[4:5]
	s_waitcnt vmcnt(28)
	v_lshlrev_b32_e32 v6, 16, v226
	v_mul_f32_e32 v6, 0xbfb8aa3b, v6
	v_exp_f32_e32 v6, v6
	s_nop 0
	v_add_f32_e32 v6, 1.0, v6
	v_rcp_f32_e32 v7, v6
	v_mul_f32_e32 v6, 0x3fb8aa3b, v3
	v_exp_f32_e32 v9, v6
	s_mul_i32 s100, s63, 0x3600
	s_mov_b32 s101, 0
	v_lshl_add_u64 v[248:249], v[4:5], 0, s[100:101]
	global_load_ushort v225, v[248:249], off
	s_waitcnt vmcnt(28)
	v_lshlrev_b32_e32 v6, 16, v227
	v_mul_f32_e32 v6, 0xbfb8aa3b, v6
	v_exp_f32_e32 v6, v6
	s_nop 0
	v_add_f32_e32 v6, 1.0, v6
	v_rcp_f32_e32 v6, v6
	s_nop 0
	v_pk_fma_f32 v[6:7], v[0:1], v[6:7], v[2:3] op_sel_hi:[0,1,0]
	v_cmp_gt_f32_e32 vcc, s35, v7
	s_nop 1
	v_cndmask_b32_e64 v8, 0, 32, vcc
	v_ldexp_f32 v8, v7, v8
	v_log_f32_e32 v8, v8
	s_nop 0
	v_mul_f32_e32 v10, 0x3f317217, v8
	v_fma_f32 v10, v8, s31, -v10
	v_fmac_f32_e32 v10, 0x3377d1cf, v8
	v_fmac_f32_e32 v10, 0x3f317217, v8
	v_cmp_lt_f32_e64 s[4:5], |v8|, s34
	s_nop 1
	v_cndmask_b32_e64 v8, v8, v10, s[4:5]
	v_cndmask_b32_e32 v10, 0, v206, vcc
	v_sub_f32_e32 v8, v8, v10
	v_add_f32_e32 v3, v8, v3
	v_pk_add_f32 v[10:11], v[6:7], 1.0 op_sel_hi:[1,0] neg_lo:[1,0] neg_hi:[1,0]
	v_mul_f32_e32 v7, 0x3fb8aa3b, v3
	v_cmp_gt_f32_e32 vcc, s35, v6
	v_exp_f32_e32 v8, v7
	s_nop 0
	v_cndmask_b32_e64 v7, 0, 32, vcc
	v_ldexp_f32 v6, v6, v7
	v_log_f32_e32 v6, v6
	v_pk_mul_f32 v[10:11], v[10:11], v[8:9]
	v_mul_f32_e32 v7, 0x3f317217, v6
	v_fma_f32 v7, v6, s31, -v7
	v_fmac_f32_e32 v7, 0x3377d1cf, v6
	v_fmac_f32_e32 v7, 0x3f317217, v6
	v_cmp_lt_f32_e64 s[4:5], |v6|, s34
	s_nop 1
	v_cndmask_b32_e64 v6, v6, v7, s[4:5]
	v_cndmask_b32_e32 v7, 0, v206, vcc
	s_mul_i32 s4, s90, 0x3600
	v_sub_f32_e32 v6, v6, v7
	s_ashr_i32 s5, s4, 31
	v_add_f32_e32 v3, v6, v3
	v_lshl_add_u64 v[6:7], v[4:5], 0, s[4:5]
	s_mul_i32 s100, s23, 0x3600
	s_mov_b32 s101, 0
	v_lshl_add_u64 v[248:249], v[4:5], 0, s[100:101]
	global_load_ushort v226, v[248:249], off
	s_mul_i32 s4, s89, 0x3600
	s_ashr_i32 s5, s4, 31
	v_lshl_add_u64 v[12:13], v[4:5], 0, s[4:5]
	s_waitcnt vmcnt(28)
	v_lshlrev_b32_e32 v6, 16, v228
	v_mul_f32_e32 v6, 0xbfb8aa3b, v6
	v_exp_f32_e32 v6, v6
	s_nop 0
	v_add_f32_e32 v6, 1.0, v6
	v_rcp_f32_e32 v7, v6
	v_mul_f32_e32 v6, 0x3fb8aa3b, v3
	v_exp_f32_e32 v9, v6
	s_mul_i32 s100, s22, 0x3600
	s_mov_b32 s101, 0
	v_lshl_add_u64 v[248:249], v[4:5], 0, s[100:101]
	global_load_ushort v227, v[248:249], off
	s_waitcnt vmcnt(28)
	v_lshlrev_b32_e32 v6, 16, v229
	v_mul_f32_e32 v6, 0xbfb8aa3b, v6
	v_exp_f32_e32 v6, v6
	s_nop 0
	v_add_f32_e32 v6, 1.0, v6
	v_rcp_f32_e32 v6, v6
	s_nop 0
	v_pk_fma_f32 v[6:7], v[0:1], v[6:7], v[2:3] op_sel_hi:[0,1,0]
	v_cmp_gt_f32_e32 vcc, s35, v7
	s_nop 1
	v_cndmask_b32_e64 v8, 0, 32, vcc
	v_ldexp_f32 v8, v7, v8
	v_log_f32_e32 v8, v8
	s_nop 0
	v_mul_f32_e32 v12, 0x3f317217, v8
	v_fma_f32 v12, v8, s31, -v12
	v_fmac_f32_e32 v12, 0x3377d1cf, v8
	v_fmac_f32_e32 v12, 0x3f317217, v8
	v_cmp_lt_f32_e64 s[4:5], |v8|, s34
	s_nop 1
	v_cndmask_b32_e64 v8, v8, v12, s[4:5]
	v_cndmask_b32_e32 v12, 0, v206, vcc
	v_sub_f32_e32 v8, v8, v12
	v_add_f32_e32 v3, v8, v3
	v_pk_add_f32 v[12:13], v[6:7], 1.0 op_sel_hi:[1,0] neg_lo:[1,0] neg_hi:[1,0]
	v_mul_f32_e32 v7, 0x3fb8aa3b, v3
	v_cmp_gt_f32_e32 vcc, s35, v6
	v_exp_f32_e32 v8, v7
	s_nop 0
	v_cndmask_b32_e64 v7, 0, 32, vcc
	v_ldexp_f32 v6, v6, v7
	v_log_f32_e32 v6, v6
	v_pk_mul_f32 v[8:9], v[12:13], v[8:9]
	v_mul_f32_e32 v7, 0x3f317217, v6
	v_fma_f32 v7, v6, s31, -v7
	v_fmac_f32_e32 v7, 0x3377d1cf, v6
	v_fmac_f32_e32 v7, 0x3f317217, v6
	v_cmp_lt_f32_e64 s[4:5], |v6|, s34
	v_cvt_pk_bf16_f32 v8, v8, v9
	v_cvt_pk_bf16_f32 v9, v10, v11
	v_cndmask_b32_e64 v6, v6, v7, s[4:5]
	v_cndmask_b32_e32 v7, 0, v206, vcc
	s_mul_i32 s4, s88, 0x3600
	v_sub_f32_e32 v6, v6, v7
	s_ashr_i32 s5, s4, 31
	v_add_f32_e32 v3, v6, v3
	v_lshl_add_u64 v[6:7], v[4:5], 0, s[4:5]
	s_mul_i32 s100, s20, 0x3600
	s_mov_b32 s101, 0
	v_lshl_add_u64 v[248:249], v[4:5], 0, s[100:101]
	global_load_ushort v228, v[248:249], off
	s_mul_i32 s4, s87, 0x3600
	s_ashr_i32 s5, s4, 31
	v_lshl_add_u64 v[14:15], v[4:5], 0, s[4:5]
	s_waitcnt vmcnt(28)
; #define LAS __attribute__((address_space(3)))
; __device__ __forceinline__ float bf2f(unsigned v) { return __uint_as_float(v << 16); }
; __device__ __forceinline__ unsigned pk2(float lo, float hi) { const f32x2_t v = {lo, hi}; const bf16x2_t b = __builtin_convertvector(v, bf16x2_t); return __builtin_bit_cast(unsigned, b); }
; __device__ __forceinline__ float sigmoidf_(float x) { return __builtin_amdgcn_rcpf(1.0f + __builtin_amdgcn_exp2f(-1.4426950408889634f * x)); }
; __device__ __forceinline__ void hgrn_h1_item(const Ctx& F, const bf16_t* PB, const float* logits, int l, int item, float* GS, float* HA, LAS unsigned char* scrb) {
;     ...
;         float kh[8];
; #pragma unroll
;         for (int i = 7; i >= 0; --i) {
;             const float pre = bf2f(PB[(size_t)hg_row(dir, c, 8 * cb + i) * INW + colf]);
;             const float f = lb + (1.0f - lb) * sigmoidf_(pre);
;             kh[i] = (1.0f - f) * __expf(r);
;             r += __logf(f);
;         }
;         const u32x4 w = {pk2(kh[0], kh[1]), pk2(kh[2], kh[3]), pk2(kh[4], kh[5]), pk2(kh[6], kh[7])};
;         *(LAS u32x4*)(TKh + lane * TP + 16 * cb) = w;
	v_lshlrev_b32_e32 v6, 16, v230
	v_mul_f32_e32 v6, 0xbfb8aa3b, v6
	v_exp_f32_e32 v6, v6
	s_nop 0
	v_add_f32_e32 v6, 1.0, v6
	v_rcp_f32_e32 v7, v6
	v_mul_f32_e32 v6, 0x3fb8aa3b, v3
	v_exp_f32_e32 v13, v6
	s_mul_i32 s100, s62, 0x3600
	s_mov_b32 s101, 0
	v_lshl_add_u64 v[248:249], v[4:5], 0, s[100:101]
	global_load_ushort v229, v[248:249], off
	s_waitcnt vmcnt(28)
	v_lshlrev_b32_e32 v6, 16, v231
	v_mul_f32_e32 v6, 0xbfb8aa3b, v6
	v_exp_f32_e32 v6, v6
	s_nop 0
	v_add_f32_e32 v6, 1.0, v6
	v_rcp_f32_e32 v6, v6
	s_nop 0
	v_pk_fma_f32 v[6:7], v[0:1], v[6:7], v[2:3] op_sel_hi:[0,1,0]
	v_cmp_gt_f32_e32 vcc, s35, v7
	s_nop 1
	v_cndmask_b32_e64 v12, 0, 32, vcc
	v_ldexp_f32 v12, v7, v12
	v_log_f32_e32 v12, v12
	s_nop 0
	v_mul_f32_e32 v14, 0x3f317217, v12
	v_fma_f32 v14, v12, s31, -v14
	v_fmac_f32_e32 v14, 0x3377d1cf, v12
	v_fmac_f32_e32 v14, 0x3f317217, v12
	v_cmp_lt_f32_e64 s[4:5], |v12|, s34
	s_nop 1
	v_cndmask_b32_e64 v12, v12, v14, s[4:5]
	v_cndmask_b32_e32 v14, 0, v206, vcc
	v_sub_f32_e32 v12, v12, v14
	v_add_f32_e32 v3, v12, v3
	v_pk_add_f32 v[14:15], v[6:7], 1.0 op_sel_hi:[1,0] neg_lo:[1,0] neg_hi:[1,0]
	v_mul_f32_e32 v7, 0x3fb8aa3b, v3
	v_cmp_gt_f32_e32 vcc, s35, v6
	v_exp_f32_e32 v12, v7
	s_nop 0
	v_cndmask_b32_e64 v7, 0, 32, vcc
	v_ldexp_f32 v6, v6, v7
	v_log_f32_e32 v6, v6
	v_pk_mul_f32 v[12:13], v[14:15], v[12:13]
	v_mul_f32_e32 v7, 0x3f317217, v6
	v_fma_f32 v7, v6, s31, -v7
	v_fmac_f32_e32 v7, 0x3377d1cf, v6
	v_fmac_f32_e32 v7, 0x3f317217, v6
	v_cmp_lt_f32_e64 s[4:5], |v6|, s34
	s_nop 1
	v_cndmask_b32_e64 v6, v6, v7, s[4:5]
	v_cndmask_b32_e32 v7, 0, v206, vcc
	s_mul_i32 s4, s86, 0x3600
	v_sub_f32_e32 v6, v6, v7
	s_ashr_i32 s5, s4, 31
	v_add_f32_e32 v3, v6, v3
	v_lshl_add_u64 v[6:7], v[4:5], 0, s[4:5]
	s_mul_i32 s100, s59, 0x3600
	s_mov_b32 s101, 0
	v_lshl_add_u64 v[248:249], v[4:5], 0, s[100:101]
	global_load_ushort v230, v[248:249], off
	s_mul_i32 s4, s85, 0x3600
	s_ashr_i32 s5, s4, 31
	v_lshl_add_u64 v[16:17], v[4:5], 0, s[4:5]
	s_waitcnt vmcnt(28)
	v_lshlrev_b32_e32 v6, 16, v232
	v_mul_f32_e32 v6, 0xbfb8aa3b, v6
	v_exp_f32_e32 v6, v6
	s_nop 0
	v_add_f32_e32 v6, 1.0, v6
	v_rcp_f32_e32 v7, v6
	v_mul_f32_e32 v6, 0x3fb8aa3b, v3
	v_exp_f32_e32 v15, v6
	s_mul_i32 s100, s58, 0x3600
	s_mov_b32 s101, 0
	v_lshl_add_u64 v[248:249], v[4:5], 0, s[100:101]
	global_load_ushort v231, v[248:249], off
	s_waitcnt vmcnt(28)
	v_lshlrev_b32_e32 v6, 16, v233
	v_mul_f32_e32 v6, 0xbfb8aa3b, v6
	v_exp_f32_e32 v6, v6
	s_nop 0
	v_add_f32_e32 v6, 1.0, v6
	v_rcp_f32_e32 v6, v6
	s_nop 0
	v_pk_fma_f32 v[6:7], v[0:1], v[6:7], v[2:3] op_sel_hi:[0,1,0]
	v_cmp_gt_f32_e32 vcc, s35, v7
	s_nop 1
	v_cndmask_b32_e64 v14, 0, 32, vcc
	v_ldexp_f32 v14, v7, v14
	v_log_f32_e32 v14, v14
	s_nop 0
	v_mul_f32_e32 v16, 0x3f317217, v14
	v_fma_f32 v16, v14, s31, -v16
	v_fmac_f32_e32 v16, 0x3377d1cf, v14
	v_fmac_f32_e32 v16, 0x3f317217, v14
	v_cmp_lt_f32_e64 s[4:5], |v14|, s34
	s_nop 1
	v_cndmask_b32_e64 v14, v14, v16, s[4:5]
	v_cndmask_b32_e32 v16, 0, v206, vcc
	v_sub_f32_e32 v14, v14, v16
	v_add_f32_e32 v3, v14, v3
	v_pk_add_f32 v[16:17], v[6:7], 1.0 op_sel_hi:[1,0] neg_lo:[1,0] neg_hi:[1,0]
	v_mul_f32_e32 v7, 0x3fb8aa3b, v3
	v_cmp_gt_f32_e32 vcc, s35, v6
	v_exp_f32_e32 v14, v7
	s_nop 0
	v_cndmask_b32_e64 v7, 0, 32, vcc
	v_ldexp_f32 v6, v6, v7
	v_log_f32_e32 v6, v6
	v_pk_mul_f32 v[14:15], v[16:17], v[14:15]
	v_mul_f32_e32 v7, 0x3f317217, v6
	v_fma_f32 v7, v6, s31, -v7
	v_fmac_f32_e32 v7, 0x3377d1cf, v6
	v_fmac_f32_e32 v7, 0x3f317217, v6
	v_cmp_lt_f32_e64 s[4:5], |v6|, s34
	s_nop 1
	v_cndmask_b32_e64 v6, v6, v7, s[4:5]
	v_cndmask_b32_e32 v7, 0, v206, vcc
	v_sub_f32_e32 v6, v6, v7
	s_mul_i32 s4, s84, 0x3600
	v_add_f32_e32 v3, v6, v3
	v_cvt_pk_bf16_f32 v6, v14, v15
	v_cvt_pk_bf16_f32 v7, v12, v13
	s_ashr_i32 s5, s4, 31
	ds_write_b128 v99, v[6:9] offset:96
	v_lshl_add_u64 v[6:7], v[4:5], 0, s[4:5]
	s_mul_i32 s100, s2, 0x3600
	s_mov_b32 s101, 0
	v_lshl_add_u64 v[248:249], v[4:5], 0, s[100:101]
	global_load_ushort v232, v[248:249], off
	s_mul_i32 s4, s83, 0x3600
	s_ashr_i32 s5, s4, 31
	v_lshl_add_u64 v[10:11], v[4:5], 0, s[4:5]
	v_readlane_b32 s84, v252, 27
	v_readlane_b32 s85, v252, 28
	s_waitcnt vmcnt(28)
	v_lshlrev_b32_e32 v6, 16, v234
	v_mul_f32_e32 v6, 0xbfb8aa3b, v6
	v_exp_f32_e32 v6, v6
	s_nop 0
	v_add_f32_e32 v6, 1.0, v6
	v_rcp_f32_e32 v7, v6
	v_mul_f32_e32 v6, 0x3fb8aa3b, v3
	v_exp_f32_e32 v9, v6
	s_mul_i32 s100, s57, 0x3600
	s_mov_b32 s101, 0
	v_lshl_add_u64 v[248:249], v[4:5], 0, s[100:101]
	global_load_ushort v233, v[248:249], off
	s_waitcnt vmcnt(28)
	v_lshlrev_b32_e32 v6, 16, v235
	v_mul_f32_e32 v6, 0xbfb8aa3b, v6
	v_exp_f32_e32 v6, v6
	s_nop 0
	v_add_f32_e32 v6, 1.0, v6
	v_rcp_f32_e32 v6, v6
	s_nop 0
	v_pk_fma_f32 v[6:7], v[0:1], v[6:7], v[2:3] op_sel_hi:[0,1,0]
	v_cmp_gt_f32_e32 vcc, s35, v7
	s_nop 1
	v_cndmask_b32_e64 v8, 0, 32, vcc
	v_ldexp_f32 v8, v7, v8
	v_log_f32_e32 v8, v8
	s_nop 0
	v_mul_f32_e32 v10, 0x3f317217, v8
	v_fma_f32 v10, v8, s31, -v10
	v_fmac_f32_e32 v10, 0x3377d1cf, v8
	v_fmac_f32_e32 v10, 0x3f317217, v8
	v_cmp_lt_f32_e64 s[4:5], |v8|, s34
	s_nop 1
	v_cndmask_b32_e64 v8, v8, v10, s[4:5]
	v_cndmask_b32_e32 v10, 0, v206, vcc
	v_sub_f32_e32 v8, v8, v10
	v_add_f32_e32 v3, v3, v8
	v_pk_add_f32 v[10:11], v[6:7], 1.0 op_sel_hi:[1,0] neg_lo:[1,0] neg_hi:[1,0]
	v_mul_f32_e32 v7, 0x3fb8aa3b, v3
	v_cmp_gt_f32_e32 vcc, s35, v6
	v_exp_f32_e32 v8, v7
	s_nop 0
	v_cndmask_b32_e64 v7, 0, 32, vcc
	v_ldexp_f32 v6, v6, v7
	v_log_f32_e32 v6, v6
	v_pk_mul_f32 v[10:11], v[10:11], v[8:9]
	v_mul_f32_e32 v7, 0x3f317217, v6
	v_fma_f32 v7, v6, s31, -v7
	v_fmac_f32_e32 v7, 0x3377d1cf, v6
	v_fmac_f32_e32 v7, 0x3f317217, v6
	v_cmp_lt_f32_e64 s[4:5], |v6|, s34
	s_nop 1
	v_cndmask_b32_e64 v6, v6, v7, s[4:5]
	v_cndmask_b32_e32 v7, 0, v206, vcc
	s_mul_i32 s4, s82, 0x3600
	v_sub_f32_e32 v6, v6, v7
	s_ashr_i32 s5, s4, 31
	v_add_f32_e32 v3, v3, v6
	v_lshl_add_u64 v[6:7], v[4:5], 0, s[4:5]
	s_mul_i32 s100, s56, 0x3600
	s_mov_b32 s101, 0
	v_lshl_add_u64 v[248:249], v[4:5], 0, s[100:101]
	global_load_ushort v234, v[248:249], off
	s_mul_i32 s4, s81, 0x3600
	s_ashr_i32 s5, s4, 31
	v_lshl_add_u64 v[12:13], v[4:5], 0, s[4:5]
	s_waitcnt vmcnt(28)
; #define LAS __attribute__((address_space(3)))
; __device__ __forceinline__ float bf2f(unsigned v) { return __uint_as_float(v << 16); }
; __device__ __forceinline__ unsigned pk2(float lo, float hi) { const f32x2_t v = {lo, hi}; const bf16x2_t b = __builtin_convertvector(v, bf16x2_t); return __builtin_bit_cast(unsigned, b); }
; __device__ __forceinline__ float sigmoidf_(float x) { return __builtin_amdgcn_rcpf(1.0f + __builtin_amdgcn_exp2f(-1.4426950408889634f * x)); }
; __device__ __forceinline__ void hgrn_h1_item(const Ctx& F, const bf16_t* PB, const float* logits, int l, int item, float* GS, float* HA, LAS unsigned char* scrb) {
;     ...
;         float kh[8];
; #pragma unroll
;         for (int i = 7; i >= 0; --i) {
;             const float pre = bf2f(PB[(size_t)hg_row(dir, c, 8 * cb + i) * INW + colf]);
;             const float f = lb + (1.0f - lb) * sigmoidf_(pre);
;             kh[i] = (1.0f - f) * __expf(r);
;             r += __logf(f);
;         }
;         const u32x4 w = {pk2(kh[0], kh[1]), pk2(kh[2], kh[3]), pk2(kh[4], kh[5]), pk2(kh[6], kh[7])};
;         *(LAS u32x4*)(TKh + lane * TP + 16 * cb) = w;
	v_lshlrev_b32_e32 v6, 16, v236
	v_mul_f32_e32 v6, 0xbfb8aa3b, v6
	v_exp_f32_e32 v6, v6
	s_nop 0
	v_add_f32_e32 v6, 1.0, v6
	v_rcp_f32_e32 v7, v6
	v_mul_f32_e32 v6, 0x3fb8aa3b, v3
	v_exp_f32_e32 v9, v6
	s_mul_i32 s100, s55, 0x3600
	s_mov_b32 s101, 0
	v_lshl_add_u64 v[248:249], v[4:5], 0, s[100:101]
	global_load_ushort v235, v[248:249], off
	s_waitcnt vmcnt(28)
	v_lshlrev_b32_e32 v6, 16, v237
	v_mul_f32_e32 v6, 0xbfb8aa3b, v6
	v_exp_f32_e32 v6, v6
	s_nop 0
	v_add_f32_e32 v6, 1.0, v6
	v_rcp_f32_e32 v6, v6
	s_nop 0
	v_pk_fma_f32 v[6:7], v[0:1], v[6:7], v[2:3] op_sel_hi:[0,1,0]
	v_cmp_gt_f32_e32 vcc, s35, v7
	s_nop 1
	v_cndmask_b32_e64 v8, 0, 32, vcc
	v_ldexp_f32 v8, v7, v8
	v_log_f32_e32 v8, v8
	s_nop 0
	v_mul_f32_e32 v12, 0x3f317217, v8
	v_fma_f32 v12, v8, s31, -v12
	v_fmac_f32_e32 v12, 0x3377d1cf, v8
	v_fmac_f32_e32 v12, 0x3f317217, v8
	v_cmp_lt_f32_e64 s[4:5], |v8|, s34
	s_nop 1
	v_cndmask_b32_e64 v8, v8, v12, s[4:5]
	v_cndmask_b32_e32 v12, 0, v206, vcc
	v_sub_f32_e32 v8, v8, v12
	v_add_f32_e32 v3, v3, v8
	v_pk_add_f32 v[12:13], v[6:7], 1.0 op_sel_hi:[1,0] neg_lo:[1,0] neg_hi:[1,0]
	v_mul_f32_e32 v7, 0x3fb8aa3b, v3
	v_cmp_gt_f32_e32 vcc, s35, v6
	v_exp_f32_e32 v8, v7
	s_nop 0
	v_cndmask_b32_e64 v7, 0, 32, vcc
	v_ldexp_f32 v6, v6, v7
	v_log_f32_e32 v6, v6
	v_pk_mul_f32 v[8:9], v[12:13], v[8:9]
	v_mul_f32_e32 v7, 0x3f317217, v6
	v_fma_f32 v7, v6, s31, -v7
	v_fmac_f32_e32 v7, 0x3377d1cf, v6
	v_fmac_f32_e32 v7, 0x3f317217, v6
	v_cmp_lt_f32_e64 s[4:5], |v6|, s34
	v_cvt_pk_bf16_f32 v8, v8, v9
	v_cvt_pk_bf16_f32 v9, v10, v11
	v_cndmask_b32_e64 v6, v6, v7, s[4:5]
	v_cndmask_b32_e32 v7, 0, v206, vcc
	s_mul_i32 s4, s80, 0x3600
	v_sub_f32_e32 v6, v6, v7
	s_ashr_i32 s5, s4, 31
	v_add_f32_e32 v3, v3, v6
	v_lshl_add_u64 v[6:7], v[4:5], 0, s[4:5]
	s_mul_i32 s100, s25, 0x3600
	s_mov_b32 s101, 0
	v_lshl_add_u64 v[248:249], v[4:5], 0, s[100:101]
	global_load_ushort v236, v[248:249], off
	s_mul_i32 s4, s79, 0x3600
	s_ashr_i32 s5, s4, 31
	v_lshl_add_u64 v[14:15], v[4:5], 0, s[4:5]
	s_waitcnt vmcnt(28)
	v_lshlrev_b32_e32 v6, 16, v238
	v_mul_f32_e32 v6, 0xbfb8aa3b, v6
	v_exp_f32_e32 v6, v6
	s_nop 0
	v_add_f32_e32 v6, 1.0, v6
	v_rcp_f32_e32 v7, v6
	v_mul_f32_e32 v6, 0x3fb8aa3b, v3
	v_exp_f32_e32 v13, v6
	s_mul_i32 s100, s24, 0x3600
	s_mov_b32 s101, 0
	v_lshl_add_u64 v[248:249], v[4:5], 0, s[100:101]
	global_load_ushort v237, v[248:249], off
	s_waitcnt vmcnt(28)
	v_lshlrev_b32_e32 v6, 16, v239
	v_mul_f32_e32 v6, 0xbfb8aa3b, v6
	v_exp_f32_e32 v6, v6
	s_nop 0
	v_add_f32_e32 v6, 1.0, v6
	v_rcp_f32_e32 v6, v6
	s_nop 0
	v_pk_fma_f32 v[6:7], v[0:1], v[6:7], v[2:3] op_sel_hi:[0,1,0]
	v_cmp_gt_f32_e32 vcc, s35, v7
	s_nop 1
	v_cndmask_b32_e64 v12, 0, 32, vcc
	v_ldexp_f32 v12, v7, v12
	v_log_f32_e32 v12, v12
	s_nop 0
	v_mul_f32_e32 v14, 0x3f317217, v12
	v_fma_f32 v14, v12, s31, -v14
	v_fmac_f32_e32 v14, 0x3377d1cf, v12
	v_fmac_f32_e32 v14, 0x3f317217, v12
	v_cmp_lt_f32_e64 s[4:5], |v12|, s34
	s_nop 1
	v_cndmask_b32_e64 v12, v12, v14, s[4:5]
	v_cndmask_b32_e32 v14, 0, v206, vcc
	v_sub_f32_e32 v12, v12, v14
	v_add_f32_e32 v3, v3, v12
	v_pk_add_f32 v[14:15], v[6:7], 1.0 op_sel_hi:[1,0] neg_lo:[1,0] neg_hi:[1,0]
	v_mul_f32_e32 v7, 0x3fb8aa3b, v3
	v_cmp_gt_f32_e32 vcc, s35, v6
	v_exp_f32_e32 v12, v7
	s_nop 0
	v_cndmask_b32_e64 v7, 0, 32, vcc
	v_ldexp_f32 v6, v6, v7
	v_log_f32_e32 v6, v6
	v_pk_mul_f32 v[12:13], v[14:15], v[12:13]
	v_mul_f32_e32 v7, 0x3f317217, v6
	v_fma_f32 v7, v6, s31, -v7
	v_fmac_f32_e32 v7, 0x3377d1cf, v6
	v_fmac_f32_e32 v7, 0x3f317217, v6
	v_cmp_lt_f32_e64 s[4:5], |v6|, s34
	s_nop 1
	v_cndmask_b32_e64 v6, v6, v7, s[4:5]
	v_cndmask_b32_e32 v7, 0, v206, vcc
	s_mul_i32 s4, s78, 0x3600
	v_sub_f32_e32 v6, v6, v7
	s_ashr_i32 s5, s4, 31
	v_add_f32_e32 v3, v3, v6
	v_lshl_add_u64 v[6:7], v[4:5], 0, s[4:5]
	s_mul_i32 s100, s53, 0x3600
	s_mov_b32 s101, 0
	v_lshl_add_u64 v[248:249], v[4:5], 0, s[100:101]
	global_load_ushort v238, v[248:249], off
	s_mul_i32 s4, s77, 0x3600
	s_ashr_i32 s5, s4, 31
	v_lshl_add_u64 v[16:17], v[4:5], 0, s[4:5]
	s_waitcnt vmcnt(28)
	v_lshlrev_b32_e32 v6, 16, v240
	v_mul_f32_e32 v6, 0xbfb8aa3b, v6
	v_exp_f32_e32 v6, v6
	s_nop 0
	v_add_f32_e32 v6, 1.0, v6
	v_rcp_f32_e32 v7, v6
	v_mul_f32_e32 v6, 0x3fb8aa3b, v3
	v_exp_f32_e32 v15, v6
	s_mul_i32 s100, s52, 0x3600
	s_mov_b32 s101, 0
	v_lshl_add_u64 v[248:249], v[4:5], 0, s[100:101]
	global_load_ushort v239, v[248:249], off
	s_waitcnt vmcnt(28)
	v_lshlrev_b32_e32 v6, 16, v241
	v_mul_f32_e32 v6, 0xbfb8aa3b, v6
	v_exp_f32_e32 v6, v6
	s_nop 0
	v_add_f32_e32 v6, 1.0, v6
	v_rcp_f32_e32 v6, v6
	s_nop 0
	v_pk_fma_f32 v[6:7], v[0:1], v[6:7], v[2:3] op_sel_hi:[0,1,0]
	v_cmp_gt_f32_e32 vcc, s35, v7
	s_nop 1
	v_cndmask_b32_e64 v14, 0, 32, vcc
	v_ldexp_f32 v14, v7, v14
	v_log_f32_e32 v14, v14
	s_nop 0
	v_mul_f32_e32 v16, 0x3f317217, v14
	v_fma_f32 v16, v14, s31, -v16
	v_fmac_f32_e32 v16, 0x3377d1cf, v14
	v_fmac_f32_e32 v16, 0x3f317217, v14
	v_cmp_lt_f32_e64 s[4:5], |v14|, s34
	s_nop 1
	v_cndmask_b32_e64 v14, v14, v16, s[4:5]
	v_cndmask_b32_e32 v16, 0, v206, vcc
	v_sub_f32_e32 v14, v14, v16
	v_add_f32_e32 v3, v3, v14
	v_pk_add_f32 v[16:17], v[6:7], 1.0 op_sel_hi:[1,0] neg_lo:[1,0] neg_hi:[1,0]
	v_mul_f32_e32 v7, 0x3fb8aa3b, v3
	v_cmp_gt_f32_e32 vcc, s35, v6
	v_exp_f32_e32 v14, v7
	s_nop 0
	v_cndmask_b32_e64 v7, 0, 32, vcc
	v_ldexp_f32 v6, v6, v7
	v_log_f32_e32 v6, v6
	v_pk_mul_f32 v[14:15], v[16:17], v[14:15]
	v_mul_f32_e32 v7, 0x3f317217, v6
	v_fma_f32 v7, v6, s31, -v7
	v_fmac_f32_e32 v7, 0x3377d1cf, v6
	v_fmac_f32_e32 v7, 0x3f317217, v6
	v_cmp_lt_f32_e64 s[4:5], |v6|, s34
	s_nop 1
	v_cndmask_b32_e64 v6, v6, v7, s[4:5]
	v_cndmask_b32_e32 v7, 0, v206, vcc
	v_sub_f32_e32 v6, v6, v7
	s_mul_i32 s4, s76, 0x3600
	v_add_f32_e32 v3, v3, v6
	v_cvt_pk_bf16_f32 v6, v14, v15
	v_cvt_pk_bf16_f32 v7, v12, v13
	s_ashr_i32 s5, s4, 31
	ds_write_b128 v99, v[6:9] offset:80
	v_lshl_add_u64 v[6:7], v[4:5], 0, s[4:5]
	s_mul_i32 s100, s51, 0x3600
	s_mov_b32 s101, 0
	v_lshl_add_u64 v[248:249], v[4:5], 0, s[100:101]
	global_load_ushort v240, v[248:249], off
	s_mul_i32 s4, s75, 0x3600
	s_ashr_i32 s5, s4, 31
	v_lshl_add_u64 v[10:11], v[4:5], 0, s[4:5]
	s_waitcnt vmcnt(28)
; #define LAS __attribute__((address_space(3)))
; __device__ __forceinline__ float bf2f(unsigned v) { return __uint_as_float(v << 16); }
; __device__ __forceinline__ unsigned pk2(float lo, float hi) { const f32x2_t v = {lo, hi}; const bf16x2_t b = __builtin_convertvector(v, bf16x2_t); return __builtin_bit_cast(unsigned, b); }
; __device__ __forceinline__ float sigmoidf_(float x) { return __builtin_amdgcn_rcpf(1.0f + __builtin_amdgcn_exp2f(-1.4426950408889634f * x)); }
; __device__ __forceinline__ void hgrn_h1_item(const Ctx& F, const bf16_t* PB, const float* logits, int l, int item, float* GS, float* HA, LAS unsigned char* scrb) {
;     ...
;         float kh[8];
; #pragma unroll
;         for (int i = 7; i >= 0; --i) {
;             const float pre = bf2f(PB[(size_t)hg_row(dir, c, 8 * cb + i) * INW + colf]);
;             const float f = lb + (1.0f - lb) * sigmoidf_(pre);
;             kh[i] = (1.0f - f) * __expf(r);
;             r += __logf(f);
;         }
;         const u32x4 w = {pk2(kh[0], kh[1]), pk2(kh[2], kh[3]), pk2(kh[4], kh[5]), pk2(kh[6], kh[7])};
;         *(LAS u32x4*)(TKh + lane * TP + 16 * cb) = w;
	v_lshlrev_b32_e32 v6, 16, v242
	v_mul_f32_e32 v6, 0xbfb8aa3b, v6
	v_exp_f32_e32 v6, v6
	s_nop 0
	v_add_f32_e32 v6, 1.0, v6
	v_rcp_f32_e32 v7, v6
	v_mul_f32_e32 v6, 0x3fb8aa3b, v3
	v_exp_f32_e32 v9, v6
	s_mul_i32 s100, s50, 0x3600
	s_mov_b32 s101, 0
	v_lshl_add_u64 v[248:249], v[4:5], 0, s[100:101]
	global_load_ushort v241, v[248:249], off
	s_waitcnt vmcnt(28)
	v_lshlrev_b32_e32 v6, 16, v243
	v_mul_f32_e32 v6, 0xbfb8aa3b, v6
	v_exp_f32_e32 v6, v6
	s_nop 0
	v_add_f32_e32 v6, 1.0, v6
	v_rcp_f32_e32 v6, v6
	s_nop 0
	v_pk_fma_f32 v[6:7], v[0:1], v[6:7], v[2:3] op_sel_hi:[0,1,0]
	v_cmp_gt_f32_e32 vcc, s35, v7
	s_nop 1
	v_cndmask_b32_e64 v8, 0, 32, vcc
	v_ldexp_f32 v8, v7, v8
	v_log_f32_e32 v8, v8
	s_nop 0
	v_mul_f32_e32 v10, 0x3f317217, v8
	v_fma_f32 v10, v8, s31, -v10
	v_fmac_f32_e32 v10, 0x3377d1cf, v8
	v_fmac_f32_e32 v10, 0x3f317217, v8
	v_cmp_lt_f32_e64 s[4:5], |v8|, s34
	s_nop 1
	v_cndmask_b32_e64 v8, v8, v10, s[4:5]
	v_cndmask_b32_e32 v10, 0, v206, vcc
	v_sub_f32_e32 v8, v8, v10
	v_add_f32_e32 v3, v3, v8
	v_pk_add_f32 v[10:11], v[6:7], 1.0 op_sel_hi:[1,0] neg_lo:[1,0] neg_hi:[1,0]
	v_mul_f32_e32 v7, 0x3fb8aa3b, v3
	v_cmp_gt_f32_e32 vcc, s35, v6
	v_exp_f32_e32 v8, v7
	s_nop 0
	v_cndmask_b32_e64 v7, 0, 32, vcc
	v_ldexp_f32 v6, v6, v7
	v_log_f32_e32 v6, v6
	v_pk_mul_f32 v[10:11], v[10:11], v[8:9]
	v_mul_f32_e32 v7, 0x3f317217, v6
	v_fma_f32 v7, v6, s31, -v7
	v_fmac_f32_e32 v7, 0x3377d1cf, v6
	v_fmac_f32_e32 v7, 0x3f317217, v6
	v_cmp_lt_f32_e64 s[4:5], |v6|, s34
	s_nop 1
	v_cndmask_b32_e64 v6, v6, v7, s[4:5]
	v_cndmask_b32_e32 v7, 0, v206, vcc
	s_mul_i32 s4, s74, 0x3600
	v_sub_f32_e32 v6, v6, v7
	s_ashr_i32 s5, s4, 31
	v_add_f32_e32 v3, v3, v6
	v_lshl_add_u64 v[6:7], v[4:5], 0, s[4:5]
	s_mul_i32 s100, s49, 0x3600
	s_mov_b32 s101, 0
	v_lshl_add_u64 v[248:249], v[4:5], 0, s[100:101]
	global_load_ushort v242, v[248:249], off
	s_mul_i32 s4, s73, 0x3600
	s_ashr_i32 s5, s4, 31
	v_lshl_add_u64 v[12:13], v[4:5], 0, s[4:5]
	s_waitcnt vmcnt(28)
	v_lshlrev_b32_e32 v6, 16, v244
	v_mul_f32_e32 v6, 0xbfb8aa3b, v6
	v_exp_f32_e32 v6, v6
	s_nop 0
	v_add_f32_e32 v6, 1.0, v6
	v_rcp_f32_e32 v7, v6
	v_mul_f32_e32 v6, 0x3fb8aa3b, v3
	v_exp_f32_e32 v9, v6
	s_mul_i32 s100, s48, 0x3600
	s_mov_b32 s101, 0
	v_lshl_add_u64 v[248:249], v[4:5], 0, s[100:101]
	global_load_ushort v243, v[248:249], off
	s_waitcnt vmcnt(28)
	v_lshlrev_b32_e32 v6, 16, v245
	v_mul_f32_e32 v6, 0xbfb8aa3b, v6
	v_exp_f32_e32 v6, v6
	s_nop 0
	v_add_f32_e32 v6, 1.0, v6
	v_rcp_f32_e32 v6, v6
	s_nop 0
	v_pk_fma_f32 v[6:7], v[0:1], v[6:7], v[2:3] op_sel_hi:[0,1,0]
	v_cmp_gt_f32_e32 vcc, s35, v7
	s_nop 1
	v_cndmask_b32_e64 v8, 0, 32, vcc
	v_ldexp_f32 v8, v7, v8
	v_log_f32_e32 v8, v8
	s_nop 0
	v_mul_f32_e32 v12, 0x3f317217, v8
	v_fma_f32 v12, v8, s31, -v12
	v_fmac_f32_e32 v12, 0x3377d1cf, v8
	v_fmac_f32_e32 v12, 0x3f317217, v8
	v_cmp_lt_f32_e64 s[4:5], |v8|, s34
	s_nop 1
	v_cndmask_b32_e64 v8, v8, v12, s[4:5]
	v_cndmask_b32_e32 v12, 0, v206, vcc
	v_sub_f32_e32 v8, v8, v12
	v_add_f32_e32 v3, v3, v8
	v_pk_add_f32 v[12:13], v[6:7], 1.0 op_sel_hi:[1,0] neg_lo:[1,0] neg_hi:[1,0]
	v_mul_f32_e32 v7, 0x3fb8aa3b, v3
	v_cmp_gt_f32_e32 vcc, s35, v6
	v_exp_f32_e32 v8, v7
	s_nop 0
	v_cndmask_b32_e64 v7, 0, 32, vcc
	v_ldexp_f32 v6, v6, v7
	v_log_f32_e32 v6, v6
	v_pk_mul_f32 v[8:9], v[12:13], v[8:9]
	v_mul_f32_e32 v7, 0x3f317217, v6
	v_fma_f32 v7, v6, s31, -v7
	v_fmac_f32_e32 v7, 0x3377d1cf, v6
	v_fmac_f32_e32 v7, 0x3f317217, v6
	v_cmp_lt_f32_e64 s[4:5], |v6|, s34
	v_cvt_pk_bf16_f32 v8, v8, v9
	v_cvt_pk_bf16_f32 v9, v10, v11
	v_cndmask_b32_e64 v6, v6, v7, s[4:5]
	v_cndmask_b32_e32 v7, 0, v206, vcc
	s_mul_i32 s4, s72, 0x3600
	v_sub_f32_e32 v6, v6, v7
	s_ashr_i32 s5, s4, 31
	v_add_f32_e32 v3, v3, v6
	v_lshl_add_u64 v[6:7], v[4:5], 0, s[4:5]
	s_mul_i32 s100, s45, 0x3600
	s_mov_b32 s101, 0
	v_lshl_add_u64 v[248:249], v[4:5], 0, s[100:101]
	global_load_ushort v244, v[248:249], off
	s_mul_i32 s4, s71, 0x3600
	s_ashr_i32 s5, s4, 31
	v_lshl_add_u64 v[14:15], v[4:5], 0, s[4:5]
	s_waitcnt vmcnt(28)
	v_lshlrev_b32_e32 v6, 16, v246
	v_mul_f32_e32 v6, 0xbfb8aa3b, v6
	v_exp_f32_e32 v6, v6
	s_nop 0
	v_add_f32_e32 v6, 1.0, v6
	v_rcp_f32_e32 v7, v6
	v_mul_f32_e32 v6, 0x3fb8aa3b, v3
	v_exp_f32_e32 v13, v6
	s_mul_i32 s100, s44, 0x3600
	s_mov_b32 s101, 0
	v_lshl_add_u64 v[248:249], v[4:5], 0, s[100:101]
	global_load_ushort v245, v[248:249], off
	s_waitcnt vmcnt(28)
	v_lshlrev_b32_e32 v6, 16, v247
	v_mul_f32_e32 v6, 0xbfb8aa3b, v6
	v_exp_f32_e32 v6, v6
	s_nop 0
	v_add_f32_e32 v6, 1.0, v6
	v_rcp_f32_e32 v6, v6
	s_nop 0
	v_pk_fma_f32 v[6:7], v[0:1], v[6:7], v[2:3] op_sel_hi:[0,1,0]
	v_cmp_gt_f32_e32 vcc, s35, v7
	s_nop 1
	v_cndmask_b32_e64 v12, 0, 32, vcc
	v_ldexp_f32 v12, v7, v12
	v_log_f32_e32 v12, v12
	s_nop 0
	v_mul_f32_e32 v14, 0x3f317217, v12
	v_fma_f32 v14, v12, s31, -v14
	v_fmac_f32_e32 v14, 0x3377d1cf, v12
	v_fmac_f32_e32 v14, 0x3f317217, v12
	v_cmp_lt_f32_e64 s[4:5], |v12|, s34
	s_nop 1
	v_cndmask_b32_e64 v12, v12, v14, s[4:5]
	v_cndmask_b32_e32 v14, 0, v206, vcc
	v_sub_f32_e32 v12, v12, v14
	v_add_f32_e32 v3, v3, v12
	v_pk_add_f32 v[14:15], v[6:7], 1.0 op_sel_hi:[1,0] neg_lo:[1,0] neg_hi:[1,0]
	v_mul_f32_e32 v7, 0x3fb8aa3b, v3
	v_cmp_gt_f32_e32 vcc, s35, v6
	v_exp_f32_e32 v12, v7
	s_nop 0
	v_cndmask_b32_e64 v7, 0, 32, vcc
	v_ldexp_f32 v6, v6, v7
	v_log_f32_e32 v6, v6
	v_pk_mul_f32 v[12:13], v[14:15], v[12:13]
	v_mul_f32_e32 v7, 0x3f317217, v6
	v_fma_f32 v7, v6, s31, -v7
	v_fmac_f32_e32 v7, 0x3377d1cf, v6
	v_fmac_f32_e32 v7, 0x3f317217, v6
	v_cmp_lt_f32_e64 s[4:5], |v6|, s34
	s_nop 1
	v_cndmask_b32_e64 v6, v6, v7, s[4:5]
	v_cndmask_b32_e32 v7, 0, v206, vcc
	s_mul_i32 s4, s70, 0x3600
	v_sub_f32_e32 v6, v6, v7
	s_ashr_i32 s5, s4, 31
	v_add_f32_e32 v3, v3, v6
	v_lshl_add_u64 v[6:7], v[4:5], 0, s[4:5]
	s_mul_i32 s100, s37, 0x3600
	s_mov_b32 s101, 0
	v_lshl_add_u64 v[248:249], v[4:5], 0, s[100:101]
	global_load_ushort v246, v[248:249], off
	s_mul_i32 s4, s69, 0x3600
	s_ashr_i32 s5, s4, 31
	v_lshl_add_u64 v[16:17], v[4:5], 0, s[4:5]
	s_waitcnt vmcnt(28)
; #define LAS __attribute__((address_space(3)))
; __device__ __forceinline__ float bf2f(unsigned v) { return __uint_as_float(v << 16); }
; __device__ __forceinline__ unsigned pk2(float lo, float hi) { const f32x2_t v = {lo, hi}; const bf16x2_t b = __builtin_convertvector(v, bf16x2_t); return __builtin_bit_cast(unsigned, b); }
; __device__ __forceinline__ float sigmoidf_(float x) { return __builtin_amdgcn_rcpf(1.0f + __builtin_amdgcn_exp2f(-1.4426950408889634f * x)); }
; __device__ __forceinline__ void hgrn_h1_item(const Ctx& F, const bf16_t* PB, const float* logits, int l, int item, float* GS, float* HA, LAS unsigned char* scrb) {
;     ...
;         float kh[8];
; #pragma unroll
;         for (int i = 7; i >= 0; --i) {
;             const float pre = bf2f(PB[(size_t)hg_row(dir, c, 8 * cb + i) * INW + colf]);
;             const float f = lb + (1.0f - lb) * sigmoidf_(pre);
;             kh[i] = (1.0f - f) * __expf(r);
;             r += __logf(f);
;         }
;         const u32x4 w = {pk2(kh[0], kh[1]), pk2(kh[2], kh[3]), pk2(kh[4], kh[5]), pk2(kh[6], kh[7])};
;         *(LAS u32x4*)(TKh + lane * TP + 16 * cb) = w;
	v_lshlrev_b32_e32 v6, 16, v218
	v_mul_f32_e32 v6, 0xbfb8aa3b, v6
	v_exp_f32_e32 v6, v6
	s_nop 0
	v_add_f32_e32 v6, 1.0, v6
	v_rcp_f32_e32 v7, v6
	v_mul_f32_e32 v6, 0x3fb8aa3b, v3
	v_exp_f32_e32 v15, v6
	s_mul_i32 s100, s36, 0x3600
	s_mov_b32 s101, 0
	v_lshl_add_u64 v[248:249], v[4:5], 0, s[100:101]
	global_load_ushort v247, v[248:249], off
	s_waitcnt vmcnt(28)
	v_lshlrev_b32_e32 v6, 16, v219
	v_mul_f32_e32 v6, 0xbfb8aa3b, v6
	v_exp_f32_e32 v6, v6
	s_nop 0
	v_add_f32_e32 v6, 1.0, v6
	v_rcp_f32_e32 v6, v6
	s_nop 0
	v_pk_fma_f32 v[6:7], v[0:1], v[6:7], v[2:3] op_sel_hi:[0,1,0]
	v_cmp_gt_f32_e32 vcc, s35, v7
	s_nop 1
	v_cndmask_b32_e64 v14, 0, 32, vcc
	v_ldexp_f32 v14, v7, v14
	v_log_f32_e32 v14, v14
	s_nop 0
	v_mul_f32_e32 v16, 0x3f317217, v14
	v_fma_f32 v16, v14, s31, -v16
	v_fmac_f32_e32 v16, 0x3377d1cf, v14
	v_fmac_f32_e32 v16, 0x3f317217, v14
	v_cmp_lt_f32_e64 s[4:5], |v14|, s34
	s_nop 1
	v_cndmask_b32_e64 v14, v14, v16, s[4:5]
	v_cndmask_b32_e32 v16, 0, v206, vcc
	v_sub_f32_e32 v14, v14, v16
	v_add_f32_e32 v3, v3, v14
	v_pk_add_f32 v[16:17], v[6:7], 1.0 op_sel_hi:[1,0] neg_lo:[1,0] neg_hi:[1,0]
	v_mul_f32_e32 v7, 0x3fb8aa3b, v3
	v_cmp_gt_f32_e32 vcc, s35, v6
	v_exp_f32_e32 v14, v7
	s_nop 0
	v_cndmask_b32_e64 v7, 0, 32, vcc
	v_ldexp_f32 v6, v6, v7
	v_log_f32_e32 v6, v6
	v_pk_mul_f32 v[14:15], v[16:17], v[14:15]
	v_mul_f32_e32 v7, 0x3f317217, v6
	v_fma_f32 v7, v6, s31, -v7
	v_fmac_f32_e32 v7, 0x3377d1cf, v6
	v_fmac_f32_e32 v7, 0x3f317217, v6
	v_cmp_lt_f32_e64 s[4:5], |v6|, s34
	s_nop 1
	v_cndmask_b32_e64 v6, v6, v7, s[4:5]
	v_cndmask_b32_e32 v7, 0, v206, vcc
	v_sub_f32_e32 v6, v6, v7
	s_mul_i32 s4, s68, 0x3600
	v_add_f32_e32 v3, v3, v6
	v_cvt_pk_bf16_f32 v6, v14, v15
	v_cvt_pk_bf16_f32 v7, v12, v13
	s_ashr_i32 s5, s4, 31
	ds_write_b128 v99, v[6:9] offset:64
	v_lshl_add_u64 v[6:7], v[4:5], 0, s[4:5]
	s_mul_i32 s100, s33, 0x3600
	s_mov_b32 s101, 0
	v_lshl_add_u64 v[248:249], v[4:5], 0, s[100:101]
	global_load_ushort v218, v[248:249], off
	s_mul_i32 s4, s67, 0x3600
	s_ashr_i32 s5, s4, 31
	v_lshl_add_u64 v[10:11], v[4:5], 0, s[4:5]
	s_waitcnt vmcnt(28)
	v_lshlrev_b32_e32 v6, 16, v220
	v_mul_f32_e32 v6, 0xbfb8aa3b, v6
	v_exp_f32_e32 v6, v6
	s_nop 0
	v_add_f32_e32 v6, 1.0, v6
	v_rcp_f32_e32 v7, v6
	v_mul_f32_e32 v6, 0x3fb8aa3b, v3
	v_exp_f32_e32 v9, v6
	s_mul_i32 s100, s27, 0x3600
	s_mov_b32 s101, 0
	v_lshl_add_u64 v[248:249], v[4:5], 0, s[100:101]
	global_load_ushort v219, v[248:249], off
	s_waitcnt vmcnt(28)
	v_lshlrev_b32_e32 v6, 16, v221
	v_mul_f32_e32 v6, 0xbfb8aa3b, v6
	v_exp_f32_e32 v6, v6
	s_nop 0
	v_add_f32_e32 v6, 1.0, v6
	v_rcp_f32_e32 v6, v6
	s_nop 0
	v_pk_fma_f32 v[6:7], v[0:1], v[6:7], v[2:3] op_sel_hi:[0,1,0]
	v_cmp_gt_f32_e32 vcc, s35, v7
	s_nop 1
	v_cndmask_b32_e64 v8, 0, 32, vcc
	v_ldexp_f32 v8, v7, v8
	v_log_f32_e32 v8, v8
	s_nop 0
	v_mul_f32_e32 v10, 0x3f317217, v8
	v_fma_f32 v10, v8, s31, -v10
	v_fmac_f32_e32 v10, 0x3377d1cf, v8
	v_fmac_f32_e32 v10, 0x3f317217, v8
	v_cmp_lt_f32_e64 s[4:5], |v8|, s34
	s_nop 1
	v_cndmask_b32_e64 v8, v8, v10, s[4:5]
	v_cndmask_b32_e32 v10, 0, v206, vcc
	v_sub_f32_e32 v8, v8, v10
	v_add_f32_e32 v3, v3, v8
	v_pk_add_f32 v[10:11], v[6:7], 1.0 op_sel_hi:[1,0] neg_lo:[1,0] neg_hi:[1,0]
	v_mul_f32_e32 v7, 0x3fb8aa3b, v3
	v_cmp_gt_f32_e32 vcc, s35, v6
	v_exp_f32_e32 v8, v7
	s_nop 0
	v_cndmask_b32_e64 v7, 0, 32, vcc
	v_ldexp_f32 v6, v6, v7
	v_log_f32_e32 v6, v6
	v_pk_mul_f32 v[10:11], v[10:11], v[8:9]
	v_mul_f32_e32 v7, 0x3f317217, v6
	v_fma_f32 v7, v6, s31, -v7
	v_fmac_f32_e32 v7, 0x3377d1cf, v6
	v_fmac_f32_e32 v7, 0x3f317217, v6
	v_cmp_lt_f32_e64 s[4:5], |v6|, s34
	s_nop 1
	v_cndmask_b32_e64 v6, v6, v7, s[4:5]
	v_cndmask_b32_e32 v7, 0, v206, vcc
	s_mul_i32 s4, s66, 0x3600
	v_sub_f32_e32 v6, v6, v7
	s_ashr_i32 s5, s4, 31
	v_add_f32_e32 v3, v3, v6
	v_lshl_add_u64 v[6:7], v[4:5], 0, s[4:5]
	s_nop 0
	s_mul_i32 s4, s65, 0x3600
	s_ashr_i32 s5, s4, 31
	v_lshl_add_u64 v[12:13], v[4:5], 0, s[4:5]
	s_waitcnt vmcnt(27)
	v_lshlrev_b32_e32 v6, 16, v222
	v_mul_f32_e32 v6, 0xbfb8aa3b, v6
	v_exp_f32_e32 v6, v6
	s_nop 0
	v_add_f32_e32 v6, 1.0, v6
	v_rcp_f32_e32 v7, v6
	v_mul_f32_e32 v6, 0x3fb8aa3b, v3
	v_exp_f32_e32 v9, v6
	s_nop 0
	s_waitcnt vmcnt(26)
	v_lshlrev_b32_e32 v6, 16, v223
	v_mul_f32_e32 v6, 0xbfb8aa3b, v6
	v_exp_f32_e32 v6, v6
	s_nop 0
	v_add_f32_e32 v6, 1.0, v6
	v_rcp_f32_e32 v6, v6
	s_nop 0
	v_pk_fma_f32 v[6:7], v[0:1], v[6:7], v[2:3] op_sel_hi:[0,1,0]
	v_cmp_gt_f32_e32 vcc, s35, v7
	s_nop 1
	v_cndmask_b32_e64 v8, 0, 32, vcc
	v_ldexp_f32 v8, v7, v8
	v_log_f32_e32 v8, v8
	s_nop 0
	v_mul_f32_e32 v12, 0x3f317217, v8
	v_fma_f32 v12, v8, s31, -v12
	v_fmac_f32_e32 v12, 0x3377d1cf, v8
	v_fmac_f32_e32 v12, 0x3f317217, v8
	v_cmp_lt_f32_e64 s[4:5], |v8|, s34
	s_nop 1
	v_cndmask_b32_e64 v8, v8, v12, s[4:5]
	v_cndmask_b32_e32 v12, 0, v206, vcc
	v_sub_f32_e32 v8, v8, v12
	v_add_f32_e32 v3, v3, v8
	v_pk_add_f32 v[12:13], v[6:7], 1.0 op_sel_hi:[1,0] neg_lo:[1,0] neg_hi:[1,0]
	v_mul_f32_e32 v7, 0x3fb8aa3b, v3
	v_cmp_gt_f32_e32 vcc, s35, v6
	v_exp_f32_e32 v8, v7
	s_nop 0
	v_cndmask_b32_e64 v7, 0, 32, vcc
	v_ldexp_f32 v6, v6, v7
	v_log_f32_e32 v6, v6
	v_pk_mul_f32 v[8:9], v[12:13], v[8:9]
	v_mul_f32_e32 v7, 0x3f317217, v6
	v_fma_f32 v7, v6, s31, -v7
	v_fmac_f32_e32 v7, 0x3377d1cf, v6
	v_fmac_f32_e32 v7, 0x3f317217, v6
	v_cmp_lt_f32_e64 s[4:5], |v6|, s34
	v_cvt_pk_bf16_f32 v8, v8, v9
	v_cvt_pk_bf16_f32 v9, v10, v11
	v_cndmask_b32_e64 v6, v6, v7, s[4:5]
	v_cndmask_b32_e32 v7, 0, v206, vcc
	s_mul_i32 s4, s64, 0x3600
	v_sub_f32_e32 v6, v6, v7
	s_ashr_i32 s5, s4, 31
	v_add_f32_e32 v3, v3, v6
	v_lshl_add_u64 v[6:7], v[4:5], 0, s[4:5]
	s_nop 0
	s_mul_i32 s4, s63, 0x3600
	s_ashr_i32 s5, s4, 31
	v_lshl_add_u64 v[14:15], v[4:5], 0, s[4:5]
	s_waitcnt vmcnt(25)
; #define LAS __attribute__((address_space(3)))
; __device__ __forceinline__ float bf2f(unsigned v) { return __uint_as_float(v << 16); }
; __device__ __forceinline__ unsigned pk2(float lo, float hi) { const f32x2_t v = {lo, hi}; const bf16x2_t b = __builtin_convertvector(v, bf16x2_t); return __builtin_bit_cast(unsigned, b); }
; __device__ __forceinline__ float sigmoidf_(float x) { return __builtin_amdgcn_rcpf(1.0f + __builtin_amdgcn_exp2f(-1.4426950408889634f * x)); }
; __device__ __forceinline__ void hgrn_h1_item(const Ctx& F, const bf16_t* PB, const float* logits, int l, int item, float* GS, float* HA, LAS unsigned char* scrb) {
;     ...
;         float kh[8];
; #pragma unroll
;         for (int i = 7; i >= 0; --i) {
;             const float pre = bf2f(PB[(size_t)hg_row(dir, c, 8 * cb + i) * INW + colf]);
;             const float f = lb + (1.0f - lb) * sigmoidf_(pre);
;             kh[i] = (1.0f - f) * __expf(r);
;             r += __logf(f);
;         }
;         const u32x4 w = {pk2(kh[0], kh[1]), pk2(kh[2], kh[3]), pk2(kh[4], kh[5]), pk2(kh[6], kh[7])};
;         *(LAS u32x4*)(TKh + lane * TP + 16 * cb) = w;
	v_lshlrev_b32_e32 v6, 16, v224
	v_mul_f32_e32 v6, 0xbfb8aa3b, v6
	v_exp_f32_e32 v6, v6
	s_nop 0
	v_add_f32_e32 v6, 1.0, v6
	v_rcp_f32_e32 v7, v6
	v_mul_f32_e32 v6, 0x3fb8aa3b, v3
	v_exp_f32_e32 v13, v6
	s_nop 0
	s_waitcnt vmcnt(24)
	v_lshlrev_b32_e32 v6, 16, v225
	v_mul_f32_e32 v6, 0xbfb8aa3b, v6
	v_exp_f32_e32 v6, v6
	s_nop 0
	v_add_f32_e32 v6, 1.0, v6
	v_rcp_f32_e32 v6, v6
	s_nop 0
	v_pk_fma_f32 v[6:7], v[0:1], v[6:7], v[2:3] op_sel_hi:[0,1,0]
	v_cmp_gt_f32_e32 vcc, s35, v7
	s_nop 1
	v_cndmask_b32_e64 v12, 0, 32, vcc
	v_ldexp_f32 v12, v7, v12
	v_log_f32_e32 v12, v12
	s_nop 0
	v_mul_f32_e32 v14, 0x3f317217, v12
	v_fma_f32 v14, v12, s31, -v14
	v_fmac_f32_e32 v14, 0x3377d1cf, v12
	v_fmac_f32_e32 v14, 0x3f317217, v12
	v_cmp_lt_f32_e64 s[4:5], |v12|, s34
	s_nop 1
	v_cndmask_b32_e64 v12, v12, v14, s[4:5]
	v_cndmask_b32_e32 v14, 0, v206, vcc
	v_sub_f32_e32 v12, v12, v14
	v_add_f32_e32 v3, v3, v12
	v_pk_add_f32 v[14:15], v[6:7], 1.0 op_sel_hi:[1,0] neg_lo:[1,0] neg_hi:[1,0]
	v_mul_f32_e32 v7, 0x3fb8aa3b, v3
	v_cmp_gt_f32_e32 vcc, s35, v6
	v_exp_f32_e32 v12, v7
	s_nop 0
	v_cndmask_b32_e64 v7, 0, 32, vcc
	v_ldexp_f32 v6, v6, v7
	v_log_f32_e32 v6, v6
	v_pk_mul_f32 v[12:13], v[14:15], v[12:13]
	v_mul_f32_e32 v7, 0x3f317217, v6
	v_fma_f32 v7, v6, s31, -v7
	v_fmac_f32_e32 v7, 0x3377d1cf, v6
	v_fmac_f32_e32 v7, 0x3f317217, v6
	v_cmp_lt_f32_e64 s[4:5], |v6|, s34
	s_nop 1
	v_cndmask_b32_e64 v6, v6, v7, s[4:5]
	v_cndmask_b32_e32 v7, 0, v206, vcc
	s_mul_i32 s4, s23, 0x3600
	v_sub_f32_e32 v6, v6, v7
	s_ashr_i32 s5, s4, 31
	v_add_f32_e32 v3, v3, v6
	v_lshl_add_u64 v[6:7], v[4:5], 0, s[4:5]
	s_nop 0
	s_mul_i32 s4, s22, 0x3600
	s_ashr_i32 s5, s4, 31
	v_lshl_add_u64 v[16:17], v[4:5], 0, s[4:5]
	s_waitcnt vmcnt(23)
	v_lshlrev_b32_e32 v6, 16, v226
	v_mul_f32_e32 v6, 0xbfb8aa3b, v6
	v_exp_f32_e32 v6, v6
	s_nop 0
	v_add_f32_e32 v6, 1.0, v6
	v_rcp_f32_e32 v7, v6
	v_mul_f32_e32 v6, 0x3fb8aa3b, v3
	v_exp_f32_e32 v15, v6
	s_nop 0
	s_waitcnt vmcnt(22)
	v_lshlrev_b32_e32 v6, 16, v227
	v_mul_f32_e32 v6, 0xbfb8aa3b, v6
	v_exp_f32_e32 v6, v6
	s_nop 0
	v_add_f32_e32 v6, 1.0, v6
	v_rcp_f32_e32 v6, v6
	s_nop 0
	v_pk_fma_f32 v[6:7], v[0:1], v[6:7], v[2:3] op_sel_hi:[0,1,0]
	v_cmp_gt_f32_e32 vcc, s35, v7
	s_nop 1
	v_cndmask_b32_e64 v14, 0, 32, vcc
	v_ldexp_f32 v14, v7, v14
	v_log_f32_e32 v14, v14
	s_nop 0
	v_mul_f32_e32 v16, 0x3f317217, v14
	v_fma_f32 v16, v14, s31, -v16
	v_fmac_f32_e32 v16, 0x3377d1cf, v14
	v_fmac_f32_e32 v16, 0x3f317217, v14
	v_cmp_lt_f32_e64 s[4:5], |v14|, s34
	s_nop 1
	v_cndmask_b32_e64 v14, v14, v16, s[4:5]
	v_cndmask_b32_e32 v16, 0, v206, vcc
	v_sub_f32_e32 v14, v14, v16
	v_add_f32_e32 v3, v3, v14
	v_pk_add_f32 v[16:17], v[6:7], 1.0 op_sel_hi:[1,0] neg_lo:[1,0] neg_hi:[1,0]
	v_mul_f32_e32 v7, 0x3fb8aa3b, v3
	v_cmp_gt_f32_e32 vcc, s35, v6
	v_exp_f32_e32 v14, v7
	s_nop 0
	v_cndmask_b32_e64 v7, 0, 32, vcc
	v_ldexp_f32 v6, v6, v7
	v_log_f32_e32 v6, v6
	v_pk_mul_f32 v[14:15], v[16:17], v[14:15]
	v_mul_f32_e32 v7, 0x3f317217, v6
	v_fma_f32 v7, v6, s31, -v7
	v_fmac_f32_e32 v7, 0x3377d1cf, v6
	v_fmac_f32_e32 v7, 0x3f317217, v6
	v_cmp_lt_f32_e64 s[4:5], |v6|, s34
	s_nop 1
	v_cndmask_b32_e64 v6, v6, v7, s[4:5]
	v_cndmask_b32_e32 v7, 0, v206, vcc
	v_sub_f32_e32 v6, v6, v7
	s_mul_i32 s4, s20, 0x3600
	v_add_f32_e32 v3, v3, v6
	v_cvt_pk_bf16_f32 v6, v14, v15
	v_cvt_pk_bf16_f32 v7, v12, v13
	s_ashr_i32 s5, s4, 31
	ds_write_b128 v99, v[6:9] offset:48
	v_lshl_add_u64 v[6:7], v[4:5], 0, s[4:5]
	s_nop 0
	s_mul_i32 s4, s62, 0x3600
	s_ashr_i32 s5, s4, 31
	v_lshl_add_u64 v[10:11], v[4:5], 0, s[4:5]
	s_waitcnt vmcnt(21)
	v_lshlrev_b32_e32 v6, 16, v228
	v_mul_f32_e32 v6, 0xbfb8aa3b, v6
	v_exp_f32_e32 v6, v6
	s_nop 0
	v_add_f32_e32 v6, 1.0, v6
	v_rcp_f32_e32 v7, v6
	v_mul_f32_e32 v6, 0x3fb8aa3b, v3
	v_exp_f32_e32 v9, v6
	s_nop 0
	s_waitcnt vmcnt(20)
	v_lshlrev_b32_e32 v6, 16, v229
	v_mul_f32_e32 v6, 0xbfb8aa3b, v6
	v_exp_f32_e32 v6, v6
	s_nop 0
	v_add_f32_e32 v6, 1.0, v6
	v_rcp_f32_e32 v6, v6
	s_nop 0
	v_pk_fma_f32 v[6:7], v[0:1], v[6:7], v[2:3] op_sel_hi:[0,1,0]
	v_cmp_gt_f32_e32 vcc, s35, v7
	s_nop 1
	v_cndmask_b32_e64 v8, 0, 32, vcc
	v_ldexp_f32 v8, v7, v8
	v_log_f32_e32 v8, v8
	s_nop 0
	v_mul_f32_e32 v10, 0x3f317217, v8
	v_fma_f32 v10, v8, s31, -v10
	v_fmac_f32_e32 v10, 0x3377d1cf, v8
	v_fmac_f32_e32 v10, 0x3f317217, v8
	v_cmp_lt_f32_e64 s[4:5], |v8|, s34
	s_nop 1
	v_cndmask_b32_e64 v8, v8, v10, s[4:5]
	v_cndmask_b32_e32 v10, 0, v206, vcc
	v_sub_f32_e32 v8, v8, v10
	v_add_f32_e32 v3, v3, v8
	v_pk_add_f32 v[10:11], v[6:7], 1.0 op_sel_hi:[1,0] neg_lo:[1,0] neg_hi:[1,0]
	v_mul_f32_e32 v7, 0x3fb8aa3b, v3
	v_cmp_gt_f32_e32 vcc, s35, v6
	v_exp_f32_e32 v8, v7
	s_nop 0
	v_cndmask_b32_e64 v7, 0, 32, vcc
	v_ldexp_f32 v6, v6, v7
	v_log_f32_e32 v6, v6
	v_pk_mul_f32 v[10:11], v[10:11], v[8:9]
	v_mul_f32_e32 v7, 0x3f317217, v6
	v_fma_f32 v7, v6, s31, -v7
	v_fmac_f32_e32 v7, 0x3377d1cf, v6
	v_fmac_f32_e32 v7, 0x3f317217, v6
	v_cmp_lt_f32_e64 s[4:5], |v6|, s34
	s_nop 1
	v_cndmask_b32_e64 v6, v6, v7, s[4:5]
	v_cndmask_b32_e32 v7, 0, v206, vcc
	s_mul_i32 s4, s59, 0x3600
	v_sub_f32_e32 v6, v6, v7
	s_ashr_i32 s5, s4, 31
	v_add_f32_e32 v3, v3, v6
	v_lshl_add_u64 v[6:7], v[4:5], 0, s[4:5]
	s_nop 0
	s_mul_i32 s4, s58, 0x3600
	s_ashr_i32 s5, s4, 31
	v_lshl_add_u64 v[12:13], v[4:5], 0, s[4:5]
	s_waitcnt vmcnt(19)
	v_lshlrev_b32_e32 v6, 16, v230
	v_mul_f32_e32 v6, 0xbfb8aa3b, v6
	v_exp_f32_e32 v6, v6
	s_nop 0
	v_add_f32_e32 v6, 1.0, v6
	v_rcp_f32_e32 v7, v6
	v_mul_f32_e32 v6, 0x3fb8aa3b, v3
	v_exp_f32_e32 v9, v6
	s_nop 0
	s_waitcnt vmcnt(18)
; #define LAS __attribute__((address_space(3)))
; __device__ __forceinline__ float bf2f(unsigned v) { return __uint_as_float(v << 16); }
; __device__ __forceinline__ unsigned pk2(float lo, float hi) { const f32x2_t v = {lo, hi}; const bf16x2_t b = __builtin_convertvector(v, bf16x2_t); return __builtin_bit_cast(unsigned, b); }
; __device__ __forceinline__ float sigmoidf_(float x) { return __builtin_amdgcn_rcpf(1.0f + __builtin_amdgcn_exp2f(-1.4426950408889634f * x)); }
; __device__ __forceinline__ void hgrn_h1_item(const Ctx& F, const bf16_t* PB, const float* logits, int l, int item, float* GS, float* HA, LAS unsigned char* scrb) {
;     ...
;         float kh[8];
; #pragma unroll
;         for (int i = 7; i >= 0; --i) {
;             const float pre = bf2f(PB[(size_t)hg_row(dir, c, 8 * cb + i) * INW + colf]);
;             const float f = lb + (1.0f - lb) * sigmoidf_(pre);
;             kh[i] = (1.0f - f) * __expf(r);
;             r += __logf(f);
;         }
;         const u32x4 w = {pk2(kh[0], kh[1]), pk2(kh[2], kh[3]), pk2(kh[4], kh[5]), pk2(kh[6], kh[7])};
;         *(LAS u32x4*)(TKh + lane * TP + 16 * cb) = w;
	v_lshlrev_b32_e32 v6, 16, v231
	v_mul_f32_e32 v6, 0xbfb8aa3b, v6
	v_exp_f32_e32 v6, v6
	s_nop 0
	v_add_f32_e32 v6, 1.0, v6
	v_rcp_f32_e32 v6, v6
	s_nop 0
	v_pk_fma_f32 v[6:7], v[0:1], v[6:7], v[2:3] op_sel_hi:[0,1,0]
	v_cmp_gt_f32_e32 vcc, s35, v7
	s_nop 1
	v_cndmask_b32_e64 v8, 0, 32, vcc
	v_ldexp_f32 v8, v7, v8
	v_log_f32_e32 v8, v8
	s_nop 0
	v_mul_f32_e32 v12, 0x3f317217, v8
	v_fma_f32 v12, v8, s31, -v12
	v_fmac_f32_e32 v12, 0x3377d1cf, v8
	v_fmac_f32_e32 v12, 0x3f317217, v8
	v_cmp_lt_f32_e64 s[4:5], |v8|, s34
	s_nop 1
	v_cndmask_b32_e64 v8, v8, v12, s[4:5]
	v_cndmask_b32_e32 v12, 0, v206, vcc
	v_sub_f32_e32 v8, v8, v12
	v_add_f32_e32 v3, v3, v8
	v_pk_add_f32 v[12:13], v[6:7], 1.0 op_sel_hi:[1,0] neg_lo:[1,0] neg_hi:[1,0]
	v_mul_f32_e32 v7, 0x3fb8aa3b, v3
	v_cmp_gt_f32_e32 vcc, s35, v6
	v_exp_f32_e32 v8, v7
	s_nop 0
	v_cndmask_b32_e64 v7, 0, 32, vcc
	v_ldexp_f32 v6, v6, v7
	v_log_f32_e32 v6, v6
	v_pk_mul_f32 v[8:9], v[12:13], v[8:9]
	v_mul_f32_e32 v7, 0x3f317217, v6
	v_fma_f32 v7, v6, s31, -v7
	v_fmac_f32_e32 v7, 0x3377d1cf, v6
	v_fmac_f32_e32 v7, 0x3f317217, v6
	v_cmp_lt_f32_e64 s[4:5], |v6|, s34
	v_cvt_pk_bf16_f32 v8, v8, v9
	v_cvt_pk_bf16_f32 v9, v10, v11
	v_cndmask_b32_e64 v6, v6, v7, s[4:5]
	v_cndmask_b32_e32 v7, 0, v206, vcc
	s_mul_i32 s4, s2, 0x3600
	v_sub_f32_e32 v6, v6, v7
	s_ashr_i32 s5, s4, 31
	v_add_f32_e32 v3, v3, v6
	v_lshl_add_u64 v[6:7], v[4:5], 0, s[4:5]
	s_nop 0
	s_mul_i32 s4, s57, 0x3600
	s_ashr_i32 s5, s4, 31
	v_lshl_add_u64 v[14:15], v[4:5], 0, s[4:5]
	s_mul_i32 s2, s54, 0x104
	s_add_i32 s2, s2, s28
	s_lshl_b32 s2, s2, 2
	s_waitcnt vmcnt(17)
	v_lshlrev_b32_e32 v6, 16, v232
	v_mul_f32_e32 v6, 0xbfb8aa3b, v6
	v_exp_f32_e32 v6, v6
	s_nop 0
	v_add_f32_e32 v6, 1.0, v6
	v_rcp_f32_e32 v7, v6
	v_mul_f32_e32 v6, 0x3fb8aa3b, v3
	v_exp_f32_e32 v13, v6
	s_nop 0
	s_waitcnt vmcnt(16)
	v_lshlrev_b32_e32 v6, 16, v233
	v_mul_f32_e32 v6, 0xbfb8aa3b, v6
	v_exp_f32_e32 v6, v6
	s_nop 0
	v_add_f32_e32 v6, 1.0, v6
	v_rcp_f32_e32 v6, v6
	s_nop 0
	v_pk_fma_f32 v[6:7], v[0:1], v[6:7], v[2:3] op_sel_hi:[0,1,0]
	v_cmp_gt_f32_e32 vcc, s35, v7
	s_nop 1
	v_cndmask_b32_e64 v12, 0, 32, vcc
	v_ldexp_f32 v12, v7, v12
	v_log_f32_e32 v12, v12
	s_nop 0
	v_mul_f32_e32 v14, 0x3f317217, v12
	v_fma_f32 v14, v12, s31, -v14
	v_fmac_f32_e32 v14, 0x3377d1cf, v12
	v_fmac_f32_e32 v14, 0x3f317217, v12
	v_cmp_lt_f32_e64 s[4:5], |v12|, s34
	s_nop 1
	v_cndmask_b32_e64 v12, v12, v14, s[4:5]
	v_cndmask_b32_e32 v14, 0, v206, vcc
	v_sub_f32_e32 v12, v12, v14
	v_add_f32_e32 v3, v3, v12
	v_pk_add_f32 v[14:15], v[6:7], 1.0 op_sel_hi:[1,0] neg_lo:[1,0] neg_hi:[1,0]
	v_mul_f32_e32 v7, 0x3fb8aa3b, v3
	v_cmp_gt_f32_e32 vcc, s35, v6
	v_exp_f32_e32 v12, v7
	s_nop 0
	v_cndmask_b32_e64 v7, 0, 32, vcc
	v_ldexp_f32 v6, v6, v7
	v_log_f32_e32 v6, v6
	v_pk_mul_f32 v[12:13], v[14:15], v[12:13]
	v_mul_f32_e32 v7, 0x3f317217, v6
	v_fma_f32 v7, v6, s31, -v7
	v_fmac_f32_e32 v7, 0x3377d1cf, v6
	v_fmac_f32_e32 v7, 0x3f317217, v6
	v_cmp_lt_f32_e64 s[4:5], |v6|, s34
	s_nop 1
	v_cndmask_b32_e64 v6, v6, v7, s[4:5]
	v_cndmask_b32_e32 v7, 0, v206, vcc
	s_mul_i32 s4, s56, 0x3600
	v_sub_f32_e32 v6, v6, v7
	s_ashr_i32 s5, s4, 31
	v_add_f32_e32 v3, v3, v6
	v_lshl_add_u64 v[6:7], v[4:5], 0, s[4:5]
	s_nop 0
	s_mul_i32 s4, s55, 0x3600
	s_ashr_i32 s5, s4, 31
	v_lshl_add_u64 v[16:17], v[4:5], 0, s[4:5]
	s_waitcnt vmcnt(15)
	v_lshlrev_b32_e32 v6, 16, v234
	v_mul_f32_e32 v6, 0xbfb8aa3b, v6
	v_exp_f32_e32 v6, v6
	s_nop 0
	v_add_f32_e32 v6, 1.0, v6
	v_rcp_f32_e32 v7, v6
	v_mul_f32_e32 v6, 0x3fb8aa3b, v3
	v_exp_f32_e32 v15, v6
	s_nop 0
	s_waitcnt vmcnt(14)
	v_lshlrev_b32_e32 v6, 16, v235
	v_mul_f32_e32 v6, 0xbfb8aa3b, v6
	v_exp_f32_e32 v6, v6
	s_nop 0
	v_add_f32_e32 v6, 1.0, v6
	v_rcp_f32_e32 v6, v6
	s_nop 0
	v_pk_fma_f32 v[6:7], v[0:1], v[6:7], v[2:3] op_sel_hi:[0,1,0]
	v_cmp_gt_f32_e32 vcc, s35, v7
	s_nop 1
	v_cndmask_b32_e64 v14, 0, 32, vcc
	v_ldexp_f32 v14, v7, v14
	v_log_f32_e32 v14, v14
	s_nop 0
	v_mul_f32_e32 v16, 0x3f317217, v14
	v_fma_f32 v16, v14, s31, -v16
	v_fmac_f32_e32 v16, 0x3377d1cf, v14
	v_fmac_f32_e32 v16, 0x3f317217, v14
	v_cmp_lt_f32_e64 s[4:5], |v14|, s34
	s_nop 1
	v_cndmask_b32_e64 v14, v14, v16, s[4:5]
	v_cndmask_b32_e32 v16, 0, v206, vcc
	v_sub_f32_e32 v14, v14, v16
	v_add_f32_e32 v3, v3, v14
	v_pk_add_f32 v[16:17], v[6:7], 1.0 op_sel_hi:[1,0] neg_lo:[1,0] neg_hi:[1,0]
	v_mul_f32_e32 v7, 0x3fb8aa3b, v3
	v_cmp_gt_f32_e32 vcc, s35, v6
	v_exp_f32_e32 v14, v7
	s_nop 0
	v_cndmask_b32_e64 v7, 0, 32, vcc
	v_ldexp_f32 v6, v6, v7
	v_log_f32_e32 v6, v6
	v_pk_mul_f32 v[14:15], v[16:17], v[14:15]
	v_mul_f32_e32 v7, 0x3f317217, v6
	v_fma_f32 v7, v6, s31, -v7
	v_fmac_f32_e32 v7, 0x3377d1cf, v6
	v_fmac_f32_e32 v7, 0x3f317217, v6
	v_cmp_lt_f32_e64 s[4:5], |v6|, s34
	s_nop 1
	v_cndmask_b32_e64 v6, v6, v7, s[4:5]
	v_cndmask_b32_e32 v7, 0, v206, vcc
	v_sub_f32_e32 v6, v6, v7
	s_mul_i32 s4, s25, 0x3600
	v_add_f32_e32 v3, v3, v6
	v_cvt_pk_bf16_f32 v6, v14, v15
	v_cvt_pk_bf16_f32 v7, v12, v13
	s_ashr_i32 s5, s4, 31
	ds_write_b128 v99, v[6:9] offset:32
	v_lshl_add_u64 v[6:7], v[4:5], 0, s[4:5]
	s_nop 0
	s_mul_i32 s4, s24, 0x3600
	s_ashr_i32 s5, s4, 31
	v_lshl_add_u64 v[10:11], v[4:5], 0, s[4:5]
	s_waitcnt vmcnt(13)
	v_lshlrev_b32_e32 v6, 16, v236
	v_mul_f32_e32 v6, 0xbfb8aa3b, v6
	v_exp_f32_e32 v6, v6
	s_nop 0
	v_add_f32_e32 v6, 1.0, v6
	v_rcp_f32_e32 v7, v6
	v_mul_f32_e32 v6, 0x3fb8aa3b, v3
	v_exp_f32_e32 v9, v6
	s_nop 0
	s_waitcnt vmcnt(12)
; #define LAS __attribute__((address_space(3)))
; __device__ __forceinline__ float bf2f(unsigned v) { return __uint_as_float(v << 16); }
; __device__ __forceinline__ unsigned pk2(float lo, float hi) { const f32x2_t v = {lo, hi}; const bf16x2_t b = __builtin_convertvector(v, bf16x2_t); return __builtin_bit_cast(unsigned, b); }
; __device__ __forceinline__ float sigmoidf_(float x) { return __builtin_amdgcn_rcpf(1.0f + __builtin_amdgcn_exp2f(-1.4426950408889634f * x)); }
; __device__ __forceinline__ void hgrn_h1_item(const Ctx& F, const bf16_t* PB, const float* logits, int l, int item, float* GS, float* HA, LAS unsigned char* scrb) {
;     ...
;         float kh[8];
; #pragma unroll
;         for (int i = 7; i >= 0; --i) {
;             const float pre = bf2f(PB[(size_t)hg_row(dir, c, 8 * cb + i) * INW + colf]);
;             const float f = lb + (1.0f - lb) * sigmoidf_(pre);
;             kh[i] = (1.0f - f) * __expf(r);
;             r += __logf(f);
;         }
;         const u32x4 w = {pk2(kh[0], kh[1]), pk2(kh[2], kh[3]), pk2(kh[4], kh[5]), pk2(kh[6], kh[7])};
;         *(LAS u32x4*)(TKh + lane * TP + 16 * cb) = w;
	v_lshlrev_b32_e32 v6, 16, v237
	v_mul_f32_e32 v6, 0xbfb8aa3b, v6
	v_exp_f32_e32 v6, v6
	s_nop 0
	v_add_f32_e32 v6, 1.0, v6
	v_rcp_f32_e32 v6, v6
	s_nop 0
	v_pk_fma_f32 v[6:7], v[0:1], v[6:7], v[2:3] op_sel_hi:[0,1,0]
	v_cmp_gt_f32_e32 vcc, s35, v7
	s_nop 1
	v_cndmask_b32_e64 v8, 0, 32, vcc
	v_ldexp_f32 v8, v7, v8
	v_log_f32_e32 v8, v8
	s_nop 0
	v_mul_f32_e32 v10, 0x3f317217, v8
	v_fma_f32 v10, v8, s31, -v10
	v_fmac_f32_e32 v10, 0x3377d1cf, v8
	v_fmac_f32_e32 v10, 0x3f317217, v8
	v_cmp_lt_f32_e64 s[4:5], |v8|, s34
	s_nop 1
	v_cndmask_b32_e64 v8, v8, v10, s[4:5]
	v_cndmask_b32_e32 v10, 0, v206, vcc
	v_sub_f32_e32 v8, v8, v10
	v_add_f32_e32 v3, v3, v8
	v_pk_add_f32 v[10:11], v[6:7], 1.0 op_sel_hi:[1,0] neg_lo:[1,0] neg_hi:[1,0]
	v_mul_f32_e32 v7, 0x3fb8aa3b, v3
	v_cmp_gt_f32_e32 vcc, s35, v6
	v_exp_f32_e32 v8, v7
	s_nop 0
	v_cndmask_b32_e64 v7, 0, 32, vcc
	v_ldexp_f32 v6, v6, v7
	v_log_f32_e32 v6, v6
	v_pk_mul_f32 v[10:11], v[10:11], v[8:9]
	v_mul_f32_e32 v7, 0x3f317217, v6
	v_fma_f32 v7, v6, s31, -v7
	v_fmac_f32_e32 v7, 0x3377d1cf, v6
	v_fmac_f32_e32 v7, 0x3f317217, v6
	v_cmp_lt_f32_e64 s[4:5], |v6|, s34
	s_nop 1
	v_cndmask_b32_e64 v6, v6, v7, s[4:5]
	v_cndmask_b32_e32 v7, 0, v206, vcc
	s_mul_i32 s4, s53, 0x3600
	v_sub_f32_e32 v6, v6, v7
	s_ashr_i32 s5, s4, 31
	v_add_f32_e32 v3, v3, v6
	v_lshl_add_u64 v[6:7], v[4:5], 0, s[4:5]
	s_nop 0
	s_mul_i32 s4, s52, 0x3600
	s_ashr_i32 s5, s4, 31
	v_lshl_add_u64 v[12:13], v[4:5], 0, s[4:5]
	s_waitcnt vmcnt(11)
	v_lshlrev_b32_e32 v6, 16, v238
	v_mul_f32_e32 v6, 0xbfb8aa3b, v6
	v_exp_f32_e32 v6, v6
	s_nop 0
	v_add_f32_e32 v6, 1.0, v6
	v_rcp_f32_e32 v7, v6
	v_mul_f32_e32 v6, 0x3fb8aa3b, v3
	v_exp_f32_e32 v9, v6
	s_nop 0
	s_waitcnt vmcnt(10)
	v_lshlrev_b32_e32 v6, 16, v239
	v_mul_f32_e32 v6, 0xbfb8aa3b, v6
	v_exp_f32_e32 v6, v6
	s_nop 0
	v_add_f32_e32 v6, 1.0, v6
	v_rcp_f32_e32 v6, v6
	s_nop 0
	v_pk_fma_f32 v[6:7], v[0:1], v[6:7], v[2:3] op_sel_hi:[0,1,0]
	v_cmp_gt_f32_e32 vcc, s35, v7
	s_nop 1
	v_cndmask_b32_e64 v8, 0, 32, vcc
	v_ldexp_f32 v8, v7, v8
	v_log_f32_e32 v8, v8
	s_nop 0
	v_mul_f32_e32 v12, 0x3f317217, v8
	v_fma_f32 v12, v8, s31, -v12
	v_fmac_f32_e32 v12, 0x3377d1cf, v8
	v_fmac_f32_e32 v12, 0x3f317217, v8
	v_cmp_lt_f32_e64 s[4:5], |v8|, s34
	s_nop 1
	v_cndmask_b32_e64 v8, v8, v12, s[4:5]
	v_cndmask_b32_e32 v12, 0, v206, vcc
	v_sub_f32_e32 v8, v8, v12
	v_add_f32_e32 v3, v3, v8
	v_pk_add_f32 v[12:13], v[6:7], 1.0 op_sel_hi:[1,0] neg_lo:[1,0] neg_hi:[1,0]
	v_mul_f32_e32 v7, 0x3fb8aa3b, v3
	v_cmp_gt_f32_e32 vcc, s35, v6
	v_exp_f32_e32 v8, v7
	s_nop 0
	v_cndmask_b32_e64 v7, 0, 32, vcc
	v_ldexp_f32 v6, v6, v7
	v_log_f32_e32 v6, v6
	v_pk_mul_f32 v[8:9], v[12:13], v[8:9]
	v_mul_f32_e32 v7, 0x3f317217, v6
	v_fma_f32 v7, v6, s31, -v7
	v_fmac_f32_e32 v7, 0x3377d1cf, v6
	v_fmac_f32_e32 v7, 0x3f317217, v6
	v_cmp_lt_f32_e64 s[4:5], |v6|, s34
	v_cvt_pk_bf16_f32 v8, v8, v9
	v_cvt_pk_bf16_f32 v9, v10, v11
	v_cndmask_b32_e64 v6, v6, v7, s[4:5]
	v_cndmask_b32_e32 v7, 0, v206, vcc
	s_mul_i32 s4, s51, 0x3600
	v_sub_f32_e32 v6, v6, v7
	s_ashr_i32 s5, s4, 31
	v_add_f32_e32 v3, v3, v6
	v_lshl_add_u64 v[6:7], v[4:5], 0, s[4:5]
	s_nop 0
	s_mul_i32 s4, s50, 0x3600
	s_ashr_i32 s5, s4, 31
	v_lshl_add_u64 v[14:15], v[4:5], 0, s[4:5]
	s_waitcnt vmcnt(9)
	v_lshlrev_b32_e32 v6, 16, v240
	v_mul_f32_e32 v6, 0xbfb8aa3b, v6
	v_exp_f32_e32 v6, v6
	s_nop 0
	v_add_f32_e32 v6, 1.0, v6
	v_rcp_f32_e32 v7, v6
	v_mul_f32_e32 v6, 0x3fb8aa3b, v3
	v_exp_f32_e32 v13, v6
	s_nop 0
	s_waitcnt vmcnt(8)
	v_lshlrev_b32_e32 v6, 16, v241
	v_mul_f32_e32 v6, 0xbfb8aa3b, v6
	v_exp_f32_e32 v6, v6
	s_nop 0
	v_add_f32_e32 v6, 1.0, v6
	v_rcp_f32_e32 v6, v6
	s_nop 0
	v_pk_fma_f32 v[6:7], v[0:1], v[6:7], v[2:3] op_sel_hi:[0,1,0]
	v_cmp_gt_f32_e32 vcc, s35, v7
	s_nop 1
	v_cndmask_b32_e64 v12, 0, 32, vcc
	v_ldexp_f32 v12, v7, v12
	v_log_f32_e32 v12, v12
	s_nop 0
	v_mul_f32_e32 v14, 0x3f317217, v12
	v_fma_f32 v14, v12, s31, -v14
	v_fmac_f32_e32 v14, 0x3377d1cf, v12
	v_fmac_f32_e32 v14, 0x3f317217, v12
	v_cmp_lt_f32_e64 s[4:5], |v12|, s34
	s_nop 1
	v_cndmask_b32_e64 v12, v12, v14, s[4:5]
	v_cndmask_b32_e32 v14, 0, v206, vcc
	v_sub_f32_e32 v12, v12, v14
	v_add_f32_e32 v3, v3, v12
	v_pk_add_f32 v[14:15], v[6:7], 1.0 op_sel_hi:[1,0] neg_lo:[1,0] neg_hi:[1,0]
	v_mul_f32_e32 v7, 0x3fb8aa3b, v3
	v_cmp_gt_f32_e32 vcc, s35, v6
	v_exp_f32_e32 v12, v7
	s_nop 0
	v_cndmask_b32_e64 v7, 0, 32, vcc
	v_ldexp_f32 v6, v6, v7
	v_log_f32_e32 v6, v6
	v_pk_mul_f32 v[12:13], v[14:15], v[12:13]
	v_mul_f32_e32 v7, 0x3f317217, v6
	v_fma_f32 v7, v6, s31, -v7
	v_fmac_f32_e32 v7, 0x3377d1cf, v6
	v_fmac_f32_e32 v7, 0x3f317217, v6
	v_cmp_lt_f32_e64 s[4:5], |v6|, s34
	s_nop 1
	v_cndmask_b32_e64 v6, v6, v7, s[4:5]
	v_cndmask_b32_e32 v7, 0, v206, vcc
	s_mul_i32 s4, s49, 0x3600
	v_sub_f32_e32 v6, v6, v7
	s_ashr_i32 s5, s4, 31
	v_add_f32_e32 v3, v3, v6
	v_lshl_add_u64 v[6:7], v[4:5], 0, s[4:5]
	s_nop 0
	s_mul_i32 s4, s48, 0x3600
	s_ashr_i32 s5, s4, 31
	v_lshl_add_u64 v[16:17], v[4:5], 0, s[4:5]
	s_waitcnt vmcnt(7)
	v_lshlrev_b32_e32 v6, 16, v242
	v_mul_f32_e32 v6, 0xbfb8aa3b, v6
	v_exp_f32_e32 v6, v6
	s_nop 0
	v_add_f32_e32 v6, 1.0, v6
	v_rcp_f32_e32 v7, v6
	v_mul_f32_e32 v6, 0x3fb8aa3b, v3
	v_exp_f32_e32 v15, v6
	s_nop 0
	s_waitcnt vmcnt(6)
; #define LAS __attribute__((address_space(3)))
; __device__ __forceinline__ float bf2f(unsigned v) { return __uint_as_float(v << 16); }
; __device__ __forceinline__ unsigned pk2(float lo, float hi) { const f32x2_t v = {lo, hi}; const bf16x2_t b = __builtin_convertvector(v, bf16x2_t); return __builtin_bit_cast(unsigned, b); }
; __device__ __forceinline__ float sigmoidf_(float x) { return __builtin_amdgcn_rcpf(1.0f + __builtin_amdgcn_exp2f(-1.4426950408889634f * x)); }
; __device__ __forceinline__ void hgrn_h1_item(const Ctx& F, const bf16_t* PB, const float* logits, int l, int item, float* GS, float* HA, LAS unsigned char* scrb) {
;     ...
;         float kh[8];
; #pragma unroll
;         for (int i = 7; i >= 0; --i) {
;             const float pre = bf2f(PB[(size_t)hg_row(dir, c, 8 * cb + i) * INW + colf]);
;             const float f = lb + (1.0f - lb) * sigmoidf_(pre);
;             kh[i] = (1.0f - f) * __expf(r);
;             r += __logf(f);
;         }
;         const u32x4 w = {pk2(kh[0], kh[1]), pk2(kh[2], kh[3]), pk2(kh[4], kh[5]), pk2(kh[6], kh[7])};
;         *(LAS u32x4*)(TKh + lane * TP + 16 * cb) = w;
	v_lshlrev_b32_e32 v6, 16, v243
	v_mul_f32_e32 v6, 0xbfb8aa3b, v6
	v_exp_f32_e32 v6, v6
	s_nop 0
	v_add_f32_e32 v6, 1.0, v6
	v_rcp_f32_e32 v6, v6
	s_nop 0
	v_pk_fma_f32 v[6:7], v[0:1], v[6:7], v[2:3] op_sel_hi:[0,1,0]
	v_cmp_gt_f32_e32 vcc, s35, v7
	s_nop 1
	v_cndmask_b32_e64 v14, 0, 32, vcc
	v_ldexp_f32 v14, v7, v14
	v_log_f32_e32 v14, v14
	s_nop 0
	v_mul_f32_e32 v16, 0x3f317217, v14
	v_fma_f32 v16, v14, s31, -v16
	v_fmac_f32_e32 v16, 0x3377d1cf, v14
	v_fmac_f32_e32 v16, 0x3f317217, v14
	v_cmp_lt_f32_e64 s[4:5], |v14|, s34
	s_nop 1
	v_cndmask_b32_e64 v14, v14, v16, s[4:5]
	v_cndmask_b32_e32 v16, 0, v206, vcc
	v_sub_f32_e32 v14, v14, v16
	v_add_f32_e32 v3, v3, v14
	v_pk_add_f32 v[16:17], v[6:7], 1.0 op_sel_hi:[1,0] neg_lo:[1,0] neg_hi:[1,0]
	v_mul_f32_e32 v7, 0x3fb8aa3b, v3
	v_cmp_gt_f32_e32 vcc, s35, v6
	v_exp_f32_e32 v14, v7
	s_nop 0
	v_cndmask_b32_e64 v7, 0, 32, vcc
	v_ldexp_f32 v6, v6, v7
	v_log_f32_e32 v6, v6
	v_pk_mul_f32 v[14:15], v[16:17], v[14:15]
	v_mul_f32_e32 v7, 0x3f317217, v6
	v_fma_f32 v7, v6, s31, -v7
	v_fmac_f32_e32 v7, 0x3377d1cf, v6
	v_fmac_f32_e32 v7, 0x3f317217, v6
	v_cmp_lt_f32_e64 s[4:5], |v6|, s34
	s_nop 1
	v_cndmask_b32_e64 v6, v6, v7, s[4:5]
	v_cndmask_b32_e32 v7, 0, v206, vcc
	v_sub_f32_e32 v6, v6, v7
	s_mul_i32 s4, s45, 0x3600
	v_add_f32_e32 v3, v3, v6
	v_cvt_pk_bf16_f32 v6, v14, v15
	v_cvt_pk_bf16_f32 v7, v12, v13
	s_ashr_i32 s5, s4, 31
	ds_write_b128 v99, v[6:9] offset:16
	v_lshl_add_u64 v[6:7], v[4:5], 0, s[4:5]
	s_nop 0
	s_mul_i32 s4, s44, 0x3600
	s_ashr_i32 s5, s4, 31
	v_lshl_add_u64 v[10:11], v[4:5], 0, s[4:5]
	s_waitcnt vmcnt(5)
	v_lshlrev_b32_e32 v6, 16, v244
	v_mul_f32_e32 v6, 0xbfb8aa3b, v6
	v_exp_f32_e32 v6, v6
	s_nop 0
	v_add_f32_e32 v6, 1.0, v6
	v_rcp_f32_e32 v7, v6
	v_mul_f32_e32 v6, 0x3fb8aa3b, v3
	v_exp_f32_e32 v9, v6
	s_nop 0
	s_waitcnt vmcnt(4)
	v_lshlrev_b32_e32 v6, 16, v245
	v_mul_f32_e32 v6, 0xbfb8aa3b, v6
	v_exp_f32_e32 v6, v6
	s_nop 0
	v_add_f32_e32 v6, 1.0, v6
	v_rcp_f32_e32 v6, v6
	s_nop 0
	v_pk_fma_f32 v[6:7], v[0:1], v[6:7], v[2:3] op_sel_hi:[0,1,0]
	v_cmp_gt_f32_e32 vcc, s35, v7
	s_nop 1
	v_cndmask_b32_e64 v8, 0, 32, vcc
	v_ldexp_f32 v8, v7, v8
	v_log_f32_e32 v8, v8
	s_nop 0
	v_mul_f32_e32 v10, 0x3f317217, v8
	v_fma_f32 v10, v8, s31, -v10
	v_fmac_f32_e32 v10, 0x3377d1cf, v8
	v_fmac_f32_e32 v10, 0x3f317217, v8
	v_cmp_lt_f32_e64 s[4:5], |v8|, s34
	s_nop 1
	v_cndmask_b32_e64 v8, v8, v10, s[4:5]
	v_cndmask_b32_e32 v10, 0, v206, vcc
	v_sub_f32_e32 v8, v8, v10
	v_add_f32_e32 v3, v3, v8
	v_pk_add_f32 v[10:11], v[6:7], 1.0 op_sel_hi:[1,0] neg_lo:[1,0] neg_hi:[1,0]
	v_mul_f32_e32 v7, 0x3fb8aa3b, v3
	v_cmp_gt_f32_e32 vcc, s35, v6
	v_exp_f32_e32 v8, v7
	s_nop 0
	v_cndmask_b32_e64 v7, 0, 32, vcc
	v_ldexp_f32 v6, v6, v7
	v_log_f32_e32 v6, v6
	v_pk_mul_f32 v[8:9], v[10:11], v[8:9]
	v_mul_f32_e32 v7, 0x3f317217, v6
	v_fma_f32 v7, v6, s31, -v7
	v_fmac_f32_e32 v7, 0x3377d1cf, v6
	v_fmac_f32_e32 v7, 0x3f317217, v6
	v_cmp_lt_f32_e64 s[4:5], |v6|, s34
	s_nop 1
	v_cndmask_b32_e64 v6, v6, v7, s[4:5]
	v_cndmask_b32_e32 v7, 0, v206, vcc
	s_mul_i32 s4, s37, 0x3600
	v_sub_f32_e32 v6, v6, v7
	s_ashr_i32 s5, s4, 31
	v_add_f32_e32 v3, v3, v6
	v_lshl_add_u64 v[6:7], v[4:5], 0, s[4:5]
	s_nop 0
	s_mul_i32 s4, s36, 0x3600
	s_ashr_i32 s5, s4, 31
	v_lshl_add_u64 v[12:13], v[4:5], 0, s[4:5]
	s_waitcnt vmcnt(3)
	v_lshlrev_b32_e32 v6, 16, v246
	v_mul_f32_e32 v6, 0xbfb8aa3b, v6
	v_exp_f32_e32 v6, v6
	s_nop 0
	v_add_f32_e32 v6, 1.0, v6
	v_rcp_f32_e32 v7, v6
	v_mul_f32_e32 v6, 0x3fb8aa3b, v3
	v_exp_f32_e32 v11, v6
	s_nop 0
	s_waitcnt vmcnt(2)
	v_lshlrev_b32_e32 v6, 16, v247
	v_mul_f32_e32 v6, 0xbfb8aa3b, v6
	v_exp_f32_e32 v6, v6
	s_nop 0
	v_add_f32_e32 v6, 1.0, v6
	v_rcp_f32_e32 v6, v6
	s_nop 0
	v_pk_fma_f32 v[6:7], v[0:1], v[6:7], v[2:3] op_sel_hi:[0,1,0]
	v_cmp_gt_f32_e32 vcc, s35, v7
	s_nop 1
	v_cndmask_b32_e64 v10, 0, 32, vcc
	v_ldexp_f32 v10, v7, v10
	v_log_f32_e32 v10, v10
	s_nop 0
	v_mul_f32_e32 v12, 0x3f317217, v10
	v_fma_f32 v12, v10, s31, -v12
	v_fmac_f32_e32 v12, 0x3377d1cf, v10
	v_fmac_f32_e32 v12, 0x3f317217, v10
	v_cmp_lt_f32_e64 s[4:5], |v10|, s34
	s_nop 1
	v_cndmask_b32_e64 v10, v10, v12, s[4:5]
	v_cndmask_b32_e32 v12, 0, v206, vcc
	v_sub_f32_e32 v10, v10, v12
	v_add_f32_e32 v3, v3, v10
	v_pk_add_f32 v[12:13], v[6:7], 1.0 op_sel_hi:[1,0] neg_lo:[1,0] neg_hi:[1,0]
	v_mul_f32_e32 v7, 0x3fb8aa3b, v3
	v_cmp_gt_f32_e32 vcc, s35, v6
	v_exp_f32_e32 v10, v7
	s_nop 0
	v_cndmask_b32_e64 v7, 0, 32, vcc
	v_ldexp_f32 v6, v6, v7
	v_log_f32_e32 v6, v6
	v_pk_mul_f32 v[10:11], v[12:13], v[10:11]
	v_mul_f32_e32 v7, 0x3f317217, v6
	v_fma_f32 v7, v6, s31, -v7
	v_fmac_f32_e32 v7, 0x3377d1cf, v6
	v_fmac_f32_e32 v7, 0x3f317217, v6
	v_cmp_lt_f32_e64 s[4:5], |v6|, s34
	s_nop 1
	v_cndmask_b32_e64 v6, v6, v7, s[4:5]
	v_cndmask_b32_e32 v7, 0, v206, vcc
	s_mul_i32 s4, s33, 0x3600
	v_sub_f32_e32 v6, v6, v7
	s_ashr_i32 s5, s4, 31
	v_add_f32_e32 v3, v3, v6
	v_lshl_add_u64 v[6:7], v[4:5], 0, s[4:5]
	s_nop 0
	s_mul_i32 s4, s27, 0x3600
	s_ashr_i32 s5, s4, 31
	v_lshl_add_u64 v[14:15], v[4:5], 0, s[4:5]
	s_waitcnt vmcnt(1)
	v_lshlrev_b32_e32 v6, 16, v218
	v_mul_f32_e32 v6, 0xbfb8aa3b, v6
	v_exp_f32_e32 v6, v6
	s_nop 0
	v_add_f32_e32 v6, 1.0, v6
	v_rcp_f32_e32 v7, v6
	v_mul_f32_e32 v6, 0x3fb8aa3b, v3
	v_exp_f32_e32 v13, v6
	s_nop 0
	s_waitcnt vmcnt(0)
; #define LAS __attribute__((address_space(3)))
; __device__ __forceinline__ unsigned pk2(float lo, float hi) { const f32x2_t v = {lo, hi}; const bf16x2_t b = __builtin_convertvector(v, bf16x2_t); return __builtin_bit_cast(unsigned, b); }
; __device__ __forceinline__ float sigmoidf_(float x) { return __builtin_amdgcn_rcpf(1.0f + __builtin_amdgcn_exp2f(-1.4426950408889634f * x)); }
; __device__ __forceinline__ void hgrn_h1_item(const Ctx& F, const bf16_t* PB, const float* logits, int l, int item, float* GS, float* HA, LAS unsigned char* scrb) {
;     ...
;             const float f = lb + (1.0f - lb) * sigmoidf_(pre);
;             kh[i] = (1.0f - f) * __expf(r);
;             r += __logf(f);
;         }
;         const u32x4 w = {pk2(kh[0], kh[1]), pk2(kh[2], kh[3]), pk2(kh[4], kh[5]), pk2(kh[6], kh[7])};
;         *(LAS u32x4*)(TKh + lane * TP + 16 * cb) = w;
;     }
;     HA[(size_t)((dir * NCHUNK + c) * 4 + head) * 64 + lane] = __expf(r);
;     ...
;     const bf16_t* vbase = PB + C_BI + head * 64 + q_;
; #pragma unroll
;     for (int k = 0; k < 4; ++k) {
;         const bf16x8 ka0 = *(const LAS bf16x8*)(TKh + q_ * TP + (16 * k + 8 * h) * 2), ka1 = *(const LAS bf16x8*)(TKh + (32 + q_) * TP + (16 * k + 8 * h) * 2);
; #pragma unroll
;         for (int vb = 0; vb < 2; ++vb) {
;             unsigned e[8];
; #pragma unroll
;             for (int j = 0; j < 8; ++j) e[j] = vbase[(size_t)hg_row(dir, c, 16 * k + 8 * h + j) * INW + 32 * vb];
	v_lshlrev_b32_e32 v6, 16, v219
	v_mul_f32_e32 v6, 0xbfb8aa3b, v6
	v_exp_f32_e32 v6, v6
	s_nop 0
	v_add_f32_e32 v6, 1.0, v6
	v_rcp_f32_e32 v6, v6
	s_nop 0
	v_pk_fma_f32 v[6:7], v[0:1], v[6:7], v[2:3] op_sel_hi:[0,1,0]
	v_cmp_gt_f32_e32 vcc, s35, v7
	s_nop 1
	v_cndmask_b32_e64 v12, 0, 32, vcc
	v_ldexp_f32 v12, v7, v12
	v_log_f32_e32 v12, v12
	s_nop 0
	v_mul_f32_e32 v14, 0x3f317217, v12
	v_fma_f32 v14, v12, s31, -v14
	v_fmac_f32_e32 v14, 0x3377d1cf, v12
	v_fmac_f32_e32 v14, 0x3f317217, v12
	v_cmp_lt_f32_e64 s[4:5], |v12|, s34
	s_nop 1
	v_cndmask_b32_e64 v12, v12, v14, s[4:5]
	v_cndmask_b32_e32 v14, 0, v206, vcc
	v_sub_f32_e32 v12, v12, v14
	v_add_f32_e32 v3, v3, v12
	v_pk_add_f32 v[14:15], v[6:7], 1.0 op_sel_hi:[1,0] neg_lo:[1,0] neg_hi:[1,0]
	v_mul_f32_e32 v7, 0x3fb8aa3b, v3
	v_cmp_gt_f32_e32 vcc, s35, v6
	v_exp_f32_e32 v12, v7
	s_nop 0
	v_cndmask_b32_e64 v7, 0, 32, vcc
	v_ldexp_f32 v6, v6, v7
	v_log_f32_e32 v6, v6
	v_pk_mul_f32 v[12:13], v[14:15], v[12:13]
	v_mul_f32_e32 v7, 0x3f317217, v6
	v_fma_f32 v7, v6, s31, -v7
	v_fmac_f32_e32 v7, 0x3377d1cf, v6
	v_fmac_f32_e32 v7, 0x3f317217, v6
	v_cmp_lt_f32_e64 s[4:5], |v6|, s34
	s_nop 1
	v_cndmask_b32_e64 v6, v6, v7, s[4:5]
	v_cndmask_b32_e32 v7, 0, v206, vcc
	s_mul_i32 s4, s26, 0x3600
	v_sub_f32_e32 v6, v6, v7
	s_ashr_i32 s5, s4, 31
	v_add_f32_e32 v14, v3, v6
	v_lshl_add_u64 v[6:7], v[4:5], 0, s[4:5]
	s_mul_i32 s4, s29, 0x3600
	s_ashr_i32 s5, s4, 31
	global_load_ushort v3, v[6:7], off
	v_lshl_add_u64 v[4:5], v[4:5], 0, s[4:5]
	global_load_ushort v4, v[4:5], off
	s_waitcnt vmcnt(1)
	v_lshlrev_b32_e32 v3, 16, v3
	v_mul_f32_e32 v3, 0xbfb8aa3b, v3
	s_waitcnt vmcnt(0)
	v_lshlrev_b32_e32 v4, 16, v4
	v_exp_f32_e32 v3, v3
	v_mul_f32_e32 v4, 0xbfb8aa3b, v4
	v_exp_f32_e32 v4, v4
	v_add_f32_e32 v3, 1.0, v3
	v_rcp_f32_e32 v7, v3
	v_mul_f32_e32 v3, 0x3fb8aa3b, v14
	v_add_f32_e32 v4, 1.0, v4
	v_exp_f32_e32 v3, v3
	v_rcp_f32_e32 v6, v4
	s_nop 0
	v_pk_fma_f32 v[4:5], v[0:1], v[6:7], v[2:3] op_sel_hi:[0,1,0]
	v_cmp_gt_f32_e32 vcc, s35, v5
	v_pk_add_f32 v[6:7], v[4:5], 1.0 op_sel_hi:[1,0] neg_lo:[1,0] neg_hi:[1,0]
	s_nop 0
	v_cndmask_b32_e64 v0, 0, 32, vcc
	v_ldexp_f32 v0, v5, v0
	v_log_f32_e32 v0, v0
	s_nop 0
	v_mul_f32_e32 v2, 0x3f317217, v0
	v_fma_f32 v2, v0, s31, -v2
	v_fmac_f32_e32 v2, 0x3377d1cf, v0
	v_fmac_f32_e32 v2, 0x3f317217, v0
	v_cmp_lt_f32_e64 s[4:5], |v0|, s34
	s_nop 1
	v_cndmask_b32_e64 v0, v0, v2, s[4:5]
	v_cndmask_b32_e32 v2, 0, v206, vcc
	v_cmp_gt_f32_e32 vcc, s35, v4
	v_sub_f32_e32 v0, v0, v2
	v_add_f32_e32 v0, v14, v0
	v_cndmask_b32_e64 v5, 0, 32, vcc
	v_ldexp_f32 v4, v4, v5
	v_log_f32_e32 v4, v4
	v_mul_f32_e32 v2, 0x3fb8aa3b, v0
	v_exp_f32_e32 v2, v2
	v_mul_f32_e32 v5, 0x3f317217, v4
	v_fma_f32 v5, v4, s31, -v5
	v_fmac_f32_e32 v5, 0x3377d1cf, v4
	v_fmac_f32_e32 v5, 0x3f317217, v4
	v_cmp_lt_f32_e64 s[4:5], |v4|, s34
	v_pk_mul_f32 v[2:3], v[6:7], v[2:3]
	s_nop 0
	v_cndmask_b32_e64 v4, v4, v5, s[4:5]
	v_cndmask_b32_e32 v5, 0, v206, vcc
	v_sub_f32_e32 v4, v4, v5
	v_add_f32_e32 v0, v0, v4
	v_mul_f32_e32 v0, 0x3fb8aa3b, v0
	v_exp_f32_e32 v0, v0
	s_or_b32 s4, s2, s1
	s_ashr_i32 s5, s4, 31
	v_cvt_pk_bf16_f32 v2, v2, v3
	v_cvt_pk_bf16_f32 v3, v12, v13
	v_cvt_pk_bf16_f32 v4, v10, v11
	v_cvt_pk_bf16_f32 v5, v8, v9
	s_lshl_b64 s[22:23], s[4:5], 8
	ds_write_b128 v99, v[2:5]
	v_lshl_add_u64 v[2:3], v[74:75], 0, s[22:23]
	v_cmp_gt_i32_e32 vcc, s6, v92
	global_store_dword v[2:3], v0, off
	v_sub_u32_e32 v10, 0x40ff, v92
	v_cndmask_b32_e32 v0, v209, v210, vcc
	v_add_u32_e32 v0, v0, v92
	v_cndmask_b32_e64 v0, v10, v0, s[46:47]
	v_mul_i32_i24_e32 v10, 0x3600, v0
	v_ashrrev_i32_e32 v11, 31, v10
	v_lshl_add_u64 v[14:15], v[76:77], 0, v[10:11]
	v_or_b32_e32 v10, 1, v92
	v_cmp_gt_i32_e32 vcc, s6, v10
	s_waitcnt lgkmcnt(0)
	ds_read_b128 v[2:5], v100
	ds_read_b128 v[6:9], v100 offset:4608
	v_cndmask_b32_e32 v11, v209, v210, vcc
	v_add_u32_e32 v11, v11, v10
	v_sub_u32_e32 v10, 0x40ff, v10
	v_cndmask_b32_e64 v10, v10, v11, s[46:47]
	v_or_b32_e32 v11, 2, v92
	v_cmp_gt_i32_e32 vcc, s6, v11
	v_mad_i64_i32 v[16:17], s[22:23], v10, s21, v[76:77]
	s_nop 0
	v_cndmask_b32_e32 v12, v209, v210, vcc
	v_add_u32_e32 v12, v12, v11
	v_sub_u32_e32 v11, 0x40ff, v11
	v_cndmask_b32_e64 v11, v11, v12, s[46:47]
	v_or_b32_e32 v12, 3, v92
	v_cmp_gt_i32_e32 vcc, s6, v12
	v_mad_i64_i32 v[34:35], s[22:23], v11, s21, v[76:77]
	s_nop 0
	v_cndmask_b32_e32 v13, v209, v210, vcc
	v_add_u32_e32 v13, v13, v12
	v_sub_u32_e32 v12, 0x40ff, v12
	v_cndmask_b32_e64 v12, v12, v13, s[46:47]
	v_or_b32_e32 v13, 4, v92
	v_cmp_gt_i32_e32 vcc, s6, v13
	v_mad_i64_i32 v[36:37], s[22:23], v12, s21, v[76:77]
	s_nop 0
	v_cndmask_b32_e32 v18, v209, v210, vcc
	v_add_u32_e32 v18, v18, v13
	v_sub_u32_e32 v13, 0x40ff, v13
	v_cndmask_b32_e64 v13, v13, v18, s[46:47]
	v_or_b32_e32 v18, 5, v92
	v_cmp_gt_i32_e32 vcc, s6, v18
	v_mad_i64_i32 v[38:39], s[22:23], v13, s21, v[76:77]
	s_nop 0
	v_cndmask_b32_e32 v19, v209, v210, vcc
	v_add_u32_e32 v19, v19, v18
	v_sub_u32_e32 v18, 0x40ff, v18
	v_cndmask_b32_e64 v18, v18, v19, s[46:47]
	v_or_b32_e32 v19, 6, v92
	v_cmp_gt_i32_e32 vcc, s6, v19
	v_mad_i64_i32 v[40:41], s[22:23], v18, s21, v[76:77]
	s_nop 0
	v_cndmask_b32_e32 v20, v209, v210, vcc
	v_add_u32_e32 v20, v20, v19
	v_sub_u32_e32 v19, 0x40ff, v19
	v_cndmask_b32_e64 v19, v19, v20, s[46:47]
	v_or_b32_e32 v20, 7, v92
	v_cmp_gt_i32_e32 vcc, s6, v20
	v_mad_i64_i32 v[42:43], s[22:23], v19, s21, v[76:77]
	s_nop 0
	v_cndmask_b32_e32 v21, v209, v210, vcc
	v_add_u32_e32 v21, v21, v20
	v_sub_u32_e32 v20, 0x40ff, v20
	v_cndmask_b32_e64 v20, v20, v21, s[46:47]
	v_mad_i64_i32 v[44:45], s[22:23], v20, s21, v[76:77]
	global_load_ushort v0, v[14:15], off
	global_load_ushort v10, v[16:17], off
	global_load_ushort v11, v[34:35], off
	global_load_ushort v12, v[36:37], off
	global_load_ushort v13, v[38:39], off
	global_load_ushort v18, v[40:41], off
	global_load_ushort v19, v[42:43], off
	global_load_ushort v20, v[44:45], off
	s_lshl_b64 s[4:5], s[4:5], 14
	s_add_u32 s4, s84, s4
	s_addc_u32 s5, s85, s5
	s_add_i32 s42, s42, s8
	s_cmpk_lt_i32 s42, 0x820
	s_waitcnt vmcnt(6)
; #define LAS __attribute__((address_space(3)))
; __device__ __forceinline__ void hgrn_h1_item(const Ctx& F, const bf16_t* PB, const float* logits, int l, int item, float* GS, float* HA, LAS unsigned char* scrb) {
;     ...
;     for (int k = 0; k < 4; ++k) {
;         const bf16x8 ka0 = *(const LAS bf16x8*)(TKh + q_ * TP + (16 * k + 8 * h) * 2), ka1 = *(const LAS bf16x8*)(TKh + (32 + q_) * TP + (16 * k + 8 * h) * 2);
; #pragma unroll
;         for (int vb = 0; vb < 2; ++vb) {
;             unsigned e[8];
; #pragma unroll
;             for (int j = 0; j < 8; ++j) e[j] = vbase[(size_t)hg_row(dir, c, 16 * k + 8 * h + j) * INW + 32 * vb];
;             const u32x4 w = {e[0] | (e[1] << 16), e[2] | (e[3] << 16), e[4] | (e[5] << 16), e[6] | (e[7] << 16)};
;             const bf16x8 vf = __builtin_bit_cast(bf16x8, w);
;             g[0][vb] = __builtin_amdgcn_mfma_f32_32x32x16_bf16(ka0, vf, g[0][vb], 0, 0, 0);
;             g[1][vb] = __builtin_amdgcn_mfma_f32_32x32x16_bf16(ka1, vf, g[1][vb], 0, 0, 0);
;         }
	v_lshl_or_b32 v10, v10, 16, v0
	s_waitcnt vmcnt(4)
	v_lshl_or_b32 v11, v12, 16, v11
	s_waitcnt vmcnt(2)
	v_lshl_or_b32 v12, v18, 16, v13
	s_waitcnt vmcnt(0)
	v_lshl_or_b32 v13, v20, 16, v19
	s_waitcnt lgkmcnt(1)
	s_nop 0
	v_mfma_f32_32x32x16_bf16 v[50:65], v[2:5], v[10:13], 0
	s_waitcnt lgkmcnt(0)
	v_mfma_f32_32x32x16_bf16 v[18:33], v[6:9], v[10:13], 0
	global_load_ushort v0, v[14:15], off offset:64
	global_load_ushort v10, v[16:17], off offset:64
	global_load_ushort v11, v[34:35], off offset:64
	global_load_ushort v12, v[36:37], off offset:64
	global_load_ushort v13, v[38:39], off offset:64
	s_nop 0
	global_load_ushort v14, v[40:41], off offset:64
	global_load_ushort v15, v[42:43], off offset:64
	global_load_ushort v16, v[44:45], off offset:64
	ds_read_b128 v[66:69], v101
	ds_read_b128 v[70:73], v101 offset:4608
	s_waitcnt vmcnt(6)
	v_lshl_or_b32 v10, v10, 16, v0
	v_or_b32_e32 v0, s38, v95
	v_cmp_gt_i32_e32 vcc, s6, v0
	s_waitcnt vmcnt(4)
	v_lshl_or_b32 v11, v12, 16, v11
	s_waitcnt vmcnt(2)
	v_lshl_or_b32 v12, v14, 16, v13
	v_cndmask_b32_e32 v78, v209, v210, vcc
	v_add_u32_e32 v78, v78, v0
	v_sub_u32_e32 v0, 0x40ff, v0
	v_cndmask_b32_e64 v0, v0, v78, s[46:47]
	v_or_b32_e32 v78, 17, v92
	v_cmp_gt_i32_e32 vcc, s6, v78
	v_mad_i64_i32 v[82:83], s[22:23], v0, s21, v[76:77]
	s_nop 0
	v_cndmask_b32_e32 v79, v209, v210, vcc
	v_add_u32_e32 v79, v79, v78
	v_sub_u32_e32 v78, 0x40ff, v78
	v_cndmask_b32_e64 v78, v78, v79, s[46:47]
	v_or_b32_e32 v79, 18, v92
	v_cmp_gt_i32_e32 vcc, s6, v79
	v_mad_i64_i32 v[84:85], s[22:23], v78, s21, v[76:77]
	s_nop 0
	v_cndmask_b32_e32 v80, v209, v210, vcc
	v_add_u32_e32 v80, v80, v79
	v_sub_u32_e32 v79, 0x40ff, v79
	v_cndmask_b32_e64 v79, v79, v80, s[46:47]
	v_or_b32_e32 v80, 19, v92
	v_cmp_gt_i32_e32 vcc, s6, v80
	v_mad_i64_i32 v[86:87], s[22:23], v79, s21, v[76:77]
	s_nop 0
	v_cndmask_b32_e32 v81, v209, v210, vcc
	v_add_u32_e32 v81, v81, v80
	v_sub_u32_e32 v80, 0x40ff, v80
	v_cndmask_b32_e64 v80, v80, v81, s[46:47]
	v_or_b32_e32 v81, 20, v92
	v_cmp_gt_i32_e32 vcc, s6, v81
	v_mad_i64_i32 v[88:89], s[22:23], v80, s21, v[76:77]
	s_nop 0
	v_cndmask_b32_e32 v90, v209, v210, vcc
	v_cmp_gt_i32_e32 vcc, s6, v93
	v_add_u32_e32 v90, v90, v81
	v_sub_u32_e32 v81, 0x40ff, v81
	v_cndmask_b32_e32 v154, v209, v210, vcc
	v_cmp_gt_i32_e32 vcc, s6, v167
	v_add_u32_e32 v154, v154, v93
	v_sub_u32_e32 v93, 0x40ff, v93
	v_cndmask_b32_e32 v168, v209, v210, vcc
	v_cmp_gt_i32_e32 vcc, s6, v170
	v_add_u32_e32 v168, v168, v167
	v_sub_u32_e32 v167, 0x40ff, v167
	v_cndmask_b32_e32 v171, v209, v210, vcc
	v_add_u32_e32 v171, v171, v170
	v_sub_u32_e32 v170, 0x40ff, v170
	v_cndmask_b32_e64 v81, v81, v90, s[46:47]
	v_cndmask_b32_e64 v93, v93, v154, s[46:47]
	v_cndmask_b32_e64 v167, v167, v168, s[46:47]
	v_cndmask_b32_e64 v170, v170, v171, s[46:47]
	v_mad_i64_i32 v[90:91], s[22:23], v81, s21, v[76:77]
	v_mad_i64_i32 v[154:155], s[22:23], v93, s21, v[76:77]
	v_mad_i64_i32 v[168:169], s[22:23], v167, s21, v[76:77]
	v_mad_i64_i32 v[170:171], s[22:23], v170, s21, v[76:77]
	global_load_ushort v0, v[82:83], off
	global_load_ushort v78, v[84:85], off
	global_load_ushort v79, v[86:87], off
	global_load_ushort v80, v[88:89], off
	global_load_ushort v81, v[90:91], off
	global_load_ushort v93, v[154:155], off
	global_load_ushort v167, v[168:169], off
	global_load_ushort v172, v[170:171], off
	s_waitcnt vmcnt(8)
	v_lshl_or_b32 v13, v16, 16, v15
	s_waitcnt vmcnt(6)
	v_lshl_or_b32 v78, v78, 16, v0
	v_mfma_f32_32x32x16_bf16 v[34:49], v[2:5], v[10:13], 0
	s_waitcnt vmcnt(4)
	v_lshl_or_b32 v79, v80, 16, v79
	s_waitcnt vmcnt(2)
	v_lshl_or_b32 v80, v93, 16, v81
	v_or_b32_e32 v93, 37, v92
	s_waitcnt vmcnt(0)
	v_lshl_or_b32 v81, v172, 16, v167
	v_or_b32_e32 v167, 38, v92
	s_waitcnt lgkmcnt(1)
	v_mfma_f32_32x32x16_bf16 v[50:65], v[66:69], v[78:81], v[50:65]
	s_waitcnt lgkmcnt(0)
	v_mfma_f32_32x32x16_bf16 v[18:33], v[70:73], v[78:81], v[18:33]
	global_load_ushort v0, v[82:83], off offset:64
	global_load_ushort v78, v[84:85], off offset:64
	global_load_ushort v79, v[86:87], off offset:64
	global_load_ushort v80, v[88:89], off offset:64
	global_load_ushort v81, v[90:91], off offset:64
	s_nop 0
	global_load_ushort v82, v[154:155], off offset:64
	global_load_ushort v83, v[168:169], off offset:64
	global_load_ushort v84, v[170:171], off offset:64
	v_or_b32_e32 v170, 39, v92
	s_waitcnt vmcnt(6)
	v_lshl_or_b32 v78, v78, 16, v0
	v_mfma_f32_32x32x16_bf16 v[2:17], v[6:9], v[10:13], 0
	v_or_b32_e32 v0, s38, v96
	s_waitcnt vmcnt(4)
	v_lshl_or_b32 v79, v80, 16, v79
	s_waitcnt vmcnt(2)
	v_lshl_or_b32 v80, v82, 16, v81
	v_cmp_gt_i32_e32 vcc, s6, v0
	s_waitcnt vmcnt(0)
; #define LAS __attribute__((address_space(3)))
; __device__ __forceinline__ void hgrn_h1_item(const Ctx& F, const bf16_t* PB, const float* logits, int l, int item, float* GS, float* HA, LAS unsigned char* scrb) {
;     ...
;     for (int k = 0; k < 4; ++k) {
;         const bf16x8 ka0 = *(const LAS bf16x8*)(TKh + q_ * TP + (16 * k + 8 * h) * 2), ka1 = *(const LAS bf16x8*)(TKh + (32 + q_) * TP + (16 * k + 8 * h) * 2);
; #pragma unroll
;         for (int vb = 0; vb < 2; ++vb) {
;             unsigned e[8];
; #pragma unroll
;             for (int j = 0; j < 8; ++j) e[j] = vbase[(size_t)hg_row(dir, c, 16 * k + 8 * h + j) * INW + 32 * vb];
;             const u32x4 w = {e[0] | (e[1] << 16), e[2] | (e[3] << 16), e[4] | (e[5] << 16), e[6] | (e[7] << 16)};
;             const bf16x8 vf = __builtin_bit_cast(bf16x8, w);
;             g[0][vb] = __builtin_amdgcn_mfma_f32_32x32x16_bf16(ka0, vf, g[0][vb], 0, 0, 0);
;             g[1][vb] = __builtin_amdgcn_mfma_f32_32x32x16_bf16(ka1, vf, g[1][vb], 0, 0, 0);
;         }
	v_lshl_or_b32 v81, v84, 16, v83
	s_nop 1
	v_mfma_f32_32x32x16_bf16 v[34:49], v[66:69], v[78:81], v[34:49]
	v_mfma_f32_32x32x16_bf16 v[2:17], v[70:73], v[78:81], v[2:17]
	v_cndmask_b32_e32 v78, v209, v210, vcc
	v_add_u32_e32 v78, v78, v0
	v_sub_u32_e32 v0, 0x40ff, v0
	v_cndmask_b32_e64 v0, v0, v78, s[46:47]
	v_or_b32_e32 v78, 33, v92
	v_cmp_gt_i32_e32 vcc, s6, v78
	v_mad_i64_i32 v[82:83], s[22:23], v0, s21, v[76:77]
	s_nop 0
	v_cndmask_b32_e32 v79, v209, v210, vcc
	v_add_u32_e32 v79, v79, v78
	v_sub_u32_e32 v78, 0x40ff, v78
	v_cndmask_b32_e64 v78, v78, v79, s[46:47]
	v_or_b32_e32 v79, 34, v92
	v_cmp_gt_i32_e32 vcc, s6, v79
	v_mad_i64_i32 v[84:85], s[22:23], v78, s21, v[76:77]
	s_nop 0
	v_cndmask_b32_e32 v80, v209, v210, vcc
	v_add_u32_e32 v80, v80, v79
	v_sub_u32_e32 v79, 0x40ff, v79
	v_cndmask_b32_e64 v79, v79, v80, s[46:47]
	v_or_b32_e32 v80, 35, v92
	v_cmp_gt_i32_e32 vcc, s6, v80
	v_mad_i64_i32 v[86:87], s[22:23], v79, s21, v[76:77]
	s_nop 0
	v_cndmask_b32_e32 v81, v209, v210, vcc
	v_add_u32_e32 v81, v81, v80
	v_sub_u32_e32 v80, 0x40ff, v80
	v_cndmask_b32_e64 v80, v80, v81, s[46:47]
	v_or_b32_e32 v81, 36, v92
	v_cmp_gt_i32_e32 vcc, s6, v81
	v_mad_i64_i32 v[88:89], s[22:23], v80, s21, v[76:77]
	s_nop 0
	v_cndmask_b32_e32 v90, v209, v210, vcc
	v_cmp_gt_i32_e32 vcc, s6, v93
	v_add_u32_e32 v90, v90, v81
	v_sub_u32_e32 v81, 0x40ff, v81
	v_cndmask_b32_e32 v154, v209, v210, vcc
	v_cmp_gt_i32_e32 vcc, s6, v167
	v_add_u32_e32 v154, v154, v93
	v_sub_u32_e32 v93, 0x40ff, v93
	v_cndmask_b32_e32 v168, v209, v210, vcc
	v_cmp_gt_i32_e32 vcc, s6, v170
	v_add_u32_e32 v168, v168, v167
	v_sub_u32_e32 v167, 0x40ff, v167
	v_cndmask_b32_e32 v171, v209, v210, vcc
	v_add_u32_e32 v171, v171, v170
	v_sub_u32_e32 v170, 0x40ff, v170
	v_cndmask_b32_e64 v81, v81, v90, s[46:47]
	v_cndmask_b32_e64 v93, v93, v154, s[46:47]
	v_cndmask_b32_e64 v167, v167, v168, s[46:47]
	v_cndmask_b32_e64 v170, v170, v171, s[46:47]
	v_mad_i64_i32 v[90:91], s[22:23], v81, s21, v[76:77]
	v_mad_i64_i32 v[154:155], s[22:23], v93, s21, v[76:77]
	v_mad_i64_i32 v[168:169], s[22:23], v167, s21, v[76:77]
	v_mad_i64_i32 v[170:171], s[22:23], v170, s21, v[76:77]
	ds_read_b128 v[66:69], v102
	ds_read_b128 v[70:73], v102 offset:4608
	global_load_ushort v0, v[82:83], off
	global_load_ushort v78, v[84:85], off
	global_load_ushort v79, v[86:87], off
	global_load_ushort v80, v[88:89], off
	global_load_ushort v81, v[90:91], off
	global_load_ushort v93, v[154:155], off
	global_load_ushort v167, v[168:169], off
	global_load_ushort v172, v[170:171], off
	s_waitcnt vmcnt(6)
	v_lshl_or_b32 v78, v78, 16, v0
	s_waitcnt vmcnt(4)
	v_lshl_or_b32 v79, v80, 16, v79
	s_waitcnt vmcnt(2)
	v_lshl_or_b32 v80, v93, 16, v81
	v_or_b32_e32 v93, 55, v92
	s_waitcnt vmcnt(0)
	v_lshl_or_b32 v81, v172, 16, v167
	s_waitcnt lgkmcnt(1)
	s_nop 0
	v_mfma_f32_32x32x16_bf16 v[50:65], v[66:69], v[78:81], v[50:65]
	s_waitcnt lgkmcnt(0)
	v_mfma_f32_32x32x16_bf16 v[18:33], v[70:73], v[78:81], v[18:33]
	global_load_ushort v0, v[82:83], off offset:64
	global_load_ushort v78, v[84:85], off offset:64
	global_load_ushort v79, v[86:87], off offset:64
	global_load_ushort v80, v[88:89], off offset:64
	global_load_ushort v81, v[90:91], off offset:64
	s_nop 0
	global_load_ushort v82, v[154:155], off offset:64
	global_load_ushort v83, v[168:169], off offset:64
	global_load_ushort v84, v[170:171], off offset:64
	v_or_b32_e32 v86, 52, v92
	v_or_b32_e32 v88, 53, v92
	v_or_b32_e32 v90, 54, v92
	s_waitcnt vmcnt(6)
	v_lshl_or_b32 v78, v78, 16, v0
	v_or_b32_e32 v0, s38, v97
	s_waitcnt vmcnt(4)
	v_lshl_or_b32 v79, v80, 16, v79
	v_cmp_gt_i32_e32 vcc, s6, v0
	s_waitcnt vmcnt(2)
	v_lshl_or_b32 v80, v82, 16, v81
	v_or_b32_e32 v82, 50, v92
	s_waitcnt vmcnt(0)
	v_lshl_or_b32 v81, v84, 16, v83
	s_nop 1
	v_mfma_f32_32x32x16_bf16 v[34:49], v[66:69], v[78:81], v[34:49]
	v_mfma_f32_32x32x16_bf16 v[2:17], v[70:73], v[78:81], v[2:17]
	v_or_b32_e32 v80, 49, v92
	v_cndmask_b32_e32 v78, v209, v210, vcc
	v_cmp_gt_i32_e32 vcc, s6, v80
	v_add_u32_e32 v78, v78, v0
	v_sub_u32_e32 v0, 0x40ff, v0
	v_cndmask_b32_e32 v81, v209, v210, vcc
	v_add_u32_e32 v81, v81, v80
	v_sub_u32_e32 v80, 0x40ff, v80
	v_cndmask_b32_e64 v0, v0, v78, s[46:47]
	v_cndmask_b32_e64 v80, v80, v81, s[46:47]
	v_mad_i64_i32 v[78:79], s[22:23], v0, s21, v[76:77]
	v_mad_i64_i32 v[80:81], s[22:23], v80, s21, v[76:77]
	ds_read_b128 v[66:69], v103
	ds_read_b128 v[70:73], v103 offset:4608
	global_load_ushort v0, v[78:79], off
	global_load_ushort v154, v[80:81], off
	v_cmp_gt_i32_e32 vcc, s6, v82
	s_nop 1
	v_cndmask_b32_e32 v83, v209, v210, vcc
	v_add_u32_e32 v83, v83, v82
	v_sub_u32_e32 v82, 0x40ff, v82
	v_cndmask_b32_e64 v82, v82, v83, s[46:47]
	v_mad_i64_i32 v[84:85], s[22:23], v82, s21, v[76:77]
	v_or_b32_e32 v82, 51, v92
	v_cmp_gt_i32_e32 vcc, s6, v82
	global_load_ushort v155, v[84:85], off
	s_nop 0
	v_cndmask_b32_e32 v83, v209, v210, vcc
	v_cmp_gt_i32_e32 vcc, s6, v86
	v_add_u32_e32 v83, v83, v82
	v_sub_u32_e32 v82, 0x40ff, v82
	v_cndmask_b32_e32 v87, v209, v210, vcc
	v_cmp_gt_i32_e32 vcc, s6, v88
	v_add_u32_e32 v87, v87, v86
	v_sub_u32_e32 v86, 0x40ff, v86
	v_cndmask_b32_e32 v89, v209, v210, vcc
	v_cmp_gt_i32_e32 vcc, s6, v90
	v_add_u32_e32 v89, v89, v88
	v_sub_u32_e32 v88, 0x40ff, v88
	v_cndmask_b32_e32 v91, v209, v210, vcc
	v_cmp_gt_i32_e32 vcc, s6, v93
	v_add_u32_e32 v91, v91, v90
	v_sub_u32_e32 v90, 0x40ff, v90
	v_cndmask_b32_e32 v92, v209, v210, vcc
	v_add_u32_e32 v92, v92, v93
	v_sub_u32_e32 v93, 0x40ff, v93
	v_cndmask_b32_e64 v82, v82, v83, s[46:47]
	v_cndmask_b32_e64 v86, v86, v87, s[46:47]
	v_cndmask_b32_e64 v88, v88, v89, s[46:47]
	v_cndmask_b32_e64 v90, v90, v91, s[46:47]
	v_cndmask_b32_e64 v92, v93, v92, s[46:47]
	v_mad_i64_i32 v[82:83], s[22:23], v82, s21, v[76:77]
	v_mad_i64_i32 v[86:87], s[22:23], v86, s21, v[76:77]
	v_mad_i64_i32 v[88:89], s[22:23], v88, s21, v[76:77]
	v_mad_i64_i32 v[90:91], s[22:23], v90, s21, v[76:77]
	v_mad_i64_i32 v[92:93], s[22:23], v92, s21, v[76:77]
	global_load_ushort v168, v[86:87], off
	global_load_ushort v169, v[88:89], off
	global_load_ushort v170, v[90:91], off
	global_load_ushort v171, v[92:93], off
	global_load_ushort v167, v[82:83], off
	s_waitcnt vmcnt(6)
; __device__ __forceinline__ void hgrn_h1_item(const Ctx& F, const bf16_t* PB, const float* logits, int l, int item, float* GS, float* HA, LAS unsigned char* scrb) {
;     ...
;     float* go = GS + ((size_t)((dir * NCHUNK + c) * 4 + head)) * 4096;
; #pragma unroll
;     for (int db = 0; db < 2; ++db)
; #pragma unroll
;         for (int vb = 0; vb < 2; ++vb)
; #pragma unroll
;             for (int r2 = 0; r2 < 16; ++r2) go[(32 * db + 8 * (r2 >> 2) + 4 * h + (r2 & 3)) * 64 + 32 * vb + q_] = g[db][vb][r2];
;     asm volatile("s_waitcnt lgkmcnt(0)" ::: "memory");
;     __builtin_amdgcn_wave_barrier();
; }
; __device__ __forceinline__ void prep_h1_phase(LAS unsigned char* lds, unsigned char* ws, const float* logits, int l, int tid, int bid, int G) {
;     ...
;     for (int it = F.wave * F.G + F.bid; it < 2 * NCHUNK * 4; it += F.ngw) hgrn_h1_item(F, PB, logits, l, it, GS, HA, scr);
	v_lshl_or_b32 v172, v154, 16, v0
	global_load_ushort v0, v[78:79], off offset:64
	s_nop 0
	global_load_ushort v78, v[80:81], off offset:64
	global_load_ushort v79, v[84:85], off offset:64
	s_nop 0
	global_load_ushort v80, v[82:83], off offset:64
	global_load_ushort v81, v[86:87], off offset:64
	s_nop 0
	global_load_ushort v82, v[88:89], off offset:64
	global_load_ushort v83, v[90:91], off offset:64
	global_load_ushort v84, v[92:93], off offset:64
	s_waitcnt vmcnt(11)
	v_lshl_or_b32 v174, v169, 16, v168
	s_waitcnt vmcnt(9)
	v_lshl_or_b32 v175, v171, 16, v170
	s_waitcnt vmcnt(8)
	v_lshl_or_b32 v173, v167, 16, v155
	s_waitcnt vmcnt(6)
	v_lshl_or_b32 v78, v78, 16, v0
	s_waitcnt lgkmcnt(1)
	v_mfma_f32_32x32x16_bf16 v[50:65], v[66:69], v[172:175], v[50:65]
	s_waitcnt vmcnt(4)
	v_lshl_or_b32 v79, v80, 16, v79
	s_waitcnt vmcnt(2)
	v_lshl_or_b32 v80, v82, 16, v81
	s_waitcnt vmcnt(0)
	v_lshl_or_b32 v81, v84, 16, v83
	s_waitcnt lgkmcnt(0)
	v_mfma_f32_32x32x16_bf16 v[18:33], v[70:73], v[172:175], v[18:33]
	v_mfma_f32_32x32x16_bf16 v[34:49], v[66:69], v[78:81], v[34:49]
	v_mfma_f32_32x32x16_bf16 v[2:17], v[70:73], v[78:81], v[2:17]
	s_nop 1
	global_store_dword v104, v50, s[4:5]
	global_store_dword v104, v51, s[4:5] offset:256
	global_store_dword v104, v52, s[4:5] offset:512
	global_store_dword v104, v53, s[4:5] offset:768
	global_store_dword v104, v54, s[4:5] offset:2048
	global_store_dword v104, v55, s[4:5] offset:2304
	global_store_dword v104, v56, s[4:5] offset:2560
	global_store_dword v104, v57, s[4:5] offset:2816
	global_store_dword v105, v58, s[4:5]
	global_store_dword v106, v59, s[4:5]
	global_store_dword v107, v60, s[4:5]
	global_store_dword v108, v61, s[4:5]
	global_store_dword v109, v62, s[4:5]
	global_store_dword v110, v63, s[4:5]
	global_store_dword v111, v64, s[4:5]
	global_store_dword v112, v65, s[4:5]
	global_store_dword v104, v34, s[4:5] offset:128
	global_store_dword v113, v35, s[4:5] offset:256
	global_store_dword v113, v36, s[4:5] offset:512
	global_store_dword v113, v37, s[4:5] offset:768
	global_store_dword v113, v38, s[4:5] offset:2048
	global_store_dword v113, v39, s[4:5] offset:2304
	global_store_dword v113, v40, s[4:5] offset:2560
	global_store_dword v113, v41, s[4:5] offset:2816
	global_store_dword v114, v42, s[4:5]
	global_store_dword v115, v43, s[4:5]
	global_store_dword v116, v44, s[4:5]
	global_store_dword v117, v45, s[4:5]
	global_store_dword v118, v46, s[4:5]
	global_store_dword v119, v47, s[4:5]
	global_store_dword v120, v48, s[4:5]
	global_store_dword v121, v49, s[4:5]
	global_store_dword v122, v18, s[4:5]
	global_store_dword v123, v19, s[4:5]
	global_store_dword v124, v20, s[4:5]
	global_store_dword v125, v21, s[4:5]
	global_store_dword v126, v22, s[4:5]
	global_store_dword v127, v23, s[4:5]
	global_store_dword v128, v24, s[4:5]
	global_store_dword v129, v25, s[4:5]
	global_store_dword v130, v26, s[4:5]
	global_store_dword v131, v27, s[4:5]
	global_store_dword v132, v28, s[4:5]
	global_store_dword v133, v29, s[4:5]
	global_store_dword v134, v30, s[4:5]
	global_store_dword v135, v31, s[4:5]
	global_store_dword v136, v32, s[4:5]
	global_store_dword v137, v33, s[4:5]
	global_store_dword v138, v2, s[4:5]
	global_store_dword v139, v3, s[4:5]
	global_store_dword v140, v4, s[4:5]
	global_store_dword v141, v5, s[4:5]
	global_store_dword v142, v6, s[4:5]
	global_store_dword v143, v7, s[4:5]
	global_store_dword v144, v8, s[4:5]
	global_store_dword v145, v9, s[4:5]
	global_store_dword v146, v10, s[4:5]
	global_store_dword v147, v11, s[4:5]
	global_store_dword v148, v12, s[4:5]
	global_store_dword v149, v13, s[4:5]
	global_store_dword v150, v14, s[4:5]
	global_store_dword v151, v15, s[4:5]
	global_store_dword v152, v16, s[4:5]
	global_store_dword v153, v17, s[4:5]
	s_waitcnt lgkmcnt(0)
	s_cbranch_scc1 .LBB0_437
